# barrier relocation + 4x s_nop 15 before the wait in the six-DMA load segments of all GEMM K-loops
# baseline (speedup 1.0000x reference)
; #define PG8_STAGE(bufoff, gbase, voff) do { _Pragma("unroll") for (int _i = 0; _i < 2; ++_i) \
;         __builtin_amdgcn_global_load_lds((const unsigned*)((const char*)(gbase) + (voff)[_i]), (LAS unsigned*)(lds + (bufoff) + ldsw + _i * 8192), 16, 0, 0); } while (0)
; #define PG8_LDA(dst, b, h) do { _Pragma("unroll") for (int m = 0; m < 4; ++m) _Pragma("unroll") for (int k = 0; k < 2; ++k) dst[m][k] = *(const LAS bf16x8*)(lds + PG8_SA(b, h) + aoff + m * 2048 + k * 1024); } while (0)
; #define PG8_LDB(dst, b, h) do { _Pragma("unroll") for (int n = 0; n < 2; ++n) _Pragma("unroll") for (int k = 0; k < 2; ++k) dst[n][k] = *(const LAS bf16x8*)(lds + PG8_SB(b, h) + boff + n * 2048 + k * 1024); } while (0)
; #define PG8_MMA(ai, bj, At, Bt) do { __builtin_amdgcn_s_setprio(1); _Pragma("unroll") for (int m = 0; m < 4; ++m) _Pragma("unroll") for (int n = 0; n < 2; ++n) _Pragma("unroll") for (int k = 0; k < 2; ++k) \
;         acc[ai][bj][m][n] = __builtin_amdgcn_mfma_f32_16x16x32_bf16(Bt[n][k], At[m][k], acc[ai][bj][m][n], 0, 0, 0); __builtin_amdgcn_s_setprio(0); } while (0)
; #define PG8_WAIT_V(n) asm volatile("s_waitcnt vmcnt(" #n ")" ::: "memory")
; #define PG8_WAIT_L(n) asm volatile("s_waitcnt lgkmcnt(" #n ")" ::: "memory")
; #define PG8_BAR __builtin_amdgcn_s_barrier()
; #define PG8_SCHED __builtin_amdgcn_sched_barrier(0)
; template <class Epi, bool ALIGN_EPI = PG8_ALIGN>
; __device__ __forceinline__ void gemm_phase(LAS unsigned char* lds, const Gemm g, const StaticOrder& S, const Epi& E) {
;     ...
;         for (int t = 0; t < nt; t += 2) {
;             const bool last = (t == nt - 2);
;             const char* a1 = cA + (size_t)(t + 1) * kstep;
;             const char* a2 = last ? nA : cA + (size_t)(t + 2) * kstep; const char* b2 = last ? nB : cB + (size_t)(t + 2) * kstep;
;             const char* a3 = a2 + kstep; const char* b3 = b2 + kstep;
;             PG8_LDB(B0, 0, 0); PG8_LDB(B1, 0, 1); PG8_SCHED; PG8_LDA(At, 0, 0); PG8_STAGE(PG8_SA(1, 1), a1 + hstepA, voffA);
;             PG8_WAIT_V(8); PG8_WAIT_L(0); PG8_BAR; PG8_MMA(0, 0, At, B0); PG8_MMA(0, 1, At, B1); PG8_BAR; PG8_SCHED;
;             PG8_LDA(At, 0, 1); PG8_STAGE(PG8_SB(0, 0), b2, voffB); PG8_STAGE(PG8_SB(0, 1), b2 + hstepB, voffB); PG8_STAGE(PG8_SA(0, 0), a2, voffA);
;             PG8_WAIT_V(8); PG8_WAIT_L(0); PG8_BAR; PG8_MMA(1, 0, At, B0); PG8_MMA(1, 1, At, B1); PG8_BAR; PG8_SCHED;
.LBB0_219:
	s_add_i32 s49, s24, 2
	s_add_u32 s20, s2, 0xfff80080
	s_addc_u32 s21, s3, -1
	s_add_i32 s22, 16, 0x10000
	s_cmp_eq_u32 s46, s24
	s_cselect_b32 s25, s15, s21
	s_cselect_b32 s24, s34, s20
	s_cselect_b32 s51, s17, s37
	s_cselect_b32 s50, s16, s36
	s_add_i32 s20, 16, 0x14000
	v_add_u32_e32 v154, s22, v139
	v_add_u32_e32 v170, s20, v139
	ds_read_b128 v[142:145], v154
	ds_read_b128 v[146:149], v154 offset:1024
	ds_read_b128 v[150:153], v154 offset:2048
	ds_read_b128 v[154:157], v154 offset:3072
	ds_read_b128 v[158:161], v170
	ds_read_b128 v[162:165], v170 offset:1024
	ds_read_b128 v[166:169], v170 offset:2048
	ds_read_b128 v[170:173], v170 offset:3072
	v_lshl_add_u64 v[174:175], s[2:3], 0, v[134:135]
	s_add_i32 m0, s29, 0xc000
	ds_read_b128 v[184:187], v141
	ds_read_b128 v[188:191], v141 offset:1024
	ds_read_b128 v[192:195], v141 offset:2048
	ds_read_b128 v[196:199], v141 offset:3072
	ds_read_b128 v[200:203], v141 offset:4096
	ds_read_b128 v[204:207], v141 offset:5120
	ds_read_b128 v[208:211], v141 offset:6144
	ds_read_b128 v[212:215], v141 offset:7168
	global_load_lds_dwordx4 v[174:175], off
	v_lshl_add_u64 v[174:175], s[2:3], 0, v[136:137]
	s_add_i32 m0, s29, 0xe000
	s_nop 0
	global_load_lds_dwordx4 v[174:175], off
	s_waitcnt vmcnt(8)
	s_waitcnt lgkmcnt(0)
	s_barrier
	s_setprio 1
	s_waitcnt lgkmcnt(0)
	v_mfma_f32_16x16x32_bf16 v[124:127], v[142:145], v[184:187], v[124:127]
	v_mfma_f32_16x16x32_bf16 v[116:119], v[150:153], v[184:187], v[116:119]
	v_mfma_f32_16x16x32_bf16 v[108:111], v[142:145], v[192:195], v[108:111]
	v_mfma_f32_16x16x32_bf16 v[100:103], v[150:153], v[192:195], v[100:103]
	v_mfma_f32_16x16x32_bf16 v[92:95], v[142:145], v[200:203], v[92:95]
	v_mfma_f32_16x16x32_bf16 v[84:87], v[150:153], v[200:203], v[84:87]
	v_mfma_f32_16x16x32_bf16 v[76:79], v[142:145], v[208:211], v[76:79]
	v_mfma_f32_16x16x32_bf16 v[68:71], v[150:153], v[208:211], v[68:71]
	v_mfma_f32_16x16x32_bf16 v[124:127], v[146:149], v[188:191], v[124:127]
	v_mfma_f32_16x16x32_bf16 v[116:119], v[154:157], v[188:191], v[116:119]
	v_mfma_f32_16x16x32_bf16 v[108:111], v[146:149], v[196:199], v[108:111]
	v_mfma_f32_16x16x32_bf16 v[100:103], v[154:157], v[196:199], v[100:103]
	v_mfma_f32_16x16x32_bf16 v[92:95], v[146:149], v[204:207], v[92:95]
	v_mfma_f32_16x16x32_bf16 v[84:87], v[154:157], v[204:207], v[84:87]
	v_mfma_f32_16x16x32_bf16 v[76:79], v[146:149], v[212:215], v[76:79]
	v_mfma_f32_16x16x32_bf16 v[68:71], v[154:157], v[212:215], v[68:71]
	s_setprio 0
	s_setprio 1
	v_mfma_f32_16x16x32_bf16 v[120:123], v[158:161], v[184:187], v[120:123]
	v_mfma_f32_16x16x32_bf16 v[112:115], v[166:169], v[184:187], v[112:115]
	v_mfma_f32_16x16x32_bf16 v[104:107], v[158:161], v[192:195], v[104:107]
	v_mfma_f32_16x16x32_bf16 v[96:99], v[166:169], v[192:195], v[96:99]
	v_mfma_f32_16x16x32_bf16 v[88:91], v[158:161], v[200:203], v[88:91]
	v_mfma_f32_16x16x32_bf16 v[80:83], v[166:169], v[200:203], v[80:83]
	v_mfma_f32_16x16x32_bf16 v[72:75], v[158:161], v[208:211], v[72:75]
	v_mfma_f32_16x16x32_bf16 v[64:67], v[166:169], v[208:211], v[64:67]
	v_mfma_f32_16x16x32_bf16 v[120:123], v[162:165], v[188:191], v[120:123]
	v_mfma_f32_16x16x32_bf16 v[112:115], v[170:173], v[188:191], v[112:115]
	v_mfma_f32_16x16x32_bf16 v[104:107], v[162:165], v[196:199], v[104:107]
	v_mfma_f32_16x16x32_bf16 v[96:99], v[170:173], v[196:199], v[96:99]
	v_mfma_f32_16x16x32_bf16 v[88:91], v[162:165], v[204:207], v[88:91]
	v_mfma_f32_16x16x32_bf16 v[80:83], v[170:173], v[204:207], v[80:83]
	v_mfma_f32_16x16x32_bf16 v[72:75], v[162:165], v[212:215], v[72:75]
	v_mfma_f32_16x16x32_bf16 v[64:67], v[170:173], v[212:215], v[64:67]
	s_setprio 0
	s_barrier
	s_add_i32 s21, s22, s18
	v_lshl_add_u64 v[174:175], s[50:51], 0, v[176:177]
	s_mov_b32 m0, s21
	ds_read_b128 v[184:187], v141 offset:16384
	ds_read_b128 v[188:191], v141 offset:17408
	ds_read_b128 v[192:195], v141 offset:18432
	ds_read_b128 v[196:199], v141 offset:19456
	ds_read_b128 v[200:203], v141 offset:20480
	ds_read_b128 v[204:207], v141 offset:21504
	ds_read_b128 v[208:211], v141 offset:22528
	ds_read_b128 v[212:215], v141 offset:23552
	global_load_lds_dwordx4 v[174:175], off
	s_add_i32 m0, s21, 0x2000
	v_lshl_add_u64 v[216:217], s[50:51], 0, v[128:129]
	s_add_u32 s50, s50, s4
	s_addc_u32 s51, s51, s5
	s_add_i32 s20, s20, s18
	global_load_lds_dwordx4 v[216:217], off
	v_lshl_add_u64 v[218:219], s[50:51], 0, v[176:177]
	s_mov_b32 m0, s20
	v_lshl_add_u64 v[220:221], s[50:51], 0, v[128:129]
	global_load_lds_dwordx4 v[218:219], off
	s_add_i32 m0, s20, 0x2000
	v_lshl_add_u64 v[222:223], s[24:25], 0, v[132:133]
	global_load_lds_dwordx4 v[220:221], off
	s_mov_b32 m0, s29
	v_lshl_add_u64 v[224:225], s[24:25], 0, v[130:131]
	global_load_lds_dwordx4 v[222:223], off
	s_mov_b32 m0, s30
	s_nop 0
	global_load_lds_dwordx4 v[224:225], off
	s_nop 15
	s_nop 15
	s_nop 15
	s_nop 15
	s_waitcnt vmcnt(8)
	s_waitcnt lgkmcnt(0)
	s_barrier
; #define PG8_STAGE(bufoff, gbase, voff) do { _Pragma("unroll") for (int _i = 0; _i < 2; ++_i) \
;         __builtin_amdgcn_global_load_lds((const unsigned*)((const char*)(gbase) + (voff)[_i]), (LAS unsigned*)(lds + (bufoff) + ldsw + _i * 8192), 16, 0, 0); } while (0)
; #define PG8_LDA(dst, b, h) do { _Pragma("unroll") for (int m = 0; m < 4; ++m) _Pragma("unroll") for (int k = 0; k < 2; ++k) dst[m][k] = *(const LAS bf16x8*)(lds + PG8_SA(b, h) + aoff + m * 2048 + k * 1024); } while (0)
; #define PG8_LDB(dst, b, h) do { _Pragma("unroll") for (int n = 0; n < 2; ++n) _Pragma("unroll") for (int k = 0; k < 2; ++k) dst[n][k] = *(const LAS bf16x8*)(lds + PG8_SB(b, h) + boff + n * 2048 + k * 1024); } while (0)
; #define PG8_MMA(ai, bj, At, Bt) do { __builtin_amdgcn_s_setprio(1); _Pragma("unroll") for (int m = 0; m < 4; ++m) _Pragma("unroll") for (int n = 0; n < 2; ++n) _Pragma("unroll") for (int k = 0; k < 2; ++k) \
;         acc[ai][bj][m][n] = __builtin_amdgcn_mfma_f32_16x16x32_bf16(Bt[n][k], At[m][k], acc[ai][bj][m][n], 0, 0, 0); __builtin_amdgcn_s_setprio(0); } while (0)
; #define PG8_WAIT_V(n) asm volatile("s_waitcnt vmcnt(" #n ")" ::: "memory")
; #define PG8_WAIT_L(n) asm volatile("s_waitcnt lgkmcnt(" #n ")" ::: "memory")
; #define PG8_BAR __builtin_amdgcn_s_barrier()
; #define PG8_SCHED __builtin_amdgcn_sched_barrier(0)
; template <class Epi, bool ALIGN_EPI = PG8_ALIGN>
; __device__ __forceinline__ void gemm_phase(LAS unsigned char* lds, const Gemm g, const StaticOrder& S, const Epi& E) {
;     ...
;             PG8_WAIT_V(8); PG8_WAIT_L(0); PG8_BAR; PG8_MMA(1, 0, At, B0); PG8_MMA(1, 1, At, B1); PG8_BAR; PG8_SCHED;
;             PG8_LDB(B0, 1, 0); PG8_LDB(B1, 1, 1); PG8_SCHED; PG8_LDA(At, 1, 0); PG8_STAGE(PG8_SA(0, 1), a2 + hstepA, voffA);
;             PG8_WAIT_V(8); PG8_WAIT_L(0); PG8_BAR; PG8_MMA(0, 0, At, B0); PG8_MMA(0, 1, At, B1); PG8_BAR; PG8_SCHED;
	s_setprio 1
	s_waitcnt lgkmcnt(0)
	v_mfma_f32_16x16x32_bf16 v[60:63], v[142:145], v[184:187], v[60:63]
	v_mfma_f32_16x16x32_bf16 v[52:55], v[150:153], v[184:187], v[52:55]
	v_mfma_f32_16x16x32_bf16 v[44:47], v[142:145], v[192:195], v[44:47]
	v_mfma_f32_16x16x32_bf16 v[36:39], v[150:153], v[192:195], v[36:39]
	v_mfma_f32_16x16x32_bf16 v[28:31], v[142:145], v[200:203], v[28:31]
	v_mfma_f32_16x16x32_bf16 v[20:23], v[150:153], v[200:203], v[20:23]
	v_mfma_f32_16x16x32_bf16 v[12:15], v[142:145], v[208:211], v[12:15]
	v_mfma_f32_16x16x32_bf16 v[4:7], v[150:153], v[208:211], v[4:7]
	v_mfma_f32_16x16x32_bf16 v[60:63], v[146:149], v[188:191], v[60:63]
	v_mfma_f32_16x16x32_bf16 v[52:55], v[154:157], v[188:191], v[52:55]
	v_mfma_f32_16x16x32_bf16 v[44:47], v[146:149], v[196:199], v[44:47]
	v_mfma_f32_16x16x32_bf16 v[36:39], v[154:157], v[196:199], v[36:39]
	v_mfma_f32_16x16x32_bf16 v[28:31], v[146:149], v[204:207], v[28:31]
	v_mfma_f32_16x16x32_bf16 v[20:23], v[154:157], v[204:207], v[20:23]
	v_mfma_f32_16x16x32_bf16 v[12:15], v[146:149], v[212:215], v[12:15]
	v_mfma_f32_16x16x32_bf16 v[4:7], v[154:157], v[212:215], v[4:7]
	s_setprio 0
	s_setprio 1
	v_mfma_f32_16x16x32_bf16 v[56:59], v[158:161], v[184:187], v[56:59]
	v_mfma_f32_16x16x32_bf16 v[48:51], v[166:169], v[184:187], v[48:51]
	v_mfma_f32_16x16x32_bf16 v[40:43], v[158:161], v[192:195], v[40:43]
	v_mfma_f32_16x16x32_bf16 v[32:35], v[166:169], v[192:195], v[32:35]
	v_mfma_f32_16x16x32_bf16 v[24:27], v[158:161], v[200:203], v[24:27]
	v_mfma_f32_16x16x32_bf16 v[16:19], v[166:169], v[200:203], v[16:19]
	v_mfma_f32_16x16x32_bf16 v[8:11], v[158:161], v[208:211], v[8:11]
	v_mfma_f32_16x16x32_bf16 v[0:3], v[166:169], v[208:211], v[0:3]
	v_mfma_f32_16x16x32_bf16 v[56:59], v[162:165], v[188:191], v[56:59]
	v_mfma_f32_16x16x32_bf16 v[48:51], v[170:173], v[188:191], v[48:51]
	v_mfma_f32_16x16x32_bf16 v[40:43], v[162:165], v[196:199], v[40:43]
	v_mfma_f32_16x16x32_bf16 v[32:35], v[170:173], v[196:199], v[32:35]
	v_mfma_f32_16x16x32_bf16 v[24:27], v[162:165], v[204:207], v[24:27]
	v_mfma_f32_16x16x32_bf16 v[16:19], v[170:173], v[204:207], v[16:19]
	v_mfma_f32_16x16x32_bf16 v[8:11], v[162:165], v[212:215], v[8:11]
	v_mfma_f32_16x16x32_bf16 v[0:3], v[170:173], v[212:215], v[0:3]
	s_setprio 0
	s_barrier
	s_add_i32 s20, 16, 0x18000
	s_add_i32 s21, 16, 0x1c000
	v_add_u32_e32 v154, s20, v139
	v_add_u32_e32 v170, s21, v139
	ds_read_b128 v[142:145], v154
	ds_read_b128 v[146:149], v154 offset:1024
	ds_read_b128 v[150:153], v154 offset:2048
	ds_read_b128 v[154:157], v154 offset:3072
	ds_read_b128 v[158:161], v170
	ds_read_b128 v[162:165], v170 offset:1024
	ds_read_b128 v[166:169], v170 offset:2048
	ds_read_b128 v[170:173], v170 offset:3072
	s_add_u32 s24, s24, 0x80000
	s_addc_u32 s25, s25, 0
	s_mov_b32 m0, s31
	v_lshl_add_u64 v[226:227], s[24:25], 0, v[132:133]
	ds_read_b128 v[184:187], v141 offset:32768
	ds_read_b128 v[188:191], v141 offset:33792
	ds_read_b128 v[192:195], v141 offset:34816
	ds_read_b128 v[196:199], v141 offset:35840
	ds_read_b128 v[200:203], v141 offset:36864
	ds_read_b128 v[204:207], v141 offset:37888
	ds_read_b128 v[208:211], v141 offset:38912
	ds_read_b128 v[212:215], v141 offset:39936
	global_load_lds_dwordx4 v[226:227], off
	v_lshl_add_u64 v[226:227], s[24:25], 0, v[130:131]
	s_mov_b32 m0, s42
	s_nop 0
	global_load_lds_dwordx4 v[226:227], off
	s_waitcnt vmcnt(8)
	s_waitcnt lgkmcnt(0)
	s_barrier
	s_setprio 1
	s_waitcnt lgkmcnt(0)
	v_mfma_f32_16x16x32_bf16 v[124:127], v[142:145], v[184:187], v[124:127]
	v_mfma_f32_16x16x32_bf16 v[116:119], v[150:153], v[184:187], v[116:119]
	v_mfma_f32_16x16x32_bf16 v[108:111], v[142:145], v[192:195], v[108:111]
	v_mfma_f32_16x16x32_bf16 v[100:103], v[150:153], v[192:195], v[100:103]
	v_mfma_f32_16x16x32_bf16 v[92:95], v[142:145], v[200:203], v[92:95]
	v_mfma_f32_16x16x32_bf16 v[84:87], v[150:153], v[200:203], v[84:87]
	v_mfma_f32_16x16x32_bf16 v[76:79], v[142:145], v[208:211], v[76:79]
	v_mfma_f32_16x16x32_bf16 v[68:71], v[150:153], v[208:211], v[68:71]
	v_mfma_f32_16x16x32_bf16 v[124:127], v[146:149], v[188:191], v[124:127]
	v_mfma_f32_16x16x32_bf16 v[116:119], v[154:157], v[188:191], v[116:119]
	v_mfma_f32_16x16x32_bf16 v[108:111], v[146:149], v[196:199], v[108:111]
	v_mfma_f32_16x16x32_bf16 v[100:103], v[154:157], v[196:199], v[100:103]
	v_mfma_f32_16x16x32_bf16 v[92:95], v[146:149], v[204:207], v[92:95]
	v_mfma_f32_16x16x32_bf16 v[84:87], v[154:157], v[204:207], v[84:87]
	v_mfma_f32_16x16x32_bf16 v[76:79], v[146:149], v[212:215], v[76:79]
	v_mfma_f32_16x16x32_bf16 v[68:71], v[154:157], v[212:215], v[68:71]
	s_setprio 0
	s_setprio 1
	v_mfma_f32_16x16x32_bf16 v[120:123], v[158:161], v[184:187], v[120:123]
	v_mfma_f32_16x16x32_bf16 v[112:115], v[166:169], v[184:187], v[112:115]
	v_mfma_f32_16x16x32_bf16 v[104:107], v[158:161], v[192:195], v[104:107]
	v_mfma_f32_16x16x32_bf16 v[96:99], v[166:169], v[192:195], v[96:99]
	v_mfma_f32_16x16x32_bf16 v[88:91], v[158:161], v[200:203], v[88:91]
	v_mfma_f32_16x16x32_bf16 v[80:83], v[166:169], v[200:203], v[80:83]
	v_mfma_f32_16x16x32_bf16 v[72:75], v[158:161], v[208:211], v[72:75]
	v_mfma_f32_16x16x32_bf16 v[64:67], v[166:169], v[208:211], v[64:67]
	v_mfma_f32_16x16x32_bf16 v[120:123], v[162:165], v[188:191], v[120:123]
	v_mfma_f32_16x16x32_bf16 v[112:115], v[170:173], v[188:191], v[112:115]
	v_mfma_f32_16x16x32_bf16 v[104:107], v[162:165], v[196:199], v[104:107]
	v_mfma_f32_16x16x32_bf16 v[96:99], v[170:173], v[196:199], v[96:99]
	v_mfma_f32_16x16x32_bf16 v[88:91], v[162:165], v[204:207], v[88:91]
	v_mfma_f32_16x16x32_bf16 v[80:83], v[170:173], v[204:207], v[80:83]
	v_mfma_f32_16x16x32_bf16 v[72:75], v[162:165], v[212:215], v[72:75]
	v_mfma_f32_16x16x32_bf16 v[64:67], v[170:173], v[212:215], v[64:67]
	s_setprio 0
	s_barrier
; #define PG8_STAGE(bufoff, gbase, voff) do { _Pragma("unroll") for (int _i = 0; _i < 2; ++_i) \
;         __builtin_amdgcn_global_load_lds((const unsigned*)((const char*)(gbase) + (voff)[_i]), (LAS unsigned*)(lds + (bufoff) + ldsw + _i * 8192), 16, 0, 0); } while (0)
; #define PG8_LDA(dst, b, h) do { _Pragma("unroll") for (int m = 0; m < 4; ++m) _Pragma("unroll") for (int k = 0; k < 2; ++k) dst[m][k] = *(const LAS bf16x8*)(lds + PG8_SA(b, h) + aoff + m * 2048 + k * 1024); } while (0)
; #define PG8_MMA(ai, bj, At, Bt) do { __builtin_amdgcn_s_setprio(1); _Pragma("unroll") for (int m = 0; m < 4; ++m) _Pragma("unroll") for (int n = 0; n < 2; ++n) _Pragma("unroll") for (int k = 0; k < 2; ++k) \
;         acc[ai][bj][m][n] = __builtin_amdgcn_mfma_f32_16x16x32_bf16(Bt[n][k], At[m][k], acc[ai][bj][m][n], 0, 0, 0); __builtin_amdgcn_s_setprio(0); } while (0)
; #define PG8_WAIT_V(n) asm volatile("s_waitcnt vmcnt(" #n ")" ::: "memory")
; #define PG8_WAIT_L(n) asm volatile("s_waitcnt lgkmcnt(" #n ")" ::: "memory")
; #define PG8_BAR __builtin_amdgcn_s_barrier()
; #define PG8_SCHED __builtin_amdgcn_sched_barrier(0)
; template <class Epi, bool ALIGN_EPI = PG8_ALIGN>
; __device__ __forceinline__ void gemm_phase(LAS unsigned char* lds, const Gemm g, const StaticOrder& S, const Epi& E) {
;     ...
;             PG8_LDA(At, 1, 1); PG8_STAGE(PG8_SB(1, 0), b3, voffB); PG8_STAGE(PG8_SB(1, 1), b3 + hstepB, voffB); PG8_STAGE(PG8_SA(1, 0), a3, voffA);
;             PG8_WAIT_V(8); PG8_WAIT_L(0); PG8_BAR; PG8_MMA(1, 0, At, B0); PG8_MMA(1, 1, At, B1); PG8_BAR; PG8_SCHED;
;         }
	s_add_i32 s20, s20, s18
	v_lshl_add_u64 v[174:175], v[174:175], 0, s[0:1]
	s_mov_b32 m0, s20
	ds_read_b128 v[184:187], v141 offset:49152
	ds_read_b128 v[188:191], v141 offset:50176
	ds_read_b128 v[192:195], v141 offset:51200
	ds_read_b128 v[196:199], v141 offset:52224
	ds_read_b128 v[200:203], v141 offset:53248
	ds_read_b128 v[204:207], v141 offset:54272
	ds_read_b128 v[208:211], v141 offset:55296
	ds_read_b128 v[212:215], v141 offset:56320
	global_load_lds_dwordx4 v[174:175], off
	v_lshl_add_u64 v[174:175], v[216:217], 0, s[0:1]
	s_add_i32 m0, s20, 0x2000
	s_add_i32 s20, s21, s18
	global_load_lds_dwordx4 v[174:175], off
	v_lshl_add_u64 v[174:175], v[218:219], 0, s[0:1]
	s_mov_b32 m0, s20
	s_nop 0
	global_load_lds_dwordx4 v[174:175], off
	v_lshl_add_u64 v[174:175], v[220:221], 0, s[0:1]
	s_add_i32 m0, s20, 0x2000
	s_nop 0
	global_load_lds_dwordx4 v[174:175], off
	v_lshl_add_u64 v[174:175], v[222:223], 0, s[0:1]
	s_mov_b32 m0, s43
	s_nop 0
	global_load_lds_dwordx4 v[174:175], off
	v_lshl_add_u64 v[174:175], v[224:225], 0, s[0:1]
	s_mov_b32 m0, s44
	s_nop 0
	global_load_lds_dwordx4 v[174:175], off
	s_nop 15
	s_nop 15
	s_nop 15
	s_nop 15
	s_waitcnt vmcnt(8)
	s_waitcnt lgkmcnt(0)
	s_barrier
	s_setprio 1
	s_waitcnt lgkmcnt(0)
	v_mfma_f32_16x16x32_bf16 v[60:63], v[142:145], v[184:187], v[60:63]
	v_mfma_f32_16x16x32_bf16 v[52:55], v[150:153], v[184:187], v[52:55]
	v_mfma_f32_16x16x32_bf16 v[44:47], v[142:145], v[192:195], v[44:47]
	v_mfma_f32_16x16x32_bf16 v[36:39], v[150:153], v[192:195], v[36:39]
	v_mfma_f32_16x16x32_bf16 v[28:31], v[142:145], v[200:203], v[28:31]
	v_mfma_f32_16x16x32_bf16 v[20:23], v[150:153], v[200:203], v[20:23]
	v_mfma_f32_16x16x32_bf16 v[12:15], v[142:145], v[208:211], v[12:15]
	v_mfma_f32_16x16x32_bf16 v[4:7], v[150:153], v[208:211], v[4:7]
	v_mfma_f32_16x16x32_bf16 v[60:63], v[146:149], v[188:191], v[60:63]
	v_mfma_f32_16x16x32_bf16 v[52:55], v[154:157], v[188:191], v[52:55]
	v_mfma_f32_16x16x32_bf16 v[44:47], v[146:149], v[196:199], v[44:47]
	v_mfma_f32_16x16x32_bf16 v[36:39], v[154:157], v[196:199], v[36:39]
	v_mfma_f32_16x16x32_bf16 v[28:31], v[146:149], v[204:207], v[28:31]
	v_mfma_f32_16x16x32_bf16 v[20:23], v[154:157], v[204:207], v[20:23]
	v_mfma_f32_16x16x32_bf16 v[12:15], v[146:149], v[212:215], v[12:15]
	v_mfma_f32_16x16x32_bf16 v[4:7], v[154:157], v[212:215], v[4:7]
	s_setprio 0
	s_setprio 1
	v_mfma_f32_16x16x32_bf16 v[56:59], v[158:161], v[184:187], v[56:59]
	v_mfma_f32_16x16x32_bf16 v[48:51], v[166:169], v[184:187], v[48:51]
	v_mfma_f32_16x16x32_bf16 v[40:43], v[158:161], v[192:195], v[40:43]
	v_mfma_f32_16x16x32_bf16 v[32:35], v[166:169], v[192:195], v[32:35]
	v_mfma_f32_16x16x32_bf16 v[24:27], v[158:161], v[200:203], v[24:27]
	v_mfma_f32_16x16x32_bf16 v[16:19], v[166:169], v[200:203], v[16:19]
	v_mfma_f32_16x16x32_bf16 v[8:11], v[158:161], v[208:211], v[8:11]
	v_mfma_f32_16x16x32_bf16 v[0:3], v[166:169], v[208:211], v[0:3]
	v_mfma_f32_16x16x32_bf16 v[56:59], v[162:165], v[188:191], v[56:59]
	v_mfma_f32_16x16x32_bf16 v[48:51], v[170:173], v[188:191], v[48:51]
	v_mfma_f32_16x16x32_bf16 v[40:43], v[162:165], v[196:199], v[40:43]
	v_mfma_f32_16x16x32_bf16 v[32:35], v[170:173], v[196:199], v[32:35]
	v_mfma_f32_16x16x32_bf16 v[24:27], v[162:165], v[204:207], v[24:27]
	v_mfma_f32_16x16x32_bf16 v[16:19], v[170:173], v[204:207], v[16:19]
	v_mfma_f32_16x16x32_bf16 v[8:11], v[162:165], v[212:215], v[8:11]
	v_mfma_f32_16x16x32_bf16 v[0:3], v[170:173], v[212:215], v[0:3]
	s_setprio 0
	s_barrier
	s_add_u32 s2, s2, 0x100
	s_addc_u32 s3, s3, 0
	s_add_u32 s36, s36, 0x100
	s_addc_u32 s37, s37, 0
	s_cmp_ge_i32 s49, s45
	s_mov_b32 s24, s49
	s_cbranch_scc0 .LBB0_219

; #define PG8_STAGE(bufoff, gbase, voff) do { _Pragma("unroll") for (int _i = 0; _i < 2; ++_i) \
;         __builtin_amdgcn_global_load_lds((const unsigned*)((const char*)(gbase) + (voff)[_i]), (LAS unsigned*)(lds + (bufoff) + ldsw + _i * 8192), 16, 0, 0); } while (0)
; #define PG8_LDA(dst, b, h) do { _Pragma("unroll") for (int m = 0; m < 4; ++m) _Pragma("unroll") for (int k = 0; k < 2; ++k) dst[m][k] = *(const LAS bf16x8*)(lds + PG8_SA(b, h) + aoff + m * 2048 + k * 1024); } while (0)
; #define PG8_LDB(dst, b, h) do { _Pragma("unroll") for (int n = 0; n < 2; ++n) _Pragma("unroll") for (int k = 0; k < 2; ++k) dst[n][k] = *(const LAS bf16x8*)(lds + PG8_SB(b, h) + boff + n * 2048 + k * 1024); } while (0)
; #define PG8_MMA(ai, bj, At, Bt) do { __builtin_amdgcn_s_setprio(1); _Pragma("unroll") for (int m = 0; m < 4; ++m) _Pragma("unroll") for (int n = 0; n < 2; ++n) _Pragma("unroll") for (int k = 0; k < 2; ++k) \
;         acc[ai][bj][m][n] = __builtin_amdgcn_mfma_f32_16x16x32_bf16(Bt[n][k], At[m][k], acc[ai][bj][m][n], 0, 0, 0); __builtin_amdgcn_s_setprio(0); } while (0)
; #define PG8_WAIT_V(n) asm volatile("s_waitcnt vmcnt(" #n ")" ::: "memory")
; #define PG8_WAIT_L(n) asm volatile("s_waitcnt lgkmcnt(" #n ")" ::: "memory")
; #define PG8_BAR __builtin_amdgcn_s_barrier()
; #define PG8_SCHED __builtin_amdgcn_sched_barrier(0)
; template <class Epi, bool ALIGN_EPI = PG8_ALIGN>
; __device__ __forceinline__ void gemm_phase(LAS unsigned char* lds, const Gemm g, const StaticOrder& S, const Epi& E) {
;     ...
;         for (int t = 0; t < nt; t += 2) {
;             const bool last = (t == nt - 2);
;             const char* a1 = cA + (size_t)(t + 1) * kstep;
;             const char* a2 = last ? nA : cA + (size_t)(t + 2) * kstep; const char* b2 = last ? nB : cB + (size_t)(t + 2) * kstep;
;             const char* a3 = a2 + kstep; const char* b3 = b2 + kstep;
;             PG8_LDB(B0, 0, 0); PG8_LDB(B1, 0, 1); PG8_SCHED; PG8_LDA(At, 0, 0); PG8_STAGE(PG8_SA(1, 1), a1 + hstepA, voffA);
;             PG8_WAIT_V(8); PG8_WAIT_L(0); PG8_BAR; PG8_MMA(0, 0, At, B0); PG8_MMA(0, 1, At, B1); PG8_BAR; PG8_SCHED;
;             PG8_LDA(At, 0, 1); PG8_STAGE(PG8_SB(0, 0), b2, voffB); PG8_STAGE(PG8_SB(0, 1), b2 + hstepB, voffB); PG8_STAGE(PG8_SA(0, 0), a2, voffA);
;             PG8_WAIT_V(8); PG8_WAIT_L(0); PG8_BAR; PG8_MMA(1, 0, At, B0); PG8_MMA(1, 1, At, B1); PG8_BAR; PG8_SCHED;
.LBB0_295:
	s_add_i32 s53, s38, 2
	s_add_u32 s36, s24, 0x100
	s_addc_u32 s37, s25, 0
	s_add_i32 s20, 16, 0x10000
	s_cmp_eq_u32 s26, s38
	s_cselect_b32 s39, s3, s37
	s_cselect_b32 s38, s2, s36
	s_cselect_b32 s55, s17, s52
	s_cselect_b32 s54, s16, s51
	s_add_i32 s21, 16, 0x14000
	v_add_u32_e32 v154, s20, v147
	v_add_u32_e32 v170, s21, v147
	ds_read_b128 v[138:141], v154
	ds_read_b128 v[142:145], v154 offset:1024
	ds_read_b128 v[150:153], v154 offset:2048
	ds_read_b128 v[154:157], v154 offset:3072
	ds_read_b128 v[158:161], v170
	ds_read_b128 v[162:165], v170 offset:1024
	ds_read_b128 v[166:169], v170 offset:2048
	ds_read_b128 v[170:173], v170 offset:3072
	v_lshl_add_u64 v[174:175], s[24:25], 0, v[134:135]
	s_add_i32 m0, s31, 0xc000
	ds_read_b128 v[184:187], v149
	ds_read_b128 v[188:191], v149 offset:1024
	ds_read_b128 v[192:195], v149 offset:2048
	ds_read_b128 v[196:199], v149 offset:3072
	ds_read_b128 v[200:203], v149 offset:4096
	ds_read_b128 v[204:207], v149 offset:5120
	ds_read_b128 v[208:211], v149 offset:6144
	ds_read_b128 v[212:215], v149 offset:7168
	global_load_lds_dwordx4 v[174:175], off
	v_lshl_add_u64 v[174:175], s[24:25], 0, v[136:137]
	s_add_i32 m0, s31, 0xe000
	s_nop 0
	global_load_lds_dwordx4 v[174:175], off
	s_waitcnt vmcnt(8)
	s_waitcnt lgkmcnt(0)
	s_barrier
	s_setprio 1
	s_waitcnt lgkmcnt(0)
	v_mfma_f32_16x16x32_bf16 v[124:127], v[138:141], v[184:187], v[124:127]
	v_mfma_f32_16x16x32_bf16 v[120:123], v[150:153], v[184:187], v[120:123]
	v_mfma_f32_16x16x32_bf16 v[116:119], v[138:141], v[192:195], v[116:119]
	v_mfma_f32_16x16x32_bf16 v[112:115], v[150:153], v[192:195], v[112:115]
	v_mfma_f32_16x16x32_bf16 v[104:107], v[138:141], v[200:203], v[104:107]
	v_mfma_f32_16x16x32_bf16 v[96:99], v[150:153], v[200:203], v[96:99]
	v_mfma_f32_16x16x32_bf16 v[88:91], v[138:141], v[208:211], v[88:91]
	v_mfma_f32_16x16x32_bf16 v[80:83], v[150:153], v[208:211], v[80:83]
	v_mfma_f32_16x16x32_bf16 v[124:127], v[142:145], v[188:191], v[124:127]
	v_mfma_f32_16x16x32_bf16 v[120:123], v[154:157], v[188:191], v[120:123]
	v_mfma_f32_16x16x32_bf16 v[116:119], v[142:145], v[196:199], v[116:119]
	v_mfma_f32_16x16x32_bf16 v[112:115], v[154:157], v[196:199], v[112:115]
	v_mfma_f32_16x16x32_bf16 v[104:107], v[142:145], v[204:207], v[104:107]
	v_mfma_f32_16x16x32_bf16 v[96:99], v[154:157], v[204:207], v[96:99]
	v_mfma_f32_16x16x32_bf16 v[88:91], v[142:145], v[212:215], v[88:91]
	v_mfma_f32_16x16x32_bf16 v[80:83], v[154:157], v[212:215], v[80:83]
	s_setprio 0
	s_setprio 1
	v_mfma_f32_16x16x32_bf16 v[108:111], v[158:161], v[184:187], v[108:111]
	v_mfma_f32_16x16x32_bf16 v[100:103], v[166:169], v[184:187], v[100:103]
	v_mfma_f32_16x16x32_bf16 v[92:95], v[158:161], v[192:195], v[92:95]
	v_mfma_f32_16x16x32_bf16 v[84:87], v[166:169], v[192:195], v[84:87]
	v_mfma_f32_16x16x32_bf16 v[76:79], v[158:161], v[200:203], v[76:79]
	v_mfma_f32_16x16x32_bf16 v[72:75], v[166:169], v[200:203], v[72:75]
	v_mfma_f32_16x16x32_bf16 v[68:71], v[158:161], v[208:211], v[68:71]
	v_mfma_f32_16x16x32_bf16 v[64:67], v[166:169], v[208:211], v[64:67]
	v_mfma_f32_16x16x32_bf16 v[108:111], v[162:165], v[188:191], v[108:111]
	v_mfma_f32_16x16x32_bf16 v[100:103], v[170:173], v[188:191], v[100:103]
	v_mfma_f32_16x16x32_bf16 v[92:95], v[162:165], v[196:199], v[92:95]
	v_mfma_f32_16x16x32_bf16 v[84:87], v[170:173], v[196:199], v[84:87]
	v_mfma_f32_16x16x32_bf16 v[76:79], v[162:165], v[204:207], v[76:79]
	v_mfma_f32_16x16x32_bf16 v[72:75], v[170:173], v[204:207], v[72:75]
	v_mfma_f32_16x16x32_bf16 v[68:71], v[162:165], v[212:215], v[68:71]
	v_mfma_f32_16x16x32_bf16 v[64:67], v[170:173], v[212:215], v[64:67]
	s_setprio 0
	s_barrier
	s_add_i32 s20, s20, s18
	v_lshl_add_u64 v[174:175], s[54:55], 0, v[176:177]
	s_mov_b32 m0, s20
	ds_read_b128 v[184:187], v149 offset:16384
	ds_read_b128 v[188:191], v149 offset:17408
	ds_read_b128 v[192:195], v149 offset:18432
	ds_read_b128 v[196:199], v149 offset:19456
	ds_read_b128 v[200:203], v149 offset:20480
	ds_read_b128 v[204:207], v149 offset:21504
	ds_read_b128 v[208:211], v149 offset:22528
	ds_read_b128 v[212:215], v149 offset:23552
	global_load_lds_dwordx4 v[174:175], off
	s_add_i32 m0, s20, 0x2000
	s_add_u32 s24, s54, s6
	v_lshl_add_u64 v[216:217], s[54:55], 0, v[128:129]
	s_addc_u32 s25, s55, s7
	s_add_i32 s20, s21, s18
	global_load_lds_dwordx4 v[216:217], off
	v_lshl_add_u64 v[218:219], s[24:25], 0, v[176:177]
	s_mov_b32 m0, s20
	v_lshl_add_u64 v[220:221], s[24:25], 0, v[128:129]
	global_load_lds_dwordx4 v[218:219], off
	s_add_i32 m0, s20, 0x2000
	v_lshl_add_u64 v[222:223], s[38:39], 0, v[132:133]
	global_load_lds_dwordx4 v[220:221], off
	s_mov_b32 m0, s31
	v_lshl_add_u64 v[224:225], s[38:39], 0, v[130:131]
	global_load_lds_dwordx4 v[222:223], off
	s_mov_b32 m0, s40
	s_nop 0
	global_load_lds_dwordx4 v[224:225], off
	s_nop 15
	s_nop 15
	s_nop 15
	s_nop 15
	s_waitcnt vmcnt(8)
	s_waitcnt lgkmcnt(0)
	s_barrier
; #define PG8_STAGE(bufoff, gbase, voff) do { _Pragma("unroll") for (int _i = 0; _i < 2; ++_i) \
;         __builtin_amdgcn_global_load_lds((const unsigned*)((const char*)(gbase) + (voff)[_i]), (LAS unsigned*)(lds + (bufoff) + ldsw + _i * 8192), 16, 0, 0); } while (0)
; #define PG8_LDA(dst, b, h) do { _Pragma("unroll") for (int m = 0; m < 4; ++m) _Pragma("unroll") for (int k = 0; k < 2; ++k) dst[m][k] = *(const LAS bf16x8*)(lds + PG8_SA(b, h) + aoff + m * 2048 + k * 1024); } while (0)
; #define PG8_LDB(dst, b, h) do { _Pragma("unroll") for (int n = 0; n < 2; ++n) _Pragma("unroll") for (int k = 0; k < 2; ++k) dst[n][k] = *(const LAS bf16x8*)(lds + PG8_SB(b, h) + boff + n * 2048 + k * 1024); } while (0)
; #define PG8_MMA(ai, bj, At, Bt) do { __builtin_amdgcn_s_setprio(1); _Pragma("unroll") for (int m = 0; m < 4; ++m) _Pragma("unroll") for (int n = 0; n < 2; ++n) _Pragma("unroll") for (int k = 0; k < 2; ++k) \
;         acc[ai][bj][m][n] = __builtin_amdgcn_mfma_f32_16x16x32_bf16(Bt[n][k], At[m][k], acc[ai][bj][m][n], 0, 0, 0); __builtin_amdgcn_s_setprio(0); } while (0)
; #define PG8_WAIT_V(n) asm volatile("s_waitcnt vmcnt(" #n ")" ::: "memory")
; #define PG8_WAIT_L(n) asm volatile("s_waitcnt lgkmcnt(" #n ")" ::: "memory")
; #define PG8_BAR __builtin_amdgcn_s_barrier()
; #define PG8_SCHED __builtin_amdgcn_sched_barrier(0)
; template <class Epi, bool ALIGN_EPI = PG8_ALIGN>
; __device__ __forceinline__ void gemm_phase(LAS unsigned char* lds, const Gemm g, const StaticOrder& S, const Epi& E) {
;     ...
;             PG8_WAIT_V(8); PG8_WAIT_L(0); PG8_BAR; PG8_MMA(1, 0, At, B0); PG8_MMA(1, 1, At, B1); PG8_BAR; PG8_SCHED;
;             PG8_LDB(B0, 1, 0); PG8_LDB(B1, 1, 1); PG8_SCHED; PG8_LDA(At, 1, 0); PG8_STAGE(PG8_SA(0, 1), a2 + hstepA, voffA);
;             PG8_WAIT_V(8); PG8_WAIT_L(0); PG8_BAR; PG8_MMA(0, 0, At, B0); PG8_MMA(0, 1, At, B1); PG8_BAR; PG8_SCHED;
	s_setprio 1
	s_waitcnt lgkmcnt(0)
	v_mfma_f32_16x16x32_bf16 v[60:63], v[138:141], v[184:187], v[60:63]
	v_mfma_f32_16x16x32_bf16 v[56:59], v[150:153], v[184:187], v[56:59]
	v_mfma_f32_16x16x32_bf16 v[52:55], v[138:141], v[192:195], v[52:55]
	v_mfma_f32_16x16x32_bf16 v[48:51], v[150:153], v[192:195], v[48:51]
	v_mfma_f32_16x16x32_bf16 v[40:43], v[138:141], v[200:203], v[40:43]
	v_mfma_f32_16x16x32_bf16 v[32:35], v[150:153], v[200:203], v[32:35]
	v_mfma_f32_16x16x32_bf16 v[24:27], v[138:141], v[208:211], v[24:27]
	v_mfma_f32_16x16x32_bf16 v[16:19], v[150:153], v[208:211], v[16:19]
	v_mfma_f32_16x16x32_bf16 v[60:63], v[142:145], v[188:191], v[60:63]
	v_mfma_f32_16x16x32_bf16 v[56:59], v[154:157], v[188:191], v[56:59]
	v_mfma_f32_16x16x32_bf16 v[52:55], v[142:145], v[196:199], v[52:55]
	v_mfma_f32_16x16x32_bf16 v[48:51], v[154:157], v[196:199], v[48:51]
	v_mfma_f32_16x16x32_bf16 v[40:43], v[142:145], v[204:207], v[40:43]
	v_mfma_f32_16x16x32_bf16 v[32:35], v[154:157], v[204:207], v[32:35]
	v_mfma_f32_16x16x32_bf16 v[24:27], v[142:145], v[212:215], v[24:27]
	v_mfma_f32_16x16x32_bf16 v[16:19], v[154:157], v[212:215], v[16:19]
	s_setprio 0
	s_setprio 1
	v_mfma_f32_16x16x32_bf16 v[44:47], v[158:161], v[184:187], v[44:47]
	v_mfma_f32_16x16x32_bf16 v[36:39], v[166:169], v[184:187], v[36:39]
	v_mfma_f32_16x16x32_bf16 v[28:31], v[158:161], v[192:195], v[28:31]
	v_mfma_f32_16x16x32_bf16 v[20:23], v[166:169], v[192:195], v[20:23]
	v_mfma_f32_16x16x32_bf16 v[12:15], v[158:161], v[200:203], v[12:15]
	v_mfma_f32_16x16x32_bf16 v[8:11], v[166:169], v[200:203], v[8:11]
	v_mfma_f32_16x16x32_bf16 v[4:7], v[158:161], v[208:211], v[4:7]
	v_mfma_f32_16x16x32_bf16 v[0:3], v[166:169], v[208:211], v[0:3]
	v_mfma_f32_16x16x32_bf16 v[44:47], v[162:165], v[188:191], v[44:47]
	v_mfma_f32_16x16x32_bf16 v[36:39], v[170:173], v[188:191], v[36:39]
	v_mfma_f32_16x16x32_bf16 v[28:31], v[162:165], v[196:199], v[28:31]
	v_mfma_f32_16x16x32_bf16 v[20:23], v[170:173], v[196:199], v[20:23]
	v_mfma_f32_16x16x32_bf16 v[12:15], v[162:165], v[204:207], v[12:15]
	v_mfma_f32_16x16x32_bf16 v[8:11], v[170:173], v[204:207], v[8:11]
	v_mfma_f32_16x16x32_bf16 v[4:7], v[162:165], v[212:215], v[4:7]
	v_mfma_f32_16x16x32_bf16 v[0:3], v[170:173], v[212:215], v[0:3]
	s_setprio 0
	s_barrier
	s_add_i32 s20, 16, 0x18000
	s_add_i32 s21, 16, 0x1c000
	v_add_u32_e32 v154, s20, v147
	v_add_u32_e32 v170, s21, v147
	ds_read_b128 v[138:141], v154
	ds_read_b128 v[142:145], v154 offset:1024
	ds_read_b128 v[150:153], v154 offset:2048
	ds_read_b128 v[154:157], v154 offset:3072
	ds_read_b128 v[158:161], v170
	ds_read_b128 v[162:165], v170 offset:1024
	ds_read_b128 v[166:169], v170 offset:2048
	ds_read_b128 v[170:173], v170 offset:3072
	s_add_u32 s24, s38, 0x160000
	s_addc_u32 s25, s39, 0
	s_mov_b32 m0, s41
	v_lshl_add_u64 v[226:227], s[24:25], 0, v[132:133]
	ds_read_b128 v[184:187], v149 offset:32768
	ds_read_b128 v[188:191], v149 offset:33792
	ds_read_b128 v[192:195], v149 offset:34816
	ds_read_b128 v[196:199], v149 offset:35840
	ds_read_b128 v[200:203], v149 offset:36864
	ds_read_b128 v[204:207], v149 offset:37888
	ds_read_b128 v[208:211], v149 offset:38912
	ds_read_b128 v[212:215], v149 offset:39936
	global_load_lds_dwordx4 v[226:227], off
	v_lshl_add_u64 v[226:227], s[24:25], 0, v[130:131]
	s_mov_b32 m0, s44
	s_nop 0
	global_load_lds_dwordx4 v[226:227], off
	s_waitcnt vmcnt(8)
	s_waitcnt lgkmcnt(0)
	s_barrier
	s_setprio 1
	s_waitcnt lgkmcnt(0)
	v_mfma_f32_16x16x32_bf16 v[124:127], v[138:141], v[184:187], v[124:127]
	v_mfma_f32_16x16x32_bf16 v[120:123], v[150:153], v[184:187], v[120:123]
	v_mfma_f32_16x16x32_bf16 v[116:119], v[138:141], v[192:195], v[116:119]
	v_mfma_f32_16x16x32_bf16 v[112:115], v[150:153], v[192:195], v[112:115]
	v_mfma_f32_16x16x32_bf16 v[104:107], v[138:141], v[200:203], v[104:107]
	v_mfma_f32_16x16x32_bf16 v[96:99], v[150:153], v[200:203], v[96:99]
	v_mfma_f32_16x16x32_bf16 v[88:91], v[138:141], v[208:211], v[88:91]
	v_mfma_f32_16x16x32_bf16 v[80:83], v[150:153], v[208:211], v[80:83]
	v_mfma_f32_16x16x32_bf16 v[124:127], v[142:145], v[188:191], v[124:127]
	v_mfma_f32_16x16x32_bf16 v[120:123], v[154:157], v[188:191], v[120:123]
	v_mfma_f32_16x16x32_bf16 v[116:119], v[142:145], v[196:199], v[116:119]
	v_mfma_f32_16x16x32_bf16 v[112:115], v[154:157], v[196:199], v[112:115]
	v_mfma_f32_16x16x32_bf16 v[104:107], v[142:145], v[204:207], v[104:107]
	v_mfma_f32_16x16x32_bf16 v[96:99], v[154:157], v[204:207], v[96:99]
	v_mfma_f32_16x16x32_bf16 v[88:91], v[142:145], v[212:215], v[88:91]
	v_mfma_f32_16x16x32_bf16 v[80:83], v[154:157], v[212:215], v[80:83]
	s_setprio 0
	s_setprio 1
	v_mfma_f32_16x16x32_bf16 v[108:111], v[158:161], v[184:187], v[108:111]
	v_mfma_f32_16x16x32_bf16 v[100:103], v[166:169], v[184:187], v[100:103]
	v_mfma_f32_16x16x32_bf16 v[92:95], v[158:161], v[192:195], v[92:95]
	v_mfma_f32_16x16x32_bf16 v[84:87], v[166:169], v[192:195], v[84:87]
	v_mfma_f32_16x16x32_bf16 v[76:79], v[158:161], v[200:203], v[76:79]
	v_mfma_f32_16x16x32_bf16 v[72:75], v[166:169], v[200:203], v[72:75]
	v_mfma_f32_16x16x32_bf16 v[68:71], v[158:161], v[208:211], v[68:71]
	v_mfma_f32_16x16x32_bf16 v[64:67], v[166:169], v[208:211], v[64:67]
	v_mfma_f32_16x16x32_bf16 v[108:111], v[162:165], v[188:191], v[108:111]
	v_mfma_f32_16x16x32_bf16 v[100:103], v[170:173], v[188:191], v[100:103]
	v_mfma_f32_16x16x32_bf16 v[92:95], v[162:165], v[196:199], v[92:95]
	v_mfma_f32_16x16x32_bf16 v[84:87], v[170:173], v[196:199], v[84:87]
	v_mfma_f32_16x16x32_bf16 v[76:79], v[162:165], v[204:207], v[76:79]
	v_mfma_f32_16x16x32_bf16 v[72:75], v[170:173], v[204:207], v[72:75]
	v_mfma_f32_16x16x32_bf16 v[68:71], v[162:165], v[212:215], v[68:71]
	v_mfma_f32_16x16x32_bf16 v[64:67], v[170:173], v[212:215], v[64:67]
	s_setprio 0
	s_barrier
; #define PG8_STAGE(bufoff, gbase, voff) do { _Pragma("unroll") for (int _i = 0; _i < 2; ++_i) \
;         __builtin_amdgcn_global_load_lds((const unsigned*)((const char*)(gbase) + (voff)[_i]), (LAS unsigned*)(lds + (bufoff) + ldsw + _i * 8192), 16, 0, 0); } while (0)
; #define PG8_LDA(dst, b, h) do { _Pragma("unroll") for (int m = 0; m < 4; ++m) _Pragma("unroll") for (int k = 0; k < 2; ++k) dst[m][k] = *(const LAS bf16x8*)(lds + PG8_SA(b, h) + aoff + m * 2048 + k * 1024); } while (0)
; #define PG8_MMA(ai, bj, At, Bt) do { __builtin_amdgcn_s_setprio(1); _Pragma("unroll") for (int m = 0; m < 4; ++m) _Pragma("unroll") for (int n = 0; n < 2; ++n) _Pragma("unroll") for (int k = 0; k < 2; ++k) \
;         acc[ai][bj][m][n] = __builtin_amdgcn_mfma_f32_16x16x32_bf16(Bt[n][k], At[m][k], acc[ai][bj][m][n], 0, 0, 0); __builtin_amdgcn_s_setprio(0); } while (0)
; #define PG8_WAIT_V(n) asm volatile("s_waitcnt vmcnt(" #n ")" ::: "memory")
; #define PG8_WAIT_L(n) asm volatile("s_waitcnt lgkmcnt(" #n ")" ::: "memory")
; #define PG8_BAR __builtin_amdgcn_s_barrier()
; #define PG8_SCHED __builtin_amdgcn_sched_barrier(0)
; template <class Epi, bool ALIGN_EPI = PG8_ALIGN>
; __device__ __forceinline__ void gemm_phase(LAS unsigned char* lds, const Gemm g, const StaticOrder& S, const Epi& E) {
;     ...
;             PG8_LDA(At, 1, 1); PG8_STAGE(PG8_SB(1, 0), b3, voffB); PG8_STAGE(PG8_SB(1, 1), b3 + hstepB, voffB); PG8_STAGE(PG8_SA(1, 0), a3, voffA);
;             PG8_WAIT_V(8); PG8_WAIT_L(0); PG8_BAR; PG8_MMA(1, 0, At, B0); PG8_MMA(1, 1, At, B1); PG8_BAR; PG8_SCHED;
;         }
	s_add_i32 s20, s20, s18
	v_lshl_add_u64 v[174:175], v[174:175], 0, s[0:1]
	s_mov_b32 m0, s20
	ds_read_b128 v[184:187], v149 offset:49152
	ds_read_b128 v[188:191], v149 offset:50176
	ds_read_b128 v[192:195], v149 offset:51200
	ds_read_b128 v[196:199], v149 offset:52224
	ds_read_b128 v[200:203], v149 offset:53248
	ds_read_b128 v[204:207], v149 offset:54272
	ds_read_b128 v[208:211], v149 offset:55296
	ds_read_b128 v[212:215], v149 offset:56320
	global_load_lds_dwordx4 v[174:175], off
	v_lshl_add_u64 v[174:175], v[216:217], 0, s[0:1]
	s_add_i32 m0, s20, 0x2000
	s_add_i32 s20, s21, s18
	global_load_lds_dwordx4 v[174:175], off
	v_lshl_add_u64 v[174:175], v[218:219], 0, s[0:1]
	s_mov_b32 m0, s20
	s_nop 0
	global_load_lds_dwordx4 v[174:175], off
	v_lshl_add_u64 v[174:175], v[220:221], 0, s[0:1]
	s_add_i32 m0, s20, 0x2000
	s_nop 0
	global_load_lds_dwordx4 v[174:175], off
	v_lshl_add_u64 v[174:175], v[222:223], 0, s[0:1]
	s_mov_b32 m0, s45
	s_nop 0
	global_load_lds_dwordx4 v[174:175], off
	v_lshl_add_u64 v[174:175], v[224:225], 0, s[0:1]
	s_mov_b32 m0, s46
	s_nop 0
	global_load_lds_dwordx4 v[174:175], off
	s_nop 15
	s_nop 15
	s_nop 15
	s_nop 15
	s_waitcnt vmcnt(8)
	s_waitcnt lgkmcnt(0)
	s_barrier
	s_setprio 1
	s_waitcnt lgkmcnt(0)
	v_mfma_f32_16x16x32_bf16 v[60:63], v[138:141], v[184:187], v[60:63]
	v_mfma_f32_16x16x32_bf16 v[56:59], v[150:153], v[184:187], v[56:59]
	v_mfma_f32_16x16x32_bf16 v[52:55], v[138:141], v[192:195], v[52:55]
	v_mfma_f32_16x16x32_bf16 v[48:51], v[150:153], v[192:195], v[48:51]
	v_mfma_f32_16x16x32_bf16 v[40:43], v[138:141], v[200:203], v[40:43]
	v_mfma_f32_16x16x32_bf16 v[32:35], v[150:153], v[200:203], v[32:35]
	v_mfma_f32_16x16x32_bf16 v[24:27], v[138:141], v[208:211], v[24:27]
	v_mfma_f32_16x16x32_bf16 v[16:19], v[150:153], v[208:211], v[16:19]
	v_mfma_f32_16x16x32_bf16 v[60:63], v[142:145], v[188:191], v[60:63]
	v_mfma_f32_16x16x32_bf16 v[56:59], v[154:157], v[188:191], v[56:59]
	v_mfma_f32_16x16x32_bf16 v[52:55], v[142:145], v[196:199], v[52:55]
	v_mfma_f32_16x16x32_bf16 v[48:51], v[154:157], v[196:199], v[48:51]
	v_mfma_f32_16x16x32_bf16 v[40:43], v[142:145], v[204:207], v[40:43]
	v_mfma_f32_16x16x32_bf16 v[32:35], v[154:157], v[204:207], v[32:35]
	v_mfma_f32_16x16x32_bf16 v[24:27], v[142:145], v[212:215], v[24:27]
	v_mfma_f32_16x16x32_bf16 v[16:19], v[154:157], v[212:215], v[16:19]
	s_setprio 0
	s_setprio 1
	v_mfma_f32_16x16x32_bf16 v[44:47], v[158:161], v[184:187], v[44:47]
	v_mfma_f32_16x16x32_bf16 v[36:39], v[166:169], v[184:187], v[36:39]
	v_mfma_f32_16x16x32_bf16 v[28:31], v[158:161], v[192:195], v[28:31]
	v_mfma_f32_16x16x32_bf16 v[20:23], v[166:169], v[192:195], v[20:23]
	v_mfma_f32_16x16x32_bf16 v[12:15], v[158:161], v[200:203], v[12:15]
	v_mfma_f32_16x16x32_bf16 v[8:11], v[166:169], v[200:203], v[8:11]
	v_mfma_f32_16x16x32_bf16 v[4:7], v[158:161], v[208:211], v[4:7]
	v_mfma_f32_16x16x32_bf16 v[0:3], v[166:169], v[208:211], v[0:3]
	v_mfma_f32_16x16x32_bf16 v[44:47], v[162:165], v[188:191], v[44:47]
	v_mfma_f32_16x16x32_bf16 v[36:39], v[170:173], v[188:191], v[36:39]
	v_mfma_f32_16x16x32_bf16 v[28:31], v[162:165], v[196:199], v[28:31]
	v_mfma_f32_16x16x32_bf16 v[20:23], v[170:173], v[196:199], v[20:23]
	v_mfma_f32_16x16x32_bf16 v[12:15], v[162:165], v[204:207], v[12:15]
	v_mfma_f32_16x16x32_bf16 v[8:11], v[170:173], v[204:207], v[8:11]
	v_mfma_f32_16x16x32_bf16 v[4:7], v[162:165], v[212:215], v[4:7]
	v_mfma_f32_16x16x32_bf16 v[0:3], v[170:173], v[212:215], v[0:3]
	s_setprio 0
	s_barrier
	s_add_u32 s51, s51, 0x100
	s_addc_u32 s52, s52, 0
	s_cmp_ge_i32 s53, s47
	s_mov_b64 s[24:25], s[36:37]
	s_mov_b32 s38, s53
	s_cbranch_scc0 .LBB0_295
; __device__ __forceinline__ unsigned cvt_pk(float lo, float hi) { f32x2_t v = {lo, hi}; bf16x2_t b = __builtin_convertvector(v, bf16x2_t); return __builtin_bit_cast(unsigned, b); }
;     __device__ __forceinline__ void operator()(const f32x4 (&acc)[2][2][4][2], const Unit& u, int wr, int wc, int fr, int fq) const {
;     ...
;                 const int row = row0 + ai * HALF + m * 16; const float sc = scv[ai][m];
;                 bf16_t* rowp = O + (size_t)row * ldc + col0;
; #pragma unroll
;                 for (int bj = 0; bj < 2; ++bj) { const f32x4 v0 = acc[ai][bj][m][0] * sc, v1 = acc[ai][bj][m][1] * sc;
;                     u32x4 w; w.x = cvt_pk(v0[0], v0[1]); w.y = cvt_pk(v0[2], v0[3]); w.z = cvt_pk(v1[0], v1[1]); w.w = cvt_pk(v1[2], v1[3]);
;                     *(u32x4*)(rowp + bj * HALF) = w; }
	v_pk_mul_f32 v[126:127], v[126:127], 0.5 op_sel_hi:[1,0]
	v_pk_mul_f32 v[124:125], v[124:125], 0.5 op_sel_hi:[1,0]
	v_pk_mul_f32 v[122:123], v[122:123], 0.5 op_sel_hi:[1,0]
	v_pk_mul_f32 v[120:121], v[120:121], 0.5 op_sel_hi:[1,0]
	v_pk_mul_f32 v[138:139], v[110:111], 0.5 op_sel_hi:[1,0]
	v_pk_mul_f32 v[140:141], v[108:109], 0.5 op_sel_hi:[1,0]
	v_pk_mul_f32 v[142:143], v[102:103], 0.5 op_sel_hi:[1,0]
	v_pk_mul_f32 v[144:145], v[100:101], 0.5 op_sel_hi:[1,0]
	v_pk_mul_f32 v[100:101], v[118:119], 0.5 op_sel_hi:[1,0]
	v_pk_mul_f32 v[102:103], v[116:117], 0.5 op_sel_hi:[1,0]
	v_pk_mul_f32 v[108:109], v[114:115], 0.5 op_sel_hi:[1,0]
	v_pk_mul_f32 v[110:111], v[112:113], 0.5 op_sel_hi:[1,0]
	v_pk_mul_f32 v[112:113], v[94:95], 0.5 op_sel_hi:[1,0]
	v_pk_mul_f32 v[114:115], v[92:93], 0.5 op_sel_hi:[1,0]
	v_pk_mul_f32 v[116:117], v[86:87], 0.5 op_sel_hi:[1,0]
	v_pk_mul_f32 v[118:119], v[84:85], 0.5 op_sel_hi:[1,0]
	v_pk_mul_f32 v[84:85], v[106:107], 0.5 op_sel_hi:[1,0]
	v_pk_mul_f32 v[86:87], v[104:105], 0.5 op_sel_hi:[1,0]
	v_pk_mul_f32 v[92:93], v[98:99], 0.5 op_sel_hi:[1,0]
	v_pk_mul_f32 v[94:95], v[96:97], 0.5 op_sel_hi:[1,0]
	v_pk_mul_f32 v[96:97], v[78:79], 0.5 op_sel_hi:[1,0]
	v_pk_mul_f32 v[98:99], v[76:77], 0.5 op_sel_hi:[1,0]
	v_pk_mul_f32 v[104:105], v[74:75], 0.5 op_sel_hi:[1,0]
	v_pk_mul_f32 v[106:107], v[72:73], 0.5 op_sel_hi:[1,0]
	v_pk_mul_f32 v[72:73], v[90:91], 0.5 op_sel_hi:[1,0]
	v_pk_mul_f32 v[74:75], v[88:89], 0.5 op_sel_hi:[1,0]
	v_pk_mul_f32 v[76:77], v[82:83], 0.5 op_sel_hi:[1,0]
	v_pk_mul_f32 v[78:79], v[80:81], 0.5 op_sel_hi:[1,0]
	v_pk_mul_f32 v[70:71], v[70:71], 0.5 op_sel_hi:[1,0]
	v_pk_mul_f32 v[68:69], v[68:69], 0.5 op_sel_hi:[1,0]
	v_pk_mul_f32 v[66:67], v[66:67], 0.5 op_sel_hi:[1,0]
	v_pk_mul_f32 v[64:65], v[64:65], 0.5 op_sel_hi:[1,0]
	v_pk_mul_f32 v[62:63], v[62:63], 0.5 op_sel_hi:[1,0]
	v_pk_mul_f32 v[60:61], v[60:61], 0.5 op_sel_hi:[1,0]
	v_pk_mul_f32 v[58:59], v[58:59], 0.5 op_sel_hi:[1,0]
	v_pk_mul_f32 v[56:57], v[56:57], 0.5 op_sel_hi:[1,0]
	v_pk_mul_f32 v[80:81], v[46:47], 0.5 op_sel_hi:[1,0]
	v_pk_mul_f32 v[82:83], v[44:45], 0.5 op_sel_hi:[1,0]
	v_pk_mul_f32 v[88:89], v[38:39], 0.5 op_sel_hi:[1,0]
	v_pk_mul_f32 v[90:91], v[36:37], 0.5 op_sel_hi:[1,0]
	v_pk_mul_f32 v[36:37], v[54:55], 0.5 op_sel_hi:[1,0]
	v_pk_mul_f32 v[38:39], v[52:53], 0.5 op_sel_hi:[1,0]
	v_pk_mul_f32 v[44:45], v[50:51], 0.5 op_sel_hi:[1,0]
	v_pk_mul_f32 v[46:47], v[48:49], 0.5 op_sel_hi:[1,0]
	v_pk_mul_f32 v[48:49], v[30:31], 0.5 op_sel_hi:[1,0]
	v_pk_mul_f32 v[50:51], v[28:29], 0.5 op_sel_hi:[1,0]
	v_pk_mul_f32 v[52:53], v[22:23], 0.5 op_sel_hi:[1,0]
	v_pk_mul_f32 v[54:55], v[20:21], 0.5 op_sel_hi:[1,0]
	v_pk_mul_f32 v[20:21], v[42:43], 0.5 op_sel_hi:[1,0]
	v_pk_mul_f32 v[22:23], v[40:41], 0.5 op_sel_hi:[1,0]
	v_pk_mul_f32 v[28:29], v[34:35], 0.5 op_sel_hi:[1,0]
	v_pk_mul_f32 v[30:31], v[32:33], 0.5 op_sel_hi:[1,0]
	v_pk_mul_f32 v[32:33], v[14:15], 0.5 op_sel_hi:[1,0]
	v_pk_mul_f32 v[34:35], v[12:13], 0.5 op_sel_hi:[1,0]
	v_pk_mul_f32 v[40:41], v[10:11], 0.5 op_sel_hi:[1,0]
	v_pk_mul_f32 v[42:43], v[8:9], 0.5 op_sel_hi:[1,0]
	v_pk_mul_f32 v[8:9], v[26:27], 0.5 op_sel_hi:[1,0]
	v_pk_mul_f32 v[10:11], v[24:25], 0.5 op_sel_hi:[1,0]
	v_pk_mul_f32 v[12:13], v[18:19], 0.5 op_sel_hi:[1,0]
	v_pk_mul_f32 v[14:15], v[16:17], 0.5 op_sel_hi:[1,0]
	v_pk_mul_f32 v[6:7], v[6:7], 0.5 op_sel_hi:[1,0]
	v_pk_mul_f32 v[4:5], v[4:5], 0.5 op_sel_hi:[1,0]
	v_pk_mul_f32 v[2:3], v[2:3], 0.5 op_sel_hi:[1,0]
	v_pk_mul_f32 v[0:1], v[0:1], 0.5 op_sel_hi:[1,0]

; #define PG8_STAGE(bufoff, gbase, voff) do { _Pragma("unroll") for (int _i = 0; _i < 2; ++_i) \
;         __builtin_amdgcn_global_load_lds((const unsigned*)((const char*)(gbase) + (voff)[_i]), (LAS unsigned*)(lds + (bufoff) + ldsw + _i * 8192), 16, 0, 0); } while (0)
; #define PG8_LDA(dst, b, h) do { _Pragma("unroll") for (int m = 0; m < 4; ++m) _Pragma("unroll") for (int k = 0; k < 2; ++k) dst[m][k] = *(const LAS bf16x8*)(lds + PG8_SA(b, h) + aoff + m * 2048 + k * 1024); } while (0)
; #define PG8_LDB(dst, b, h) do { _Pragma("unroll") for (int n = 0; n < 2; ++n) _Pragma("unroll") for (int k = 0; k < 2; ++k) dst[n][k] = *(const LAS bf16x8*)(lds + PG8_SB(b, h) + boff + n * 2048 + k * 1024); } while (0)
; #define PG8_MMA(ai, bj, At, Bt) do { __builtin_amdgcn_s_setprio(1); _Pragma("unroll") for (int m = 0; m < 4; ++m) _Pragma("unroll") for (int n = 0; n < 2; ++n) _Pragma("unroll") for (int k = 0; k < 2; ++k) \
;         acc[ai][bj][m][n] = __builtin_amdgcn_mfma_f32_16x16x32_bf16(Bt[n][k], At[m][k], acc[ai][bj][m][n], 0, 0, 0); __builtin_amdgcn_s_setprio(0); } while (0)
; #define PG8_WAIT_V(n) asm volatile("s_waitcnt vmcnt(" #n ")" ::: "memory")
; #define PG8_WAIT_L(n) asm volatile("s_waitcnt lgkmcnt(" #n ")" ::: "memory")
; #define PG8_BAR __builtin_amdgcn_s_barrier()
; #define PG8_SCHED __builtin_amdgcn_sched_barrier(0)
; template <class Epi, bool ALIGN_EPI = PG8_ALIGN>
; __device__ __forceinline__ void gemm_phase(LAS unsigned char* lds, const Gemm g, const StaticOrder& S, const Epi& E) {
;     ...
;         for (int t = 0; t < nt; t += 2) {
;             const bool last = (t == nt - 2);
;             const char* a1 = cA + (size_t)(t + 1) * kstep;
;             const char* a2 = last ? nA : cA + (size_t)(t + 2) * kstep; const char* b2 = last ? nB : cB + (size_t)(t + 2) * kstep;
;             const char* a3 = a2 + kstep; const char* b3 = b2 + kstep;
;             PG8_LDB(B0, 0, 0); PG8_LDB(B1, 0, 1); PG8_SCHED; PG8_LDA(At, 0, 0); PG8_STAGE(PG8_SA(1, 1), a1 + hstepA, voffA);
;             PG8_WAIT_V(8); PG8_WAIT_L(0); PG8_BAR; PG8_MMA(0, 0, At, B0); PG8_MMA(0, 1, At, B1); PG8_BAR; PG8_SCHED;
;             PG8_LDA(At, 0, 1); PG8_STAGE(PG8_SB(0, 0), b2, voffB); PG8_STAGE(PG8_SB(0, 1), b2 + hstepB, voffB); PG8_STAGE(PG8_SA(0, 0), a2, voffA);
;             PG8_WAIT_V(8); PG8_WAIT_L(0); PG8_BAR; PG8_MMA(1, 0, At, B0); PG8_MMA(1, 1, At, B1); PG8_BAR; PG8_SCHED;
.LBB0_458:
	s_add_i32 s51, s38, 2
	s_add_u32 s20, s4, 0xfff80080
	s_addc_u32 s21, s5, -1
	s_add_i32 s22, 16, 0x10000
	s_cmp_eq_u32 s45, s38
	s_cselect_b32 s39, s17, s21
	s_cselect_b32 s38, s50, s20
	s_cselect_b32 s53, s25, s41
	s_cselect_b32 s52, s24, s40
	s_add_i32 s20, 16, 0x14000
	v_add_u32_e32 v154, s22, v139
	v_add_u32_e32 v170, s20, v139
	ds_read_b128 v[142:145], v154
	ds_read_b128 v[146:149], v154 offset:1024
	ds_read_b128 v[150:153], v154 offset:2048
	ds_read_b128 v[154:157], v154 offset:3072
	ds_read_b128 v[158:161], v170
	ds_read_b128 v[162:165], v170 offset:1024
	ds_read_b128 v[166:169], v170 offset:2048
	ds_read_b128 v[170:173], v170 offset:3072
	v_lshl_add_u64 v[174:175], s[4:5], 0, v[134:135]
	s_add_i32 m0, s29, 0xc000
	ds_read_b128 v[184:187], v141
	ds_read_b128 v[188:191], v141 offset:1024
	ds_read_b128 v[192:195], v141 offset:2048
	ds_read_b128 v[196:199], v141 offset:3072
	ds_read_b128 v[200:203], v141 offset:4096
	ds_read_b128 v[204:207], v141 offset:5120
	ds_read_b128 v[208:211], v141 offset:6144
	ds_read_b128 v[212:215], v141 offset:7168
	global_load_lds_dwordx4 v[174:175], off
	v_lshl_add_u64 v[174:175], s[4:5], 0, v[136:137]
	s_add_i32 m0, s29, 0xe000
	s_nop 0
	global_load_lds_dwordx4 v[174:175], off
	s_waitcnt vmcnt(8)
	s_waitcnt lgkmcnt(0)
	s_barrier
	s_setprio 1
	s_waitcnt lgkmcnt(0)
	v_mfma_f32_16x16x32_bf16 v[120:123], v[142:145], v[184:187], v[120:123]
	v_mfma_f32_16x16x32_bf16 v[124:127], v[150:153], v[184:187], v[124:127]
	v_mfma_f32_16x16x32_bf16 v[108:111], v[142:145], v[192:195], v[108:111]
	v_mfma_f32_16x16x32_bf16 v[104:107], v[150:153], v[192:195], v[104:107]
	v_mfma_f32_16x16x32_bf16 v[92:95], v[142:145], v[200:203], v[92:95]
	v_mfma_f32_16x16x32_bf16 v[88:91], v[150:153], v[200:203], v[88:91]
	v_mfma_f32_16x16x32_bf16 v[76:79], v[142:145], v[208:211], v[76:79]
	v_mfma_f32_16x16x32_bf16 v[72:75], v[150:153], v[208:211], v[72:75]
	v_mfma_f32_16x16x32_bf16 v[120:123], v[146:149], v[188:191], v[120:123]
	v_mfma_f32_16x16x32_bf16 v[124:127], v[154:157], v[188:191], v[124:127]
	v_mfma_f32_16x16x32_bf16 v[108:111], v[146:149], v[196:199], v[108:111]
	v_mfma_f32_16x16x32_bf16 v[104:107], v[154:157], v[196:199], v[104:107]
	v_mfma_f32_16x16x32_bf16 v[92:95], v[146:149], v[204:207], v[92:95]
	v_mfma_f32_16x16x32_bf16 v[88:91], v[154:157], v[204:207], v[88:91]
	v_mfma_f32_16x16x32_bf16 v[76:79], v[146:149], v[212:215], v[76:79]
	v_mfma_f32_16x16x32_bf16 v[72:75], v[154:157], v[212:215], v[72:75]
	s_setprio 0
	s_setprio 1
	v_mfma_f32_16x16x32_bf16 v[116:119], v[158:161], v[184:187], v[116:119]
	v_mfma_f32_16x16x32_bf16 v[112:115], v[166:169], v[184:187], v[112:115]
	v_mfma_f32_16x16x32_bf16 v[100:103], v[158:161], v[192:195], v[100:103]
	v_mfma_f32_16x16x32_bf16 v[96:99], v[166:169], v[192:195], v[96:99]
	v_mfma_f32_16x16x32_bf16 v[84:87], v[158:161], v[200:203], v[84:87]
	v_mfma_f32_16x16x32_bf16 v[80:83], v[166:169], v[200:203], v[80:83]
	v_mfma_f32_16x16x32_bf16 v[68:71], v[158:161], v[208:211], v[68:71]
	v_mfma_f32_16x16x32_bf16 v[64:67], v[166:169], v[208:211], v[64:67]
	v_mfma_f32_16x16x32_bf16 v[116:119], v[162:165], v[188:191], v[116:119]
	v_mfma_f32_16x16x32_bf16 v[112:115], v[170:173], v[188:191], v[112:115]
	v_mfma_f32_16x16x32_bf16 v[100:103], v[162:165], v[196:199], v[100:103]
	v_mfma_f32_16x16x32_bf16 v[96:99], v[170:173], v[196:199], v[96:99]
	v_mfma_f32_16x16x32_bf16 v[84:87], v[162:165], v[204:207], v[84:87]
	v_mfma_f32_16x16x32_bf16 v[80:83], v[170:173], v[204:207], v[80:83]
	v_mfma_f32_16x16x32_bf16 v[68:71], v[162:165], v[212:215], v[68:71]
	v_mfma_f32_16x16x32_bf16 v[64:67], v[170:173], v[212:215], v[64:67]
	s_setprio 0
	s_barrier
	s_add_i32 s21, s22, s18
	v_lshl_add_u64 v[174:175], s[52:53], 0, v[176:177]
	s_mov_b32 m0, s21
	ds_read_b128 v[184:187], v141 offset:16384
	ds_read_b128 v[188:191], v141 offset:17408
	ds_read_b128 v[192:195], v141 offset:18432
	ds_read_b128 v[196:199], v141 offset:19456
	ds_read_b128 v[200:203], v141 offset:20480
	ds_read_b128 v[204:207], v141 offset:21504
	ds_read_b128 v[208:211], v141 offset:22528
	ds_read_b128 v[212:215], v141 offset:23552
	global_load_lds_dwordx4 v[174:175], off
	s_add_i32 m0, s21, 0x2000
	v_lshl_add_u64 v[216:217], s[52:53], 0, v[128:129]
	s_add_u32 s52, s52, s6
	s_addc_u32 s53, s53, s7
	s_add_i32 s20, s20, s18
	global_load_lds_dwordx4 v[216:217], off
	v_lshl_add_u64 v[218:219], s[52:53], 0, v[176:177]
	s_mov_b32 m0, s20
	v_lshl_add_u64 v[220:221], s[52:53], 0, v[128:129]
	global_load_lds_dwordx4 v[218:219], off
	s_add_i32 m0, s20, 0x2000
	v_lshl_add_u64 v[222:223], s[38:39], 0, v[132:133]
	global_load_lds_dwordx4 v[220:221], off
	s_mov_b32 m0, s29
	v_lshl_add_u64 v[224:225], s[38:39], 0, v[130:131]
	global_load_lds_dwordx4 v[222:223], off
	s_mov_b32 m0, s30
	s_nop 0
	global_load_lds_dwordx4 v[224:225], off
	s_nop 15
	s_nop 15
	s_nop 15
	s_nop 15
	s_waitcnt vmcnt(8)
	s_waitcnt lgkmcnt(0)
	s_barrier
; #define PG8_STAGE(bufoff, gbase, voff) do { _Pragma("unroll") for (int _i = 0; _i < 2; ++_i) \
;         __builtin_amdgcn_global_load_lds((const unsigned*)((const char*)(gbase) + (voff)[_i]), (LAS unsigned*)(lds + (bufoff) + ldsw + _i * 8192), 16, 0, 0); } while (0)
; #define PG8_LDA(dst, b, h) do { _Pragma("unroll") for (int m = 0; m < 4; ++m) _Pragma("unroll") for (int k = 0; k < 2; ++k) dst[m][k] = *(const LAS bf16x8*)(lds + PG8_SA(b, h) + aoff + m * 2048 + k * 1024); } while (0)
; #define PG8_LDB(dst, b, h) do { _Pragma("unroll") for (int n = 0; n < 2; ++n) _Pragma("unroll") for (int k = 0; k < 2; ++k) dst[n][k] = *(const LAS bf16x8*)(lds + PG8_SB(b, h) + boff + n * 2048 + k * 1024); } while (0)
; #define PG8_MMA(ai, bj, At, Bt) do { __builtin_amdgcn_s_setprio(1); _Pragma("unroll") for (int m = 0; m < 4; ++m) _Pragma("unroll") for (int n = 0; n < 2; ++n) _Pragma("unroll") for (int k = 0; k < 2; ++k) \
;         acc[ai][bj][m][n] = __builtin_amdgcn_mfma_f32_16x16x32_bf16(Bt[n][k], At[m][k], acc[ai][bj][m][n], 0, 0, 0); __builtin_amdgcn_s_setprio(0); } while (0)
; #define PG8_WAIT_V(n) asm volatile("s_waitcnt vmcnt(" #n ")" ::: "memory")
; #define PG8_WAIT_L(n) asm volatile("s_waitcnt lgkmcnt(" #n ")" ::: "memory")
; #define PG8_BAR __builtin_amdgcn_s_barrier()
; #define PG8_SCHED __builtin_amdgcn_sched_barrier(0)
; template <class Epi, bool ALIGN_EPI = PG8_ALIGN>
; __device__ __forceinline__ void gemm_phase(LAS unsigned char* lds, const Gemm g, const StaticOrder& S, const Epi& E) {
;     ...
;             PG8_WAIT_V(8); PG8_WAIT_L(0); PG8_BAR; PG8_MMA(1, 0, At, B0); PG8_MMA(1, 1, At, B1); PG8_BAR; PG8_SCHED;
;             PG8_LDB(B0, 1, 0); PG8_LDB(B1, 1, 1); PG8_SCHED; PG8_LDA(At, 1, 0); PG8_STAGE(PG8_SA(0, 1), a2 + hstepA, voffA);
;             PG8_WAIT_V(8); PG8_WAIT_L(0); PG8_BAR; PG8_MMA(0, 0, At, B0); PG8_MMA(0, 1, At, B1); PG8_BAR; PG8_SCHED;
	s_setprio 1
	s_waitcnt lgkmcnt(0)
	v_mfma_f32_16x16x32_bf16 v[60:63], v[142:145], v[184:187], v[60:63]
	v_mfma_f32_16x16x32_bf16 v[56:59], v[150:153], v[184:187], v[56:59]
	v_mfma_f32_16x16x32_bf16 v[44:47], v[142:145], v[192:195], v[44:47]
	v_mfma_f32_16x16x32_bf16 v[40:43], v[150:153], v[192:195], v[40:43]
	v_mfma_f32_16x16x32_bf16 v[28:31], v[142:145], v[200:203], v[28:31]
	v_mfma_f32_16x16x32_bf16 v[24:27], v[150:153], v[200:203], v[24:27]
	v_mfma_f32_16x16x32_bf16 v[12:15], v[142:145], v[208:211], v[12:15]
	v_mfma_f32_16x16x32_bf16 v[8:11], v[150:153], v[208:211], v[8:11]
	v_mfma_f32_16x16x32_bf16 v[60:63], v[146:149], v[188:191], v[60:63]
	v_mfma_f32_16x16x32_bf16 v[56:59], v[154:157], v[188:191], v[56:59]
	v_mfma_f32_16x16x32_bf16 v[44:47], v[146:149], v[196:199], v[44:47]
	v_mfma_f32_16x16x32_bf16 v[40:43], v[154:157], v[196:199], v[40:43]
	v_mfma_f32_16x16x32_bf16 v[28:31], v[146:149], v[204:207], v[28:31]
	v_mfma_f32_16x16x32_bf16 v[24:27], v[154:157], v[204:207], v[24:27]
	v_mfma_f32_16x16x32_bf16 v[12:15], v[146:149], v[212:215], v[12:15]
	v_mfma_f32_16x16x32_bf16 v[8:11], v[154:157], v[212:215], v[8:11]
	s_setprio 0
	s_setprio 1
	v_mfma_f32_16x16x32_bf16 v[52:55], v[158:161], v[184:187], v[52:55]
	v_mfma_f32_16x16x32_bf16 v[48:51], v[166:169], v[184:187], v[48:51]
	v_mfma_f32_16x16x32_bf16 v[36:39], v[158:161], v[192:195], v[36:39]
	v_mfma_f32_16x16x32_bf16 v[32:35], v[166:169], v[192:195], v[32:35]
	v_mfma_f32_16x16x32_bf16 v[20:23], v[158:161], v[200:203], v[20:23]
	v_mfma_f32_16x16x32_bf16 v[16:19], v[166:169], v[200:203], v[16:19]
	v_mfma_f32_16x16x32_bf16 v[4:7], v[158:161], v[208:211], v[4:7]
	v_mfma_f32_16x16x32_bf16 v[0:3], v[166:169], v[208:211], v[0:3]
	v_mfma_f32_16x16x32_bf16 v[52:55], v[162:165], v[188:191], v[52:55]
	v_mfma_f32_16x16x32_bf16 v[48:51], v[170:173], v[188:191], v[48:51]
	v_mfma_f32_16x16x32_bf16 v[36:39], v[162:165], v[196:199], v[36:39]
	v_mfma_f32_16x16x32_bf16 v[32:35], v[170:173], v[196:199], v[32:35]
	v_mfma_f32_16x16x32_bf16 v[20:23], v[162:165], v[204:207], v[20:23]
	v_mfma_f32_16x16x32_bf16 v[16:19], v[170:173], v[204:207], v[16:19]
	v_mfma_f32_16x16x32_bf16 v[4:7], v[162:165], v[212:215], v[4:7]
	v_mfma_f32_16x16x32_bf16 v[0:3], v[170:173], v[212:215], v[0:3]
	s_setprio 0
	s_barrier
	s_add_i32 s20, 16, 0x18000
	s_add_i32 s21, 16, 0x1c000
	v_add_u32_e32 v154, s20, v139
	v_add_u32_e32 v170, s21, v139
	ds_read_b128 v[142:145], v154
	ds_read_b128 v[146:149], v154 offset:1024
	ds_read_b128 v[150:153], v154 offset:2048
	ds_read_b128 v[154:157], v154 offset:3072
	ds_read_b128 v[158:161], v170
	ds_read_b128 v[162:165], v170 offset:1024
	ds_read_b128 v[166:169], v170 offset:2048
	ds_read_b128 v[170:173], v170 offset:3072
	s_add_u32 s38, s38, 0x80000
	s_addc_u32 s39, s39, 0
	s_mov_b32 m0, s31
	v_lshl_add_u64 v[226:227], s[38:39], 0, v[132:133]
	ds_read_b128 v[184:187], v141 offset:32768
	ds_read_b128 v[188:191], v141 offset:33792
	ds_read_b128 v[192:195], v141 offset:34816
	ds_read_b128 v[196:199], v141 offset:35840
	ds_read_b128 v[200:203], v141 offset:36864
	ds_read_b128 v[204:207], v141 offset:37888
	ds_read_b128 v[208:211], v141 offset:38912
	ds_read_b128 v[212:215], v141 offset:39936
	global_load_lds_dwordx4 v[226:227], off
	v_lshl_add_u64 v[226:227], s[38:39], 0, v[130:131]
	s_mov_b32 m0, s42
	s_nop 0
	global_load_lds_dwordx4 v[226:227], off
	s_waitcnt vmcnt(8)
	s_waitcnt lgkmcnt(0)
	s_barrier
	s_setprio 1
	s_waitcnt lgkmcnt(0)
	v_mfma_f32_16x16x32_bf16 v[120:123], v[142:145], v[184:187], v[120:123]
	v_mfma_f32_16x16x32_bf16 v[124:127], v[150:153], v[184:187], v[124:127]
	v_mfma_f32_16x16x32_bf16 v[108:111], v[142:145], v[192:195], v[108:111]
	v_mfma_f32_16x16x32_bf16 v[104:107], v[150:153], v[192:195], v[104:107]
	v_mfma_f32_16x16x32_bf16 v[92:95], v[142:145], v[200:203], v[92:95]
	v_mfma_f32_16x16x32_bf16 v[88:91], v[150:153], v[200:203], v[88:91]
	v_mfma_f32_16x16x32_bf16 v[76:79], v[142:145], v[208:211], v[76:79]
	v_mfma_f32_16x16x32_bf16 v[72:75], v[150:153], v[208:211], v[72:75]
	v_mfma_f32_16x16x32_bf16 v[120:123], v[146:149], v[188:191], v[120:123]
	v_mfma_f32_16x16x32_bf16 v[124:127], v[154:157], v[188:191], v[124:127]
	v_mfma_f32_16x16x32_bf16 v[108:111], v[146:149], v[196:199], v[108:111]
	v_mfma_f32_16x16x32_bf16 v[104:107], v[154:157], v[196:199], v[104:107]
	v_mfma_f32_16x16x32_bf16 v[92:95], v[146:149], v[204:207], v[92:95]
	v_mfma_f32_16x16x32_bf16 v[88:91], v[154:157], v[204:207], v[88:91]
	v_mfma_f32_16x16x32_bf16 v[76:79], v[146:149], v[212:215], v[76:79]
	v_mfma_f32_16x16x32_bf16 v[72:75], v[154:157], v[212:215], v[72:75]
	s_setprio 0
	s_setprio 1
	v_mfma_f32_16x16x32_bf16 v[116:119], v[158:161], v[184:187], v[116:119]
	v_mfma_f32_16x16x32_bf16 v[112:115], v[166:169], v[184:187], v[112:115]
	v_mfma_f32_16x16x32_bf16 v[100:103], v[158:161], v[192:195], v[100:103]
	v_mfma_f32_16x16x32_bf16 v[96:99], v[166:169], v[192:195], v[96:99]
	v_mfma_f32_16x16x32_bf16 v[84:87], v[158:161], v[200:203], v[84:87]
	v_mfma_f32_16x16x32_bf16 v[80:83], v[166:169], v[200:203], v[80:83]
	v_mfma_f32_16x16x32_bf16 v[68:71], v[158:161], v[208:211], v[68:71]
	v_mfma_f32_16x16x32_bf16 v[64:67], v[166:169], v[208:211], v[64:67]
	v_mfma_f32_16x16x32_bf16 v[116:119], v[162:165], v[188:191], v[116:119]
	v_mfma_f32_16x16x32_bf16 v[112:115], v[170:173], v[188:191], v[112:115]
	v_mfma_f32_16x16x32_bf16 v[100:103], v[162:165], v[196:199], v[100:103]
	v_mfma_f32_16x16x32_bf16 v[96:99], v[170:173], v[196:199], v[96:99]
	v_mfma_f32_16x16x32_bf16 v[84:87], v[162:165], v[204:207], v[84:87]
	v_mfma_f32_16x16x32_bf16 v[80:83], v[170:173], v[204:207], v[80:83]
	v_mfma_f32_16x16x32_bf16 v[68:71], v[162:165], v[212:215], v[68:71]
	v_mfma_f32_16x16x32_bf16 v[64:67], v[170:173], v[212:215], v[64:67]
	s_setprio 0
	s_barrier
; #define PG8_STAGE(bufoff, gbase, voff) do { _Pragma("unroll") for (int _i = 0; _i < 2; ++_i) \
;         __builtin_amdgcn_global_load_lds((const unsigned*)((const char*)(gbase) + (voff)[_i]), (LAS unsigned*)(lds + (bufoff) + ldsw + _i * 8192), 16, 0, 0); } while (0)
; #define PG8_LDA(dst, b, h) do { _Pragma("unroll") for (int m = 0; m < 4; ++m) _Pragma("unroll") for (int k = 0; k < 2; ++k) dst[m][k] = *(const LAS bf16x8*)(lds + PG8_SA(b, h) + aoff + m * 2048 + k * 1024); } while (0)
; #define PG8_MMA(ai, bj, At, Bt) do { __builtin_amdgcn_s_setprio(1); _Pragma("unroll") for (int m = 0; m < 4; ++m) _Pragma("unroll") for (int n = 0; n < 2; ++n) _Pragma("unroll") for (int k = 0; k < 2; ++k) \
;         acc[ai][bj][m][n] = __builtin_amdgcn_mfma_f32_16x16x32_bf16(Bt[n][k], At[m][k], acc[ai][bj][m][n], 0, 0, 0); __builtin_amdgcn_s_setprio(0); } while (0)
; #define PG8_WAIT_V(n) asm volatile("s_waitcnt vmcnt(" #n ")" ::: "memory")
; #define PG8_WAIT_L(n) asm volatile("s_waitcnt lgkmcnt(" #n ")" ::: "memory")
; #define PG8_BAR __builtin_amdgcn_s_barrier()
; #define PG8_SCHED __builtin_amdgcn_sched_barrier(0)
; template <class Epi, bool ALIGN_EPI = PG8_ALIGN>
; __device__ __forceinline__ void gemm_phase(LAS unsigned char* lds, const Gemm g, const StaticOrder& S, const Epi& E) {
;     ...
;             PG8_LDA(At, 1, 1); PG8_STAGE(PG8_SB(1, 0), b3, voffB); PG8_STAGE(PG8_SB(1, 1), b3 + hstepB, voffB); PG8_STAGE(PG8_SA(1, 0), a3, voffA);
;             PG8_WAIT_V(8); PG8_WAIT_L(0); PG8_BAR; PG8_MMA(1, 0, At, B0); PG8_MMA(1, 1, At, B1); PG8_BAR; PG8_SCHED;
;         }
	s_add_i32 s20, s20, s18
	v_lshl_add_u64 v[174:175], v[174:175], 0, s[0:1]
	s_mov_b32 m0, s20
	ds_read_b128 v[184:187], v141 offset:49152
	ds_read_b128 v[188:191], v141 offset:50176
	ds_read_b128 v[192:195], v141 offset:51200
	ds_read_b128 v[196:199], v141 offset:52224
	ds_read_b128 v[200:203], v141 offset:53248
	ds_read_b128 v[204:207], v141 offset:54272
	ds_read_b128 v[208:211], v141 offset:55296
	ds_read_b128 v[212:215], v141 offset:56320
	global_load_lds_dwordx4 v[174:175], off
	v_lshl_add_u64 v[174:175], v[216:217], 0, s[0:1]
	s_add_i32 m0, s20, 0x2000
	s_add_i32 s20, s21, s18
	global_load_lds_dwordx4 v[174:175], off
	v_lshl_add_u64 v[174:175], v[218:219], 0, s[0:1]
	s_mov_b32 m0, s20
	s_nop 0
	global_load_lds_dwordx4 v[174:175], off
	v_lshl_add_u64 v[174:175], v[220:221], 0, s[0:1]
	s_add_i32 m0, s20, 0x2000
	s_nop 0
	global_load_lds_dwordx4 v[174:175], off
	v_lshl_add_u64 v[174:175], v[222:223], 0, s[0:1]
	s_mov_b32 m0, s34
	s_nop 0
	global_load_lds_dwordx4 v[174:175], off
	v_lshl_add_u64 v[174:175], v[224:225], 0, s[0:1]
	s_mov_b32 m0, s43
	s_nop 0
	global_load_lds_dwordx4 v[174:175], off
	s_nop 15
	s_nop 15
	s_nop 15
	s_nop 15
	s_waitcnt vmcnt(8)
	s_waitcnt lgkmcnt(0)
	s_barrier
	s_setprio 1
	s_waitcnt lgkmcnt(0)
	v_mfma_f32_16x16x32_bf16 v[60:63], v[142:145], v[184:187], v[60:63]
	v_mfma_f32_16x16x32_bf16 v[56:59], v[150:153], v[184:187], v[56:59]
	v_mfma_f32_16x16x32_bf16 v[44:47], v[142:145], v[192:195], v[44:47]
	v_mfma_f32_16x16x32_bf16 v[40:43], v[150:153], v[192:195], v[40:43]
	v_mfma_f32_16x16x32_bf16 v[28:31], v[142:145], v[200:203], v[28:31]
	v_mfma_f32_16x16x32_bf16 v[24:27], v[150:153], v[200:203], v[24:27]
	v_mfma_f32_16x16x32_bf16 v[12:15], v[142:145], v[208:211], v[12:15]
	v_mfma_f32_16x16x32_bf16 v[8:11], v[150:153], v[208:211], v[8:11]
	v_mfma_f32_16x16x32_bf16 v[60:63], v[146:149], v[188:191], v[60:63]
	v_mfma_f32_16x16x32_bf16 v[56:59], v[154:157], v[188:191], v[56:59]
	v_mfma_f32_16x16x32_bf16 v[44:47], v[146:149], v[196:199], v[44:47]
	v_mfma_f32_16x16x32_bf16 v[40:43], v[154:157], v[196:199], v[40:43]
	v_mfma_f32_16x16x32_bf16 v[28:31], v[146:149], v[204:207], v[28:31]
	v_mfma_f32_16x16x32_bf16 v[24:27], v[154:157], v[204:207], v[24:27]
	v_mfma_f32_16x16x32_bf16 v[12:15], v[146:149], v[212:215], v[12:15]
	v_mfma_f32_16x16x32_bf16 v[8:11], v[154:157], v[212:215], v[8:11]
	s_setprio 0
	s_setprio 1
	v_mfma_f32_16x16x32_bf16 v[52:55], v[158:161], v[184:187], v[52:55]
	v_mfma_f32_16x16x32_bf16 v[48:51], v[166:169], v[184:187], v[48:51]
	v_mfma_f32_16x16x32_bf16 v[36:39], v[158:161], v[192:195], v[36:39]
	v_mfma_f32_16x16x32_bf16 v[32:35], v[166:169], v[192:195], v[32:35]
	v_mfma_f32_16x16x32_bf16 v[20:23], v[158:161], v[200:203], v[20:23]
	v_mfma_f32_16x16x32_bf16 v[16:19], v[166:169], v[200:203], v[16:19]
	v_mfma_f32_16x16x32_bf16 v[4:7], v[158:161], v[208:211], v[4:7]
	v_mfma_f32_16x16x32_bf16 v[0:3], v[166:169], v[208:211], v[0:3]
	v_mfma_f32_16x16x32_bf16 v[52:55], v[162:165], v[188:191], v[52:55]
	v_mfma_f32_16x16x32_bf16 v[48:51], v[170:173], v[188:191], v[48:51]
	v_mfma_f32_16x16x32_bf16 v[36:39], v[162:165], v[196:199], v[36:39]
	v_mfma_f32_16x16x32_bf16 v[32:35], v[170:173], v[196:199], v[32:35]
	v_mfma_f32_16x16x32_bf16 v[20:23], v[162:165], v[204:207], v[20:23]
	v_mfma_f32_16x16x32_bf16 v[16:19], v[170:173], v[204:207], v[16:19]
	v_mfma_f32_16x16x32_bf16 v[4:7], v[162:165], v[212:215], v[4:7]
	v_mfma_f32_16x16x32_bf16 v[0:3], v[170:173], v[212:215], v[0:3]
	s_setprio 0
	s_barrier
	s_add_u32 s4, s4, 0x100
	s_addc_u32 s5, s5, 0
	s_add_u32 s40, s40, 0x100
	s_addc_u32 s41, s41, 0
	s_cmp_ge_i32 s51, s44
	s_mov_b32 s38, s51
	s_cbranch_scc0 .LBB0_458

; #define PG8_STAGE(bufoff, gbase, voff) do { _Pragma("unroll") for (int _i = 0; _i < 2; ++_i) \
;         __builtin_amdgcn_global_load_lds((const unsigned*)((const char*)(gbase) + (voff)[_i]), (LAS unsigned*)(lds + (bufoff) + ldsw + _i * 8192), 16, 0, 0); } while (0)
; #define PG8_LDA(dst, b, h) do { _Pragma("unroll") for (int m = 0; m < 4; ++m) _Pragma("unroll") for (int k = 0; k < 2; ++k) dst[m][k] = *(const LAS bf16x8*)(lds + PG8_SA(b, h) + aoff + m * 2048 + k * 1024); } while (0)
; #define PG8_LDB(dst, b, h) do { _Pragma("unroll") for (int n = 0; n < 2; ++n) _Pragma("unroll") for (int k = 0; k < 2; ++k) dst[n][k] = *(const LAS bf16x8*)(lds + PG8_SB(b, h) + boff + n * 2048 + k * 1024); } while (0)
; #define PG8_MMA(ai, bj, At, Bt) do { __builtin_amdgcn_s_setprio(1); _Pragma("unroll") for (int m = 0; m < 4; ++m) _Pragma("unroll") for (int n = 0; n < 2; ++n) _Pragma("unroll") for (int k = 0; k < 2; ++k) \
;         acc[ai][bj][m][n] = __builtin_amdgcn_mfma_f32_16x16x32_bf16(Bt[n][k], At[m][k], acc[ai][bj][m][n], 0, 0, 0); __builtin_amdgcn_s_setprio(0); } while (0)
; #define PG8_BAR __builtin_amdgcn_s_barrier()
; template <class Epi, bool ALIGN_EPI = PG8_ALIGN>
; __device__ __forceinline__ void gemm_phase(LAS unsigned char* lds, const Gemm g, const StaticOrder& S, const Epi& E) {
;     ...
;         const bool has_next = S.next(ui + 1, nxt);
;         const char* nA = has_next ? (const char*)g.A + (size_t)nxt.pm * tstepA : cA; const char* nB = has_next ? (const char*)g.Bt + (size_t)nxt.pn * tstepB : cB;
;         for (int t = 0; t < nt; t += 2) {
;             const bool last = (t == nt - 2);
;             const char* a1 = cA + (size_t)(t + 1) * kstep;
;             const char* a2 = last ? nA : cA + (size_t)(t + 2) * kstep; const char* b2 = last ? nB : cB + (size_t)(t + 2) * kstep;
;             const char* a3 = a2 + kstep; const char* b3 = b2 + kstep;
;             PG8_LDB(B0, 0, 0); PG8_LDB(B1, 0, 1); PG8_SCHED; PG8_LDA(At, 0, 0); PG8_STAGE(PG8_SA(1, 1), a1 + hstepA, voffA);
;             PG8_WAIT_V(8); PG8_WAIT_L(0); PG8_BAR; PG8_MMA(0, 0, At, B0); PG8_MMA(0, 1, At, B1); PG8_BAR; PG8_SCHED;
;             PG8_LDA(At, 0, 1); PG8_STAGE(PG8_SB(0, 0), b2, voffB); PG8_STAGE(PG8_SB(0, 1), b2 + hstepB, voffB); PG8_STAGE(PG8_SA(0, 0), a2, voffA);
;             PG8_WAIT_V(8); PG8_WAIT_L(0); PG8_BAR; PG8_MMA(1, 0, At, B0); PG8_MMA(1, 1, At, B1); PG8_BAR; PG8_SCHED;
.LBB0_481:
	s_add_i32 s53, s38, 2
	s_add_u32 s20, s4, 0xffff0080
	s_addc_u32 s21, s5, -1
	s_add_i32 s22, 16, 0x10000
	s_cmp_eq_u32 s47, s38
	s_cselect_b32 s39, s17, s21
	s_cselect_b32 s38, s52, s20
	s_cselect_b32 s55, s25, s41
	s_cselect_b32 s54, s24, s40
	s_add_i32 s20, 16, 0x14000
	v_add_u32_e32 v154, s22, v139
	v_add_u32_e32 v170, s20, v139
	ds_read_b128 v[142:145], v154
	ds_read_b128 v[146:149], v154 offset:1024
	ds_read_b128 v[150:153], v154 offset:2048
	ds_read_b128 v[154:157], v154 offset:3072
	ds_read_b128 v[158:161], v170
	ds_read_b128 v[162:165], v170 offset:1024
	ds_read_b128 v[166:169], v170 offset:2048
	ds_read_b128 v[170:173], v170 offset:3072
	v_lshl_add_u64 v[174:175], s[4:5], 0, v[134:135]
	s_add_i32 m0, s26, 0xc000
	ds_read_b128 v[184:187], v141
	ds_read_b128 v[188:191], v141 offset:1024
	ds_read_b128 v[192:195], v141 offset:2048
	ds_read_b128 v[196:199], v141 offset:3072
	ds_read_b128 v[200:203], v141 offset:4096
	ds_read_b128 v[204:207], v141 offset:5120
	ds_read_b128 v[208:211], v141 offset:6144
	ds_read_b128 v[212:215], v141 offset:7168
	global_load_lds_dwordx4 v[174:175], off
	v_lshl_add_u64 v[174:175], s[4:5], 0, v[136:137]
	s_add_i32 m0, s26, 0xe000
	s_nop 0
	global_load_lds_dwordx4 v[174:175], off
	s_waitcnt vmcnt(8)
	s_waitcnt lgkmcnt(0)
	s_barrier
	s_setprio 1
	s_waitcnt lgkmcnt(0)
	v_mfma_f32_16x16x32_bf16 v[120:123], v[142:145], v[184:187], v[120:123]
	v_mfma_f32_16x16x32_bf16 v[124:127], v[150:153], v[184:187], v[124:127]
	v_mfma_f32_16x16x32_bf16 v[108:111], v[142:145], v[192:195], v[108:111]
	v_mfma_f32_16x16x32_bf16 v[104:107], v[150:153], v[192:195], v[104:107]
	v_mfma_f32_16x16x32_bf16 v[92:95], v[142:145], v[200:203], v[92:95]
	v_mfma_f32_16x16x32_bf16 v[88:91], v[150:153], v[200:203], v[88:91]
	v_mfma_f32_16x16x32_bf16 v[76:79], v[142:145], v[208:211], v[76:79]
	v_mfma_f32_16x16x32_bf16 v[72:75], v[150:153], v[208:211], v[72:75]
	v_mfma_f32_16x16x32_bf16 v[120:123], v[146:149], v[188:191], v[120:123]
	v_mfma_f32_16x16x32_bf16 v[124:127], v[154:157], v[188:191], v[124:127]
	v_mfma_f32_16x16x32_bf16 v[108:111], v[146:149], v[196:199], v[108:111]
	v_mfma_f32_16x16x32_bf16 v[104:107], v[154:157], v[196:199], v[104:107]
	v_mfma_f32_16x16x32_bf16 v[92:95], v[146:149], v[204:207], v[92:95]
	v_mfma_f32_16x16x32_bf16 v[88:91], v[154:157], v[204:207], v[88:91]
	v_mfma_f32_16x16x32_bf16 v[76:79], v[146:149], v[212:215], v[76:79]
	v_mfma_f32_16x16x32_bf16 v[72:75], v[154:157], v[212:215], v[72:75]
	s_setprio 0
	s_setprio 1
	v_mfma_f32_16x16x32_bf16 v[116:119], v[158:161], v[184:187], v[116:119]
	v_mfma_f32_16x16x32_bf16 v[112:115], v[166:169], v[184:187], v[112:115]
	v_mfma_f32_16x16x32_bf16 v[100:103], v[158:161], v[192:195], v[100:103]
	v_mfma_f32_16x16x32_bf16 v[96:99], v[166:169], v[192:195], v[96:99]
	v_mfma_f32_16x16x32_bf16 v[84:87], v[158:161], v[200:203], v[84:87]
	v_mfma_f32_16x16x32_bf16 v[80:83], v[166:169], v[200:203], v[80:83]
	v_mfma_f32_16x16x32_bf16 v[68:71], v[158:161], v[208:211], v[68:71]
	v_mfma_f32_16x16x32_bf16 v[64:67], v[166:169], v[208:211], v[64:67]
	v_mfma_f32_16x16x32_bf16 v[116:119], v[162:165], v[188:191], v[116:119]
	v_mfma_f32_16x16x32_bf16 v[112:115], v[170:173], v[188:191], v[112:115]
	v_mfma_f32_16x16x32_bf16 v[100:103], v[162:165], v[196:199], v[100:103]
	v_mfma_f32_16x16x32_bf16 v[96:99], v[170:173], v[196:199], v[96:99]
	v_mfma_f32_16x16x32_bf16 v[84:87], v[162:165], v[204:207], v[84:87]
	v_mfma_f32_16x16x32_bf16 v[80:83], v[170:173], v[204:207], v[80:83]
	v_mfma_f32_16x16x32_bf16 v[68:71], v[162:165], v[212:215], v[68:71]
	v_mfma_f32_16x16x32_bf16 v[64:67], v[170:173], v[212:215], v[64:67]
	s_setprio 0
	s_barrier
	s_add_i32 s21, s22, s42
	v_lshl_add_u64 v[174:175], s[54:55], 0, v[176:177]
	s_mov_b32 m0, s21
	ds_read_b128 v[184:187], v141 offset:16384
	ds_read_b128 v[188:191], v141 offset:17408
	ds_read_b128 v[192:195], v141 offset:18432
	ds_read_b128 v[196:199], v141 offset:19456
	ds_read_b128 v[200:203], v141 offset:20480
	ds_read_b128 v[204:207], v141 offset:21504
	ds_read_b128 v[208:211], v141 offset:22528
	ds_read_b128 v[212:215], v141 offset:23552
	global_load_lds_dwordx4 v[174:175], off
	s_add_i32 m0, s21, 0x2000
	v_lshl_add_u64 v[216:217], s[54:55], 0, v[128:129]
	s_add_u32 s54, s54, s6
	s_addc_u32 s55, s55, s7
	s_add_i32 s20, s20, s42
	global_load_lds_dwordx4 v[216:217], off
	v_lshl_add_u64 v[218:219], s[54:55], 0, v[176:177]
	s_mov_b32 m0, s20
	v_lshl_add_u64 v[220:221], s[54:55], 0, v[128:129]
	global_load_lds_dwordx4 v[218:219], off
	s_add_i32 m0, s20, 0x2000
	v_lshl_add_u64 v[222:223], s[38:39], 0, v[132:133]
	global_load_lds_dwordx4 v[220:221], off
	s_mov_b32 m0, s26
	v_lshl_add_u64 v[224:225], s[38:39], 0, v[130:131]
	global_load_lds_dwordx4 v[222:223], off
	s_mov_b32 m0, s27
	s_nop 0
	global_load_lds_dwordx4 v[224:225], off
	s_nop 15
	s_nop 15
	s_nop 15
	s_nop 15
	s_waitcnt vmcnt(8)
	s_waitcnt lgkmcnt(0)
	s_barrier
; #define PG8_STAGE(bufoff, gbase, voff) do { _Pragma("unroll") for (int _i = 0; _i < 2; ++_i) \
;         __builtin_amdgcn_global_load_lds((const unsigned*)((const char*)(gbase) + (voff)[_i]), (LAS unsigned*)(lds + (bufoff) + ldsw + _i * 8192), 16, 0, 0); } while (0)
; #define PG8_LDA(dst, b, h) do { _Pragma("unroll") for (int m = 0; m < 4; ++m) _Pragma("unroll") for (int k = 0; k < 2; ++k) dst[m][k] = *(const LAS bf16x8*)(lds + PG8_SA(b, h) + aoff + m * 2048 + k * 1024); } while (0)
; #define PG8_LDB(dst, b, h) do { _Pragma("unroll") for (int n = 0; n < 2; ++n) _Pragma("unroll") for (int k = 0; k < 2; ++k) dst[n][k] = *(const LAS bf16x8*)(lds + PG8_SB(b, h) + boff + n * 2048 + k * 1024); } while (0)
; #define PG8_MMA(ai, bj, At, Bt) do { __builtin_amdgcn_s_setprio(1); _Pragma("unroll") for (int m = 0; m < 4; ++m) _Pragma("unroll") for (int n = 0; n < 2; ++n) _Pragma("unroll") for (int k = 0; k < 2; ++k) \
;         acc[ai][bj][m][n] = __builtin_amdgcn_mfma_f32_16x16x32_bf16(Bt[n][k], At[m][k], acc[ai][bj][m][n], 0, 0, 0); __builtin_amdgcn_s_setprio(0); } while (0)
; #define PG8_WAIT_V(n) asm volatile("s_waitcnt vmcnt(" #n ")" ::: "memory")
; #define PG8_WAIT_L(n) asm volatile("s_waitcnt lgkmcnt(" #n ")" ::: "memory")
; #define PG8_BAR __builtin_amdgcn_s_barrier()
; #define PG8_SCHED __builtin_amdgcn_sched_barrier(0)
; template <class Epi, bool ALIGN_EPI = PG8_ALIGN>
; __device__ __forceinline__ void gemm_phase(LAS unsigned char* lds, const Gemm g, const StaticOrder& S, const Epi& E) {
;     ...
;             PG8_WAIT_V(8); PG8_WAIT_L(0); PG8_BAR; PG8_MMA(1, 0, At, B0); PG8_MMA(1, 1, At, B1); PG8_BAR; PG8_SCHED;
;             PG8_LDB(B0, 1, 0); PG8_LDB(B1, 1, 1); PG8_SCHED; PG8_LDA(At, 1, 0); PG8_STAGE(PG8_SA(0, 1), a2 + hstepA, voffA);
;             PG8_WAIT_V(8); PG8_WAIT_L(0); PG8_BAR; PG8_MMA(0, 0, At, B0); PG8_MMA(0, 1, At, B1); PG8_BAR; PG8_SCHED;
	s_setprio 1
	s_waitcnt lgkmcnt(0)
	v_mfma_f32_16x16x32_bf16 v[60:63], v[142:145], v[184:187], v[60:63]
	v_mfma_f32_16x16x32_bf16 v[56:59], v[150:153], v[184:187], v[56:59]
	v_mfma_f32_16x16x32_bf16 v[44:47], v[142:145], v[192:195], v[44:47]
	v_mfma_f32_16x16x32_bf16 v[40:43], v[150:153], v[192:195], v[40:43]
	v_mfma_f32_16x16x32_bf16 v[28:31], v[142:145], v[200:203], v[28:31]
	v_mfma_f32_16x16x32_bf16 v[24:27], v[150:153], v[200:203], v[24:27]
	v_mfma_f32_16x16x32_bf16 v[12:15], v[142:145], v[208:211], v[12:15]
	v_mfma_f32_16x16x32_bf16 v[8:11], v[150:153], v[208:211], v[8:11]
	v_mfma_f32_16x16x32_bf16 v[60:63], v[146:149], v[188:191], v[60:63]
	v_mfma_f32_16x16x32_bf16 v[56:59], v[154:157], v[188:191], v[56:59]
	v_mfma_f32_16x16x32_bf16 v[44:47], v[146:149], v[196:199], v[44:47]
	v_mfma_f32_16x16x32_bf16 v[40:43], v[154:157], v[196:199], v[40:43]
	v_mfma_f32_16x16x32_bf16 v[28:31], v[146:149], v[204:207], v[28:31]
	v_mfma_f32_16x16x32_bf16 v[24:27], v[154:157], v[204:207], v[24:27]
	v_mfma_f32_16x16x32_bf16 v[12:15], v[146:149], v[212:215], v[12:15]
	v_mfma_f32_16x16x32_bf16 v[8:11], v[154:157], v[212:215], v[8:11]
	s_setprio 0
	s_setprio 1
	v_mfma_f32_16x16x32_bf16 v[52:55], v[158:161], v[184:187], v[52:55]
	v_mfma_f32_16x16x32_bf16 v[48:51], v[166:169], v[184:187], v[48:51]
	v_mfma_f32_16x16x32_bf16 v[36:39], v[158:161], v[192:195], v[36:39]
	v_mfma_f32_16x16x32_bf16 v[32:35], v[166:169], v[192:195], v[32:35]
	v_mfma_f32_16x16x32_bf16 v[20:23], v[158:161], v[200:203], v[20:23]
	v_mfma_f32_16x16x32_bf16 v[16:19], v[166:169], v[200:203], v[16:19]
	v_mfma_f32_16x16x32_bf16 v[4:7], v[158:161], v[208:211], v[4:7]
	v_mfma_f32_16x16x32_bf16 v[0:3], v[166:169], v[208:211], v[0:3]
	v_mfma_f32_16x16x32_bf16 v[52:55], v[162:165], v[188:191], v[52:55]
	v_mfma_f32_16x16x32_bf16 v[48:51], v[170:173], v[188:191], v[48:51]
	v_mfma_f32_16x16x32_bf16 v[36:39], v[162:165], v[196:199], v[36:39]
	v_mfma_f32_16x16x32_bf16 v[32:35], v[170:173], v[196:199], v[32:35]
	v_mfma_f32_16x16x32_bf16 v[20:23], v[162:165], v[204:207], v[20:23]
	v_mfma_f32_16x16x32_bf16 v[16:19], v[170:173], v[204:207], v[16:19]
	v_mfma_f32_16x16x32_bf16 v[4:7], v[162:165], v[212:215], v[4:7]
	v_mfma_f32_16x16x32_bf16 v[0:3], v[170:173], v[212:215], v[0:3]
	s_setprio 0
	s_barrier
	s_add_i32 s20, 16, 0x18000
	s_add_i32 s21, 16, 0x1c000
	v_add_u32_e32 v154, s20, v139
	v_add_u32_e32 v170, s21, v139
	ds_read_b128 v[142:145], v154
	ds_read_b128 v[146:149], v154 offset:1024
	ds_read_b128 v[150:153], v154 offset:2048
	ds_read_b128 v[154:157], v154 offset:3072
	ds_read_b128 v[158:161], v170
	ds_read_b128 v[162:165], v170 offset:1024
	ds_read_b128 v[166:169], v170 offset:2048
	ds_read_b128 v[170:173], v170 offset:3072
	s_add_u32 s38, s38, 0x10000
	s_addc_u32 s39, s39, 0
	s_mov_b32 m0, s43
	v_lshl_add_u64 v[226:227], s[38:39], 0, v[132:133]
	ds_read_b128 v[184:187], v141 offset:32768
	ds_read_b128 v[188:191], v141 offset:33792
	ds_read_b128 v[192:195], v141 offset:34816
	ds_read_b128 v[196:199], v141 offset:35840
	ds_read_b128 v[200:203], v141 offset:36864
	ds_read_b128 v[204:207], v141 offset:37888
	ds_read_b128 v[208:211], v141 offset:38912
	ds_read_b128 v[212:215], v141 offset:39936
	global_load_lds_dwordx4 v[226:227], off
	v_lshl_add_u64 v[226:227], s[38:39], 0, v[130:131]
	s_mov_b32 m0, s44
	s_nop 0
	global_load_lds_dwordx4 v[226:227], off
	s_waitcnt vmcnt(8)
	s_waitcnt lgkmcnt(0)
	s_barrier
	s_setprio 1
	s_waitcnt lgkmcnt(0)
	v_mfma_f32_16x16x32_bf16 v[120:123], v[142:145], v[184:187], v[120:123]
	v_mfma_f32_16x16x32_bf16 v[124:127], v[150:153], v[184:187], v[124:127]
	v_mfma_f32_16x16x32_bf16 v[108:111], v[142:145], v[192:195], v[108:111]
	v_mfma_f32_16x16x32_bf16 v[104:107], v[150:153], v[192:195], v[104:107]
	v_mfma_f32_16x16x32_bf16 v[92:95], v[142:145], v[200:203], v[92:95]
	v_mfma_f32_16x16x32_bf16 v[88:91], v[150:153], v[200:203], v[88:91]
	v_mfma_f32_16x16x32_bf16 v[76:79], v[142:145], v[208:211], v[76:79]
	v_mfma_f32_16x16x32_bf16 v[72:75], v[150:153], v[208:211], v[72:75]
	v_mfma_f32_16x16x32_bf16 v[120:123], v[146:149], v[188:191], v[120:123]
	v_mfma_f32_16x16x32_bf16 v[124:127], v[154:157], v[188:191], v[124:127]
	v_mfma_f32_16x16x32_bf16 v[108:111], v[146:149], v[196:199], v[108:111]
	v_mfma_f32_16x16x32_bf16 v[104:107], v[154:157], v[196:199], v[104:107]
	v_mfma_f32_16x16x32_bf16 v[92:95], v[146:149], v[204:207], v[92:95]
	v_mfma_f32_16x16x32_bf16 v[88:91], v[154:157], v[204:207], v[88:91]
	v_mfma_f32_16x16x32_bf16 v[76:79], v[146:149], v[212:215], v[76:79]
	v_mfma_f32_16x16x32_bf16 v[72:75], v[154:157], v[212:215], v[72:75]
	s_setprio 0
	s_setprio 1
	v_mfma_f32_16x16x32_bf16 v[116:119], v[158:161], v[184:187], v[116:119]
	v_mfma_f32_16x16x32_bf16 v[112:115], v[166:169], v[184:187], v[112:115]
	v_mfma_f32_16x16x32_bf16 v[100:103], v[158:161], v[192:195], v[100:103]
	v_mfma_f32_16x16x32_bf16 v[96:99], v[166:169], v[192:195], v[96:99]
	v_mfma_f32_16x16x32_bf16 v[84:87], v[158:161], v[200:203], v[84:87]
	v_mfma_f32_16x16x32_bf16 v[80:83], v[166:169], v[200:203], v[80:83]
	v_mfma_f32_16x16x32_bf16 v[68:71], v[158:161], v[208:211], v[68:71]
	v_mfma_f32_16x16x32_bf16 v[64:67], v[166:169], v[208:211], v[64:67]
	v_mfma_f32_16x16x32_bf16 v[116:119], v[162:165], v[188:191], v[116:119]
	v_mfma_f32_16x16x32_bf16 v[112:115], v[170:173], v[188:191], v[112:115]
	v_mfma_f32_16x16x32_bf16 v[100:103], v[162:165], v[196:199], v[100:103]
	v_mfma_f32_16x16x32_bf16 v[96:99], v[170:173], v[196:199], v[96:99]
	v_mfma_f32_16x16x32_bf16 v[84:87], v[162:165], v[204:207], v[84:87]
	v_mfma_f32_16x16x32_bf16 v[80:83], v[170:173], v[204:207], v[80:83]
	v_mfma_f32_16x16x32_bf16 v[68:71], v[162:165], v[212:215], v[68:71]
	v_mfma_f32_16x16x32_bf16 v[64:67], v[170:173], v[212:215], v[64:67]
	s_setprio 0
	s_barrier
; #define PG8_STAGE(bufoff, gbase, voff) do { _Pragma("unroll") for (int _i = 0; _i < 2; ++_i) \
;         __builtin_amdgcn_global_load_lds((const unsigned*)((const char*)(gbase) + (voff)[_i]), (LAS unsigned*)(lds + (bufoff) + ldsw + _i * 8192), 16, 0, 0); } while (0)
; #define PG8_LDA(dst, b, h) do { _Pragma("unroll") for (int m = 0; m < 4; ++m) _Pragma("unroll") for (int k = 0; k < 2; ++k) dst[m][k] = *(const LAS bf16x8*)(lds + PG8_SA(b, h) + aoff + m * 2048 + k * 1024); } while (0)
; #define PG8_MMA(ai, bj, At, Bt) do { __builtin_amdgcn_s_setprio(1); _Pragma("unroll") for (int m = 0; m < 4; ++m) _Pragma("unroll") for (int n = 0; n < 2; ++n) _Pragma("unroll") for (int k = 0; k < 2; ++k) \
;         acc[ai][bj][m][n] = __builtin_amdgcn_mfma_f32_16x16x32_bf16(Bt[n][k], At[m][k], acc[ai][bj][m][n], 0, 0, 0); __builtin_amdgcn_s_setprio(0); } while (0)
; #define PG8_WAIT_V(n) asm volatile("s_waitcnt vmcnt(" #n ")" ::: "memory")
; #define PG8_WAIT_L(n) asm volatile("s_waitcnt lgkmcnt(" #n ")" ::: "memory")
; #define PG8_BAR __builtin_amdgcn_s_barrier()
; #define PG8_SCHED __builtin_amdgcn_sched_barrier(0)
; template <class Epi, bool ALIGN_EPI = PG8_ALIGN>
; __device__ __forceinline__ void gemm_phase(LAS unsigned char* lds, const Gemm g, const StaticOrder& S, const Epi& E) {
;     ...
;             PG8_LDA(At, 1, 1); PG8_STAGE(PG8_SB(1, 0), b3, voffB); PG8_STAGE(PG8_SB(1, 1), b3 + hstepB, voffB); PG8_STAGE(PG8_SA(1, 0), a3, voffA);
;             PG8_WAIT_V(8); PG8_WAIT_L(0); PG8_BAR; PG8_MMA(1, 0, At, B0); PG8_MMA(1, 1, At, B1); PG8_BAR; PG8_SCHED;
;         }
	s_add_i32 s20, s20, s42
	v_lshl_add_u64 v[174:175], v[174:175], 0, s[0:1]
	s_mov_b32 m0, s20
	ds_read_b128 v[184:187], v141 offset:49152
	ds_read_b128 v[188:191], v141 offset:50176
	ds_read_b128 v[192:195], v141 offset:51200
	ds_read_b128 v[196:199], v141 offset:52224
	ds_read_b128 v[200:203], v141 offset:53248
	ds_read_b128 v[204:207], v141 offset:54272
	ds_read_b128 v[208:211], v141 offset:55296
	ds_read_b128 v[212:215], v141 offset:56320
	global_load_lds_dwordx4 v[174:175], off
	v_lshl_add_u64 v[174:175], v[216:217], 0, s[0:1]
	s_add_i32 m0, s20, 0x2000
	s_add_i32 s20, s21, s42
	global_load_lds_dwordx4 v[174:175], off
	v_lshl_add_u64 v[174:175], v[218:219], 0, s[0:1]
	s_mov_b32 m0, s20
	s_nop 0
	global_load_lds_dwordx4 v[174:175], off
	v_lshl_add_u64 v[174:175], v[220:221], 0, s[0:1]
	s_add_i32 m0, s20, 0x2000
	s_nop 0
	global_load_lds_dwordx4 v[174:175], off
	v_lshl_add_u64 v[174:175], v[222:223], 0, s[0:1]
	s_mov_b32 m0, s45
	s_nop 0
	global_load_lds_dwordx4 v[174:175], off
	v_lshl_add_u64 v[174:175], v[224:225], 0, s[0:1]
	s_mov_b32 m0, s46
	s_nop 0
	global_load_lds_dwordx4 v[174:175], off
	s_nop 15
	s_nop 15
	s_nop 15
	s_nop 15
	s_waitcnt vmcnt(8)
	s_waitcnt lgkmcnt(0)
	s_barrier
	s_setprio 1
	s_waitcnt lgkmcnt(0)
	v_mfma_f32_16x16x32_bf16 v[60:63], v[142:145], v[184:187], v[60:63]
	v_mfma_f32_16x16x32_bf16 v[56:59], v[150:153], v[184:187], v[56:59]
	v_mfma_f32_16x16x32_bf16 v[44:47], v[142:145], v[192:195], v[44:47]
	v_mfma_f32_16x16x32_bf16 v[40:43], v[150:153], v[192:195], v[40:43]
	v_mfma_f32_16x16x32_bf16 v[28:31], v[142:145], v[200:203], v[28:31]
	v_mfma_f32_16x16x32_bf16 v[24:27], v[150:153], v[200:203], v[24:27]
	v_mfma_f32_16x16x32_bf16 v[12:15], v[142:145], v[208:211], v[12:15]
	v_mfma_f32_16x16x32_bf16 v[8:11], v[150:153], v[208:211], v[8:11]
	v_mfma_f32_16x16x32_bf16 v[60:63], v[146:149], v[188:191], v[60:63]
	v_mfma_f32_16x16x32_bf16 v[56:59], v[154:157], v[188:191], v[56:59]
	v_mfma_f32_16x16x32_bf16 v[44:47], v[146:149], v[196:199], v[44:47]
	v_mfma_f32_16x16x32_bf16 v[40:43], v[154:157], v[196:199], v[40:43]
	v_mfma_f32_16x16x32_bf16 v[28:31], v[146:149], v[204:207], v[28:31]
	v_mfma_f32_16x16x32_bf16 v[24:27], v[154:157], v[204:207], v[24:27]
	v_mfma_f32_16x16x32_bf16 v[12:15], v[146:149], v[212:215], v[12:15]
	v_mfma_f32_16x16x32_bf16 v[8:11], v[154:157], v[212:215], v[8:11]
	s_setprio 0
	s_setprio 1
	v_mfma_f32_16x16x32_bf16 v[52:55], v[158:161], v[184:187], v[52:55]
	v_mfma_f32_16x16x32_bf16 v[48:51], v[166:169], v[184:187], v[48:51]
	v_mfma_f32_16x16x32_bf16 v[36:39], v[158:161], v[192:195], v[36:39]
	v_mfma_f32_16x16x32_bf16 v[32:35], v[166:169], v[192:195], v[32:35]
	v_mfma_f32_16x16x32_bf16 v[20:23], v[158:161], v[200:203], v[20:23]
	v_mfma_f32_16x16x32_bf16 v[16:19], v[166:169], v[200:203], v[16:19]
	v_mfma_f32_16x16x32_bf16 v[4:7], v[158:161], v[208:211], v[4:7]
	v_mfma_f32_16x16x32_bf16 v[0:3], v[166:169], v[208:211], v[0:3]
	v_mfma_f32_16x16x32_bf16 v[52:55], v[162:165], v[188:191], v[52:55]
	v_mfma_f32_16x16x32_bf16 v[48:51], v[170:173], v[188:191], v[48:51]
	v_mfma_f32_16x16x32_bf16 v[36:39], v[162:165], v[196:199], v[36:39]
	v_mfma_f32_16x16x32_bf16 v[32:35], v[170:173], v[196:199], v[32:35]
	v_mfma_f32_16x16x32_bf16 v[20:23], v[162:165], v[204:207], v[20:23]
	v_mfma_f32_16x16x32_bf16 v[16:19], v[170:173], v[204:207], v[16:19]
	v_mfma_f32_16x16x32_bf16 v[4:7], v[162:165], v[212:215], v[4:7]
	v_mfma_f32_16x16x32_bf16 v[0:3], v[170:173], v[212:215], v[0:3]
	s_setprio 0
	s_barrier
	s_add_u32 s4, s4, 0x100
	s_addc_u32 s5, s5, 0
	s_add_u32 s40, s40, 0x100
	s_addc_u32 s41, s41, 0
	s_cmp_ge_i32 s53, s34
	s_mov_b32 s38, s53
	s_cbranch_scc0 .LBB0_481

; #define PG8_STAGE(bufoff, gbase, voff) do { _Pragma("unroll") for (int _i = 0; _i < 2; ++_i) \
;         __builtin_amdgcn_global_load_lds((const unsigned*)((const char*)(gbase) + (voff)[_i]), (LAS unsigned*)(lds + (bufoff) + ldsw + _i * 8192), 16, 0, 0); } while (0)
; #define PG8_LDA(dst, b, h) do { _Pragma("unroll") for (int m = 0; m < 4; ++m) _Pragma("unroll") for (int k = 0; k < 2; ++k) dst[m][k] = *(const LAS bf16x8*)(lds + PG8_SA(b, h) + aoff + m * 2048 + k * 1024); } while (0)
; #define PG8_LDB(dst, b, h) do { _Pragma("unroll") for (int n = 0; n < 2; ++n) _Pragma("unroll") for (int k = 0; k < 2; ++k) dst[n][k] = *(const LAS bf16x8*)(lds + PG8_SB(b, h) + boff + n * 2048 + k * 1024); } while (0)
; #define PG8_MMA(ai, bj, At, Bt) do { __builtin_amdgcn_s_setprio(1); _Pragma("unroll") for (int m = 0; m < 4; ++m) _Pragma("unroll") for (int n = 0; n < 2; ++n) _Pragma("unroll") for (int k = 0; k < 2; ++k) \
;         acc[ai][bj][m][n] = __builtin_amdgcn_mfma_f32_16x16x32_bf16(Bt[n][k], At[m][k], acc[ai][bj][m][n], 0, 0, 0); __builtin_amdgcn_s_setprio(0); } while (0)
; #define PG8_BAR __builtin_amdgcn_s_barrier()
; template <class Epi, bool ALIGN_EPI = PG8_ALIGN>
; __device__ __forceinline__ void gemm_phase(LAS unsigned char* lds, const Gemm g, const StaticOrder& S, const Epi& E) {
;     ...
;         const bool has_next = S.next(ui + 1, nxt);
;         const char* nA = has_next ? (const char*)g.A + (size_t)nxt.pm * tstepA : cA; const char* nB = has_next ? (const char*)g.Bt + (size_t)nxt.pn * tstepB : cB;
;         for (int t = 0; t < nt; t += 2) {
;             const bool last = (t == nt - 2);
;             const char* a1 = cA + (size_t)(t + 1) * kstep;
;             const char* a2 = last ? nA : cA + (size_t)(t + 2) * kstep; const char* b2 = last ? nB : cB + (size_t)(t + 2) * kstep;
;             const char* a3 = a2 + kstep; const char* b3 = b2 + kstep;
;             PG8_LDB(B0, 0, 0); PG8_LDB(B1, 0, 1); PG8_SCHED; PG8_LDA(At, 0, 0); PG8_STAGE(PG8_SA(1, 1), a1 + hstepA, voffA);
;             PG8_WAIT_V(8); PG8_WAIT_L(0); PG8_BAR; PG8_MMA(0, 0, At, B0); PG8_MMA(0, 1, At, B1); PG8_BAR; PG8_SCHED;
;             PG8_LDA(At, 0, 1); PG8_STAGE(PG8_SB(0, 0), b2, voffB); PG8_STAGE(PG8_SB(0, 1), b2 + hstepB, voffB); PG8_STAGE(PG8_SA(0, 0), a2, voffA);
;             PG8_WAIT_V(8); PG8_WAIT_L(0); PG8_BAR; PG8_MMA(1, 0, At, B0); PG8_MMA(1, 1, At, B1); PG8_BAR; PG8_SCHED;
.LBB0_642:
	s_add_i32 s53, s38, 2
	s_add_u32 s36, s24, 0x100
	s_addc_u32 s37, s25, 0
	s_add_i32 s20, 16, 0x10000
	s_cmp_eq_u32 s48, s38
	s_cselect_b32 s39, s3, s37
	s_cselect_b32 s38, s2, s36
	v_add_u32_e32 v142, s20, v149
	s_cselect_b32 s55, s17, s52
	s_cselect_b32 s54, s16, s51
	s_add_i32 s21, 16, 0x14000
	ds_read_b128 v[138:141], v142
	ds_read_b128 v[152:155], v142 offset:1024
	ds_read_b128 v[156:159], v142 offset:2048
	ds_read_b128 v[160:163], v142 offset:3072
	v_add_u32_e32 v142, s21, v149
	ds_read_b128 v[164:167], v142
	ds_read_b128 v[168:171], v142 offset:1024
	ds_read_b128 v[172:175], v142 offset:2048
	ds_read_b128 v[184:187], v142 offset:3072
	v_lshl_add_u64 v[142:143], s[24:25], 0, v[134:135]
	s_add_i32 m0, s31, 0xc000
	ds_read_b128 v[188:191], v151
	ds_read_b128 v[192:195], v151 offset:1024
	ds_read_b128 v[196:199], v151 offset:2048
	ds_read_b128 v[200:203], v151 offset:3072
	ds_read_b128 v[204:207], v151 offset:4096
	ds_read_b128 v[208:211], v151 offset:5120
	ds_read_b128 v[212:215], v151 offset:6144
	ds_read_b128 v[216:219], v151 offset:7168
	global_load_lds_dwordx4 v[142:143], off
	v_lshl_add_u64 v[142:143], s[24:25], 0, v[136:137]
	s_add_i32 m0, s31, 0xe000
	s_nop 0
	global_load_lds_dwordx4 v[142:143], off
	s_waitcnt vmcnt(8)
	s_waitcnt lgkmcnt(0)
	s_barrier
	s_setprio 1
	s_waitcnt lgkmcnt(0)
	v_mfma_f32_16x16x32_bf16 v[120:123], v[138:141], v[188:191], v[120:123]
	v_mfma_f32_16x16x32_bf16 v[124:127], v[156:159], v[188:191], v[124:127]
	v_mfma_f32_16x16x32_bf16 v[108:111], v[138:141], v[196:199], v[108:111]
	v_mfma_f32_16x16x32_bf16 v[104:107], v[156:159], v[196:199], v[104:107]
	v_mfma_f32_16x16x32_bf16 v[92:95], v[138:141], v[204:207], v[92:95]
	v_mfma_f32_16x16x32_bf16 v[88:91], v[156:159], v[204:207], v[88:91]
	v_mfma_f32_16x16x32_bf16 v[76:79], v[138:141], v[212:215], v[76:79]
	v_mfma_f32_16x16x32_bf16 v[72:75], v[156:159], v[212:215], v[72:75]
	v_mfma_f32_16x16x32_bf16 v[120:123], v[152:155], v[192:195], v[120:123]
	v_mfma_f32_16x16x32_bf16 v[124:127], v[160:163], v[192:195], v[124:127]
	v_mfma_f32_16x16x32_bf16 v[108:111], v[152:155], v[200:203], v[108:111]
	v_mfma_f32_16x16x32_bf16 v[104:107], v[160:163], v[200:203], v[104:107]
	v_mfma_f32_16x16x32_bf16 v[92:95], v[152:155], v[208:211], v[92:95]
	v_mfma_f32_16x16x32_bf16 v[88:91], v[160:163], v[208:211], v[88:91]
	v_mfma_f32_16x16x32_bf16 v[76:79], v[152:155], v[216:219], v[76:79]
	v_mfma_f32_16x16x32_bf16 v[72:75], v[160:163], v[216:219], v[72:75]
	s_setprio 0
	s_setprio 1
	v_mfma_f32_16x16x32_bf16 v[116:119], v[164:167], v[188:191], v[116:119]
	v_mfma_f32_16x16x32_bf16 v[112:115], v[172:175], v[188:191], v[112:115]
	v_mfma_f32_16x16x32_bf16 v[100:103], v[164:167], v[196:199], v[100:103]
	v_mfma_f32_16x16x32_bf16 v[96:99], v[172:175], v[196:199], v[96:99]
	v_mfma_f32_16x16x32_bf16 v[84:87], v[164:167], v[204:207], v[84:87]
	v_mfma_f32_16x16x32_bf16 v[80:83], v[172:175], v[204:207], v[80:83]
	v_mfma_f32_16x16x32_bf16 v[68:71], v[164:167], v[212:215], v[68:71]
	v_mfma_f32_16x16x32_bf16 v[64:67], v[172:175], v[212:215], v[64:67]
	v_mfma_f32_16x16x32_bf16 v[116:119], v[168:171], v[192:195], v[116:119]
	v_mfma_f32_16x16x32_bf16 v[112:115], v[184:187], v[192:195], v[112:115]
	v_mfma_f32_16x16x32_bf16 v[100:103], v[168:171], v[200:203], v[100:103]
	v_mfma_f32_16x16x32_bf16 v[96:99], v[184:187], v[200:203], v[96:99]
	v_mfma_f32_16x16x32_bf16 v[84:87], v[168:171], v[208:211], v[84:87]
	v_mfma_f32_16x16x32_bf16 v[80:83], v[184:187], v[208:211], v[80:83]
	v_mfma_f32_16x16x32_bf16 v[68:71], v[168:171], v[216:219], v[68:71]
	v_mfma_f32_16x16x32_bf16 v[64:67], v[184:187], v[216:219], v[64:67]
	s_setprio 0
	s_barrier
	s_add_i32 s20, s20, s30
	v_lshl_add_u64 v[142:143], s[54:55], 0, v[176:177]
	s_mov_b32 m0, s20
	ds_read_b128 v[188:191], v151 offset:16384
	ds_read_b128 v[192:195], v151 offset:17408
	ds_read_b128 v[196:199], v151 offset:18432
	ds_read_b128 v[200:203], v151 offset:19456
	ds_read_b128 v[204:207], v151 offset:20480
	ds_read_b128 v[208:211], v151 offset:21504
	ds_read_b128 v[212:215], v151 offset:22528
	ds_read_b128 v[216:219], v151 offset:23552
	global_load_lds_dwordx4 v[142:143], off
	s_add_i32 m0, s20, 0x2000
	s_add_u32 s24, s54, s6
	v_lshl_add_u64 v[146:147], s[54:55], 0, v[128:129]
	s_addc_u32 s25, s55, s7
	s_add_i32 s20, s21, s30
	global_load_lds_dwordx4 v[146:147], off
	v_lshl_add_u64 v[220:221], s[24:25], 0, v[176:177]
	s_mov_b32 m0, s20
	v_lshl_add_u64 v[222:223], s[24:25], 0, v[128:129]
	global_load_lds_dwordx4 v[220:221], off
	s_add_i32 m0, s20, 0x2000
	v_lshl_add_u64 v[224:225], s[38:39], 0, v[132:133]
	global_load_lds_dwordx4 v[222:223], off
	s_mov_b32 m0, s31
	v_lshl_add_u64 v[226:227], s[38:39], 0, v[130:131]
	global_load_lds_dwordx4 v[224:225], off
	s_mov_b32 m0, s40
	s_nop 0
	global_load_lds_dwordx4 v[226:227], off
	s_nop 15
	s_nop 15
	s_nop 15
	s_nop 15
	s_waitcnt vmcnt(8)
	s_waitcnt lgkmcnt(0)
	s_barrier
; #define PG8_STAGE(bufoff, gbase, voff) do { _Pragma("unroll") for (int _i = 0; _i < 2; ++_i) \
;         __builtin_amdgcn_global_load_lds((const unsigned*)((const char*)(gbase) + (voff)[_i]), (LAS unsigned*)(lds + (bufoff) + ldsw + _i * 8192), 16, 0, 0); } while (0)
; #define PG8_LDA(dst, b, h) do { _Pragma("unroll") for (int m = 0; m < 4; ++m) _Pragma("unroll") for (int k = 0; k < 2; ++k) dst[m][k] = *(const LAS bf16x8*)(lds + PG8_SA(b, h) + aoff + m * 2048 + k * 1024); } while (0)
; #define PG8_LDB(dst, b, h) do { _Pragma("unroll") for (int n = 0; n < 2; ++n) _Pragma("unroll") for (int k = 0; k < 2; ++k) dst[n][k] = *(const LAS bf16x8*)(lds + PG8_SB(b, h) + boff + n * 2048 + k * 1024); } while (0)
; #define PG8_MMA(ai, bj, At, Bt) do { __builtin_amdgcn_s_setprio(1); _Pragma("unroll") for (int m = 0; m < 4; ++m) _Pragma("unroll") for (int n = 0; n < 2; ++n) _Pragma("unroll") for (int k = 0; k < 2; ++k) \
;         acc[ai][bj][m][n] = __builtin_amdgcn_mfma_f32_16x16x32_bf16(Bt[n][k], At[m][k], acc[ai][bj][m][n], 0, 0, 0); __builtin_amdgcn_s_setprio(0); } while (0)
; #define PG8_WAIT_V(n) asm volatile("s_waitcnt vmcnt(" #n ")" ::: "memory")
; #define PG8_WAIT_L(n) asm volatile("s_waitcnt lgkmcnt(" #n ")" ::: "memory")
; #define PG8_BAR __builtin_amdgcn_s_barrier()
; #define PG8_SCHED __builtin_amdgcn_sched_barrier(0)
; template <class Epi, bool ALIGN_EPI = PG8_ALIGN>
; __device__ __forceinline__ void gemm_phase(LAS unsigned char* lds, const Gemm g, const StaticOrder& S, const Epi& E) {
;     ...
;             PG8_WAIT_V(8); PG8_WAIT_L(0); PG8_BAR; PG8_MMA(1, 0, At, B0); PG8_MMA(1, 1, At, B1); PG8_BAR; PG8_SCHED;
;             PG8_LDB(B0, 1, 0); PG8_LDB(B1, 1, 1); PG8_SCHED; PG8_LDA(At, 1, 0); PG8_STAGE(PG8_SA(0, 1), a2 + hstepA, voffA);
;             PG8_WAIT_V(8); PG8_WAIT_L(0); PG8_BAR; PG8_MMA(0, 0, At, B0); PG8_MMA(0, 1, At, B1); PG8_BAR; PG8_SCHED;
	s_setprio 1
	s_waitcnt lgkmcnt(0)
	v_mfma_f32_16x16x32_bf16 v[60:63], v[138:141], v[188:191], v[60:63]
	v_mfma_f32_16x16x32_bf16 v[56:59], v[156:159], v[188:191], v[56:59]
	v_mfma_f32_16x16x32_bf16 v[44:47], v[138:141], v[196:199], v[44:47]
	v_mfma_f32_16x16x32_bf16 v[40:43], v[156:159], v[196:199], v[40:43]
	v_mfma_f32_16x16x32_bf16 v[28:31], v[138:141], v[204:207], v[28:31]
	v_mfma_f32_16x16x32_bf16 v[24:27], v[156:159], v[204:207], v[24:27]
	v_mfma_f32_16x16x32_bf16 v[12:15], v[138:141], v[212:215], v[12:15]
	v_mfma_f32_16x16x32_bf16 v[8:11], v[156:159], v[212:215], v[8:11]
	v_mfma_f32_16x16x32_bf16 v[60:63], v[152:155], v[192:195], v[60:63]
	v_mfma_f32_16x16x32_bf16 v[56:59], v[160:163], v[192:195], v[56:59]
	v_mfma_f32_16x16x32_bf16 v[44:47], v[152:155], v[200:203], v[44:47]
	v_mfma_f32_16x16x32_bf16 v[40:43], v[160:163], v[200:203], v[40:43]
	v_mfma_f32_16x16x32_bf16 v[28:31], v[152:155], v[208:211], v[28:31]
	v_mfma_f32_16x16x32_bf16 v[24:27], v[160:163], v[208:211], v[24:27]
	v_mfma_f32_16x16x32_bf16 v[12:15], v[152:155], v[216:219], v[12:15]
	v_mfma_f32_16x16x32_bf16 v[8:11], v[160:163], v[216:219], v[8:11]
	s_setprio 0
	s_setprio 1
	v_mfma_f32_16x16x32_bf16 v[52:55], v[164:167], v[188:191], v[52:55]
	v_mfma_f32_16x16x32_bf16 v[48:51], v[172:175], v[188:191], v[48:51]
	v_mfma_f32_16x16x32_bf16 v[36:39], v[164:167], v[196:199], v[36:39]
	v_mfma_f32_16x16x32_bf16 v[32:35], v[172:175], v[196:199], v[32:35]
	v_mfma_f32_16x16x32_bf16 v[20:23], v[164:167], v[204:207], v[20:23]
	v_mfma_f32_16x16x32_bf16 v[16:19], v[172:175], v[204:207], v[16:19]
	v_mfma_f32_16x16x32_bf16 v[4:7], v[164:167], v[212:215], v[4:7]
	v_mfma_f32_16x16x32_bf16 v[0:3], v[172:175], v[212:215], v[0:3]
	v_mfma_f32_16x16x32_bf16 v[52:55], v[168:171], v[192:195], v[52:55]
	v_mfma_f32_16x16x32_bf16 v[48:51], v[184:187], v[192:195], v[48:51]
	v_mfma_f32_16x16x32_bf16 v[36:39], v[168:171], v[200:203], v[36:39]
	v_mfma_f32_16x16x32_bf16 v[32:35], v[184:187], v[200:203], v[32:35]
	v_mfma_f32_16x16x32_bf16 v[20:23], v[168:171], v[208:211], v[20:23]
	v_mfma_f32_16x16x32_bf16 v[16:19], v[184:187], v[208:211], v[16:19]
	v_mfma_f32_16x16x32_bf16 v[4:7], v[168:171], v[216:219], v[4:7]
	v_mfma_f32_16x16x32_bf16 v[0:3], v[184:187], v[216:219], v[0:3]
	s_setprio 0
	s_barrier
	s_add_i32 s20, 16, 0x18000
	v_add_u32_e32 v144, s20, v149
	s_add_i32 s21, 16, 0x1c000
	ds_read_b128 v[138:141], v144
	ds_read_b128 v[152:155], v144 offset:1024
	ds_read_b128 v[156:159], v144 offset:2048
	ds_read_b128 v[160:163], v144 offset:3072
	v_add_u32_e32 v144, s21, v149
	ds_read_b128 v[164:167], v144
	ds_read_b128 v[168:171], v144 offset:1024
	ds_read_b128 v[172:175], v144 offset:2048
	ds_read_b128 v[184:187], v144 offset:3072
	s_add_u32 s24, s38, 0x110000
	s_addc_u32 s25, s39, 0
	s_mov_b32 m0, s41
	v_lshl_add_u64 v[228:229], s[24:25], 0, v[132:133]
	ds_read_b128 v[188:191], v151 offset:32768
	ds_read_b128 v[192:195], v151 offset:33792
	ds_read_b128 v[196:199], v151 offset:34816
	ds_read_b128 v[200:203], v151 offset:35840
	ds_read_b128 v[204:207], v151 offset:36864
	ds_read_b128 v[208:211], v151 offset:37888
	ds_read_b128 v[212:215], v151 offset:38912
	ds_read_b128 v[216:219], v151 offset:39936
	global_load_lds_dwordx4 v[228:229], off
	v_lshl_add_u64 v[228:229], s[24:25], 0, v[130:131]
	s_mov_b32 m0, s44
	s_nop 0
	global_load_lds_dwordx4 v[228:229], off
	s_waitcnt vmcnt(8)
	s_waitcnt lgkmcnt(0)
	s_barrier
	s_setprio 1
	s_waitcnt lgkmcnt(0)
	v_mfma_f32_16x16x32_bf16 v[120:123], v[138:141], v[188:191], v[120:123]
	v_mfma_f32_16x16x32_bf16 v[124:127], v[156:159], v[188:191], v[124:127]
	v_mfma_f32_16x16x32_bf16 v[108:111], v[138:141], v[196:199], v[108:111]
	v_mfma_f32_16x16x32_bf16 v[104:107], v[156:159], v[196:199], v[104:107]
	v_mfma_f32_16x16x32_bf16 v[92:95], v[138:141], v[204:207], v[92:95]
	v_mfma_f32_16x16x32_bf16 v[88:91], v[156:159], v[204:207], v[88:91]
	v_mfma_f32_16x16x32_bf16 v[76:79], v[138:141], v[212:215], v[76:79]
	v_mfma_f32_16x16x32_bf16 v[72:75], v[156:159], v[212:215], v[72:75]
	v_mfma_f32_16x16x32_bf16 v[120:123], v[152:155], v[192:195], v[120:123]
	v_mfma_f32_16x16x32_bf16 v[124:127], v[160:163], v[192:195], v[124:127]
	v_mfma_f32_16x16x32_bf16 v[108:111], v[152:155], v[200:203], v[108:111]
	v_mfma_f32_16x16x32_bf16 v[104:107], v[160:163], v[200:203], v[104:107]
	v_mfma_f32_16x16x32_bf16 v[92:95], v[152:155], v[208:211], v[92:95]
	v_mfma_f32_16x16x32_bf16 v[88:91], v[160:163], v[208:211], v[88:91]
	v_mfma_f32_16x16x32_bf16 v[76:79], v[152:155], v[216:219], v[76:79]
	v_mfma_f32_16x16x32_bf16 v[72:75], v[160:163], v[216:219], v[72:75]
	s_setprio 0
	s_setprio 1
	v_mfma_f32_16x16x32_bf16 v[116:119], v[164:167], v[188:191], v[116:119]
	v_mfma_f32_16x16x32_bf16 v[112:115], v[172:175], v[188:191], v[112:115]
	v_mfma_f32_16x16x32_bf16 v[100:103], v[164:167], v[196:199], v[100:103]
	v_mfma_f32_16x16x32_bf16 v[96:99], v[172:175], v[196:199], v[96:99]
	v_mfma_f32_16x16x32_bf16 v[84:87], v[164:167], v[204:207], v[84:87]
	v_mfma_f32_16x16x32_bf16 v[80:83], v[172:175], v[204:207], v[80:83]
	v_mfma_f32_16x16x32_bf16 v[68:71], v[164:167], v[212:215], v[68:71]
	v_mfma_f32_16x16x32_bf16 v[64:67], v[172:175], v[212:215], v[64:67]
	v_mfma_f32_16x16x32_bf16 v[116:119], v[168:171], v[192:195], v[116:119]
	v_mfma_f32_16x16x32_bf16 v[112:115], v[184:187], v[192:195], v[112:115]
	v_mfma_f32_16x16x32_bf16 v[100:103], v[168:171], v[200:203], v[100:103]
	v_mfma_f32_16x16x32_bf16 v[96:99], v[184:187], v[200:203], v[96:99]
	v_mfma_f32_16x16x32_bf16 v[84:87], v[168:171], v[208:211], v[84:87]
	v_mfma_f32_16x16x32_bf16 v[80:83], v[184:187], v[208:211], v[80:83]
	v_mfma_f32_16x16x32_bf16 v[68:71], v[168:171], v[216:219], v[68:71]
	v_mfma_f32_16x16x32_bf16 v[64:67], v[184:187], v[216:219], v[64:67]
	s_setprio 0
	s_barrier
; #define PG8_STAGE(bufoff, gbase, voff) do { _Pragma("unroll") for (int _i = 0; _i < 2; ++_i) \
;         __builtin_amdgcn_global_load_lds((const unsigned*)((const char*)(gbase) + (voff)[_i]), (LAS unsigned*)(lds + (bufoff) + ldsw + _i * 8192), 16, 0, 0); } while (0)
; #define PG8_LDA(dst, b, h) do { _Pragma("unroll") for (int m = 0; m < 4; ++m) _Pragma("unroll") for (int k = 0; k < 2; ++k) dst[m][k] = *(const LAS bf16x8*)(lds + PG8_SA(b, h) + aoff + m * 2048 + k * 1024); } while (0)
; #define PG8_MMA(ai, bj, At, Bt) do { __builtin_amdgcn_s_setprio(1); _Pragma("unroll") for (int m = 0; m < 4; ++m) _Pragma("unroll") for (int n = 0; n < 2; ++n) _Pragma("unroll") for (int k = 0; k < 2; ++k) \
;         acc[ai][bj][m][n] = __builtin_amdgcn_mfma_f32_16x16x32_bf16(Bt[n][k], At[m][k], acc[ai][bj][m][n], 0, 0, 0); __builtin_amdgcn_s_setprio(0); } while (0)
; #define PG8_WAIT_V(n) asm volatile("s_waitcnt vmcnt(" #n ")" ::: "memory")
; #define PG8_WAIT_L(n) asm volatile("s_waitcnt lgkmcnt(" #n ")" ::: "memory")
; #define PG8_BAR __builtin_amdgcn_s_barrier()
; #define PG8_SCHED __builtin_amdgcn_sched_barrier(0)
; template <class Epi, bool ALIGN_EPI = PG8_ALIGN>
; __device__ __forceinline__ void gemm_phase(LAS unsigned char* lds, const Gemm g, const StaticOrder& S, const Epi& E) {
;     ...
;             PG8_LDA(At, 1, 1); PG8_STAGE(PG8_SB(1, 0), b3, voffB); PG8_STAGE(PG8_SB(1, 1), b3 + hstepB, voffB); PG8_STAGE(PG8_SA(1, 0), a3, voffA);
;             PG8_WAIT_V(8); PG8_WAIT_L(0); PG8_BAR; PG8_MMA(1, 0, At, B0); PG8_MMA(1, 1, At, B1); PG8_BAR; PG8_SCHED;
;         }
	s_add_i32 s20, s20, s30
	v_lshl_add_u64 v[142:143], v[142:143], 0, s[0:1]
	s_mov_b32 m0, s20
	ds_read_b128 v[188:191], v151 offset:49152
	ds_read_b128 v[192:195], v151 offset:50176
	ds_read_b128 v[196:199], v151 offset:51200
	ds_read_b128 v[200:203], v151 offset:52224
	ds_read_b128 v[204:207], v151 offset:53248
	ds_read_b128 v[208:211], v151 offset:54272
	ds_read_b128 v[212:215], v151 offset:55296
	ds_read_b128 v[216:219], v151 offset:56320
	global_load_lds_dwordx4 v[142:143], off
	v_lshl_add_u64 v[142:143], v[146:147], 0, s[0:1]
	s_add_i32 m0, s20, 0x2000
	s_add_i32 s20, s21, s30
	global_load_lds_dwordx4 v[142:143], off
	v_lshl_add_u64 v[142:143], v[220:221], 0, s[0:1]
	s_mov_b32 m0, s20
	s_nop 0
	global_load_lds_dwordx4 v[142:143], off
	v_lshl_add_u64 v[142:143], v[222:223], 0, s[0:1]
	s_add_i32 m0, s20, 0x2000
	s_nop 0
	global_load_lds_dwordx4 v[142:143], off
	v_lshl_add_u64 v[142:143], v[224:225], 0, s[0:1]
	s_mov_b32 m0, s45
	s_nop 0
	global_load_lds_dwordx4 v[142:143], off
	v_lshl_add_u64 v[142:143], v[226:227], 0, s[0:1]
	s_mov_b32 m0, s46
	s_nop 0
	global_load_lds_dwordx4 v[142:143], off
	s_nop 15
	s_nop 15
	s_nop 15
	s_nop 15
	s_waitcnt vmcnt(8)
	s_waitcnt lgkmcnt(0)
	s_barrier
	s_setprio 1
	s_waitcnt lgkmcnt(0)
	v_mfma_f32_16x16x32_bf16 v[60:63], v[138:141], v[188:191], v[60:63]
	v_mfma_f32_16x16x32_bf16 v[56:59], v[156:159], v[188:191], v[56:59]
	v_mfma_f32_16x16x32_bf16 v[44:47], v[138:141], v[196:199], v[44:47]
	v_mfma_f32_16x16x32_bf16 v[40:43], v[156:159], v[196:199], v[40:43]
	v_mfma_f32_16x16x32_bf16 v[28:31], v[138:141], v[204:207], v[28:31]
	v_mfma_f32_16x16x32_bf16 v[24:27], v[156:159], v[204:207], v[24:27]
	v_mfma_f32_16x16x32_bf16 v[12:15], v[138:141], v[212:215], v[12:15]
	v_mfma_f32_16x16x32_bf16 v[8:11], v[156:159], v[212:215], v[8:11]
	v_mfma_f32_16x16x32_bf16 v[60:63], v[152:155], v[192:195], v[60:63]
	v_mfma_f32_16x16x32_bf16 v[56:59], v[160:163], v[192:195], v[56:59]
	v_mfma_f32_16x16x32_bf16 v[44:47], v[152:155], v[200:203], v[44:47]
	v_mfma_f32_16x16x32_bf16 v[40:43], v[160:163], v[200:203], v[40:43]
	v_mfma_f32_16x16x32_bf16 v[28:31], v[152:155], v[208:211], v[28:31]
	v_mfma_f32_16x16x32_bf16 v[24:27], v[160:163], v[208:211], v[24:27]
	v_mfma_f32_16x16x32_bf16 v[12:15], v[152:155], v[216:219], v[12:15]
	v_mfma_f32_16x16x32_bf16 v[8:11], v[160:163], v[216:219], v[8:11]
	s_setprio 0
	s_setprio 1
	v_mfma_f32_16x16x32_bf16 v[52:55], v[164:167], v[188:191], v[52:55]
	v_mfma_f32_16x16x32_bf16 v[48:51], v[172:175], v[188:191], v[48:51]
	v_mfma_f32_16x16x32_bf16 v[36:39], v[164:167], v[196:199], v[36:39]
	v_mfma_f32_16x16x32_bf16 v[32:35], v[172:175], v[196:199], v[32:35]
	v_mfma_f32_16x16x32_bf16 v[20:23], v[164:167], v[204:207], v[20:23]
	v_mfma_f32_16x16x32_bf16 v[16:19], v[172:175], v[204:207], v[16:19]
	v_mfma_f32_16x16x32_bf16 v[4:7], v[164:167], v[212:215], v[4:7]
	v_mfma_f32_16x16x32_bf16 v[0:3], v[172:175], v[212:215], v[0:3]
	v_mfma_f32_16x16x32_bf16 v[52:55], v[168:171], v[192:195], v[52:55]
	v_mfma_f32_16x16x32_bf16 v[48:51], v[184:187], v[192:195], v[48:51]
	v_mfma_f32_16x16x32_bf16 v[36:39], v[168:171], v[200:203], v[36:39]
	v_mfma_f32_16x16x32_bf16 v[32:35], v[184:187], v[200:203], v[32:35]
	v_mfma_f32_16x16x32_bf16 v[20:23], v[168:171], v[208:211], v[20:23]
	v_mfma_f32_16x16x32_bf16 v[16:19], v[184:187], v[208:211], v[16:19]
	v_mfma_f32_16x16x32_bf16 v[4:7], v[168:171], v[216:219], v[4:7]
	v_mfma_f32_16x16x32_bf16 v[0:3], v[184:187], v[216:219], v[0:3]
	s_setprio 0
	s_barrier
	s_add_u32 s51, s51, 0x100
	s_addc_u32 s52, s52, 0
	s_cmp_ge_i32 s53, s47
	s_mov_b64 s[24:25], s[36:37]
	s_mov_b32 s38, s53
	s_cbranch_scc0 .LBB0_642

; #define PG8_STAGE(bufoff, gbase, voff) do { _Pragma("unroll") for (int _i = 0; _i < 2; ++_i) \
;         __builtin_amdgcn_global_load_lds((const unsigned*)((const char*)(gbase) + (voff)[_i]), (LAS unsigned*)(lds + (bufoff) + ldsw + _i * 8192), 16, 0, 0); } while (0)
; #define PG8_LDA(dst, b, h) do { _Pragma("unroll") for (int m = 0; m < 4; ++m) _Pragma("unroll") for (int k = 0; k < 2; ++k) dst[m][k] = *(const LAS bf16x8*)(lds + PG8_SA(b, h) + aoff + m * 2048 + k * 1024); } while (0)
; #define PG8_LDB(dst, b, h) do { _Pragma("unroll") for (int n = 0; n < 2; ++n) _Pragma("unroll") for (int k = 0; k < 2; ++k) dst[n][k] = *(const LAS bf16x8*)(lds + PG8_SB(b, h) + boff + n * 2048 + k * 1024); } while (0)
; #define PG8_MMA(ai, bj, At, Bt) do { __builtin_amdgcn_s_setprio(1); _Pragma("unroll") for (int m = 0; m < 4; ++m) _Pragma("unroll") for (int n = 0; n < 2; ++n) _Pragma("unroll") for (int k = 0; k < 2; ++k) \
;         acc[ai][bj][m][n] = __builtin_amdgcn_mfma_f32_16x16x32_bf16(Bt[n][k], At[m][k], acc[ai][bj][m][n], 0, 0, 0); __builtin_amdgcn_s_setprio(0); } while (0)
; #define PG8_BAR __builtin_amdgcn_s_barrier()
; template <class Epi, bool ALIGN_EPI = PG8_ALIGN>
; __device__ __forceinline__ void gemm_phase(LAS unsigned char* lds, const Gemm g, const StaticOrder& S, const Epi& E) {
;     ...
;         const bool has_next = S.next(ui + 1, nxt);
;         const char* nA = has_next ? (const char*)g.A + (size_t)nxt.pm * tstepA : cA; const char* nB = has_next ? (const char*)g.Bt + (size_t)nxt.pn * tstepB : cB;
;         for (int t = 0; t < nt; t += 2) {
;             const bool last = (t == nt - 2);
;             const char* a1 = cA + (size_t)(t + 1) * kstep;
;             const char* a2 = last ? nA : cA + (size_t)(t + 2) * kstep; const char* b2 = last ? nB : cB + (size_t)(t + 2) * kstep;
;             const char* a3 = a2 + kstep; const char* b3 = b2 + kstep;
;             PG8_LDB(B0, 0, 0); PG8_LDB(B1, 0, 1); PG8_SCHED; PG8_LDA(At, 0, 0); PG8_STAGE(PG8_SA(1, 1), a1 + hstepA, voffA);
;             PG8_WAIT_V(8); PG8_WAIT_L(0); PG8_BAR; PG8_MMA(0, 0, At, B0); PG8_MMA(0, 1, At, B1); PG8_BAR; PG8_SCHED;
;             PG8_LDA(At, 0, 1); PG8_STAGE(PG8_SB(0, 0), b2, voffB); PG8_STAGE(PG8_SB(0, 1), b2 + hstepB, voffB); PG8_STAGE(PG8_SA(0, 0), a2, voffA);
;             PG8_WAIT_V(8); PG8_WAIT_L(0); PG8_BAR; PG8_MMA(1, 0, At, B0); PG8_MMA(1, 1, At, B1); PG8_BAR; PG8_SCHED;
.LBB0_663:
	s_add_i32 s53, s38, 2
	s_add_u32 s36, s24, 0x100
	s_addc_u32 s37, s25, 0
	s_add_i32 s20, 16, 0x10000
	s_cmp_eq_u32 s48, s38
	s_cselect_b32 s39, s3, s37
	s_cselect_b32 s38, s2, s36
	v_add_u32_e32 v138, s20, v143
	s_cselect_b32 s55, s17, s52
	s_cselect_b32 s54, s16, s34
	s_add_i32 s21, 16, 0x14000
	ds_read_b128 v[152:155], v138
	ds_read_b128 v[156:159], v138 offset:1024
	ds_read_b128 v[160:163], v138 offset:2048
	ds_read_b128 v[164:167], v138 offset:3072
	v_add_u32_e32 v138, s21, v143
	ds_read_b128 v[168:171], v138
	ds_read_b128 v[172:175], v138 offset:1024
	ds_read_b128 v[184:187], v138 offset:2048
	ds_read_b128 v[188:191], v138 offset:3072
	v_lshl_add_u64 v[140:141], s[24:25], 0, v[134:135]
	s_add_i32 m0, s31, 0xc000
	ds_read_b128 v[192:195], v151
	ds_read_b128 v[196:199], v151 offset:1024
	ds_read_b128 v[200:203], v151 offset:2048
	ds_read_b128 v[204:207], v151 offset:3072
	ds_read_b128 v[208:211], v151 offset:4096
	ds_read_b128 v[212:215], v151 offset:5120
	ds_read_b128 v[216:219], v151 offset:6144
	ds_read_b128 v[220:223], v151 offset:7168
	global_load_lds_dwordx4 v[140:141], off
	v_lshl_add_u64 v[140:141], s[24:25], 0, v[136:137]
	s_add_i32 m0, s31, 0xe000
	s_nop 0
	global_load_lds_dwordx4 v[140:141], off
	s_waitcnt vmcnt(8)
	s_waitcnt lgkmcnt(0)
	s_barrier
	s_setprio 1
	s_waitcnt lgkmcnt(0)
	v_mfma_f32_16x16x32_bf16 v[120:123], v[152:155], v[192:195], v[120:123]
	v_mfma_f32_16x16x32_bf16 v[124:127], v[160:163], v[192:195], v[124:127]
	v_mfma_f32_16x16x32_bf16 v[108:111], v[152:155], v[200:203], v[108:111]
	v_mfma_f32_16x16x32_bf16 v[104:107], v[160:163], v[200:203], v[104:107]
	v_mfma_f32_16x16x32_bf16 v[92:95], v[152:155], v[208:211], v[92:95]
	v_mfma_f32_16x16x32_bf16 v[88:91], v[160:163], v[208:211], v[88:91]
	v_mfma_f32_16x16x32_bf16 v[76:79], v[152:155], v[216:219], v[76:79]
	v_mfma_f32_16x16x32_bf16 v[72:75], v[160:163], v[216:219], v[72:75]
	v_mfma_f32_16x16x32_bf16 v[120:123], v[156:159], v[196:199], v[120:123]
	v_mfma_f32_16x16x32_bf16 v[124:127], v[164:167], v[196:199], v[124:127]
	v_mfma_f32_16x16x32_bf16 v[108:111], v[156:159], v[204:207], v[108:111]
	v_mfma_f32_16x16x32_bf16 v[104:107], v[164:167], v[204:207], v[104:107]
	v_mfma_f32_16x16x32_bf16 v[92:95], v[156:159], v[212:215], v[92:95]
	v_mfma_f32_16x16x32_bf16 v[88:91], v[164:167], v[212:215], v[88:91]
	v_mfma_f32_16x16x32_bf16 v[76:79], v[156:159], v[220:223], v[76:79]
	v_mfma_f32_16x16x32_bf16 v[72:75], v[164:167], v[220:223], v[72:75]
	s_setprio 0
	s_setprio 1
	v_mfma_f32_16x16x32_bf16 v[116:119], v[168:171], v[192:195], v[116:119]
	v_mfma_f32_16x16x32_bf16 v[112:115], v[184:187], v[192:195], v[112:115]
	v_mfma_f32_16x16x32_bf16 v[100:103], v[168:171], v[200:203], v[100:103]
	v_mfma_f32_16x16x32_bf16 v[96:99], v[184:187], v[200:203], v[96:99]
	v_mfma_f32_16x16x32_bf16 v[84:87], v[168:171], v[208:211], v[84:87]
	v_mfma_f32_16x16x32_bf16 v[80:83], v[184:187], v[208:211], v[80:83]
	v_mfma_f32_16x16x32_bf16 v[68:71], v[168:171], v[216:219], v[68:71]
	v_mfma_f32_16x16x32_bf16 v[64:67], v[184:187], v[216:219], v[64:67]
	v_mfma_f32_16x16x32_bf16 v[116:119], v[172:175], v[196:199], v[116:119]
	v_mfma_f32_16x16x32_bf16 v[112:115], v[188:191], v[196:199], v[112:115]
	v_mfma_f32_16x16x32_bf16 v[100:103], v[172:175], v[204:207], v[100:103]
	v_mfma_f32_16x16x32_bf16 v[96:99], v[188:191], v[204:207], v[96:99]
	v_mfma_f32_16x16x32_bf16 v[84:87], v[172:175], v[212:215], v[84:87]
	v_mfma_f32_16x16x32_bf16 v[80:83], v[188:191], v[212:215], v[80:83]
	v_mfma_f32_16x16x32_bf16 v[68:71], v[172:175], v[220:223], v[68:71]
	v_mfma_f32_16x16x32_bf16 v[64:67], v[188:191], v[220:223], v[64:67]
	s_setprio 0
	s_barrier
	s_add_i32 s20, s20, s30
	v_lshl_add_u64 v[140:141], s[54:55], 0, v[176:177]
	s_mov_b32 m0, s20
	ds_read_b128 v[192:195], v151 offset:16384
	ds_read_b128 v[196:199], v151 offset:17408
	ds_read_b128 v[200:203], v151 offset:18432
	ds_read_b128 v[204:207], v151 offset:19456
	ds_read_b128 v[208:211], v151 offset:20480
	ds_read_b128 v[212:215], v151 offset:21504
	ds_read_b128 v[216:219], v151 offset:22528
	ds_read_b128 v[220:223], v151 offset:23552
	global_load_lds_dwordx4 v[140:141], off
	s_add_i32 m0, s20, 0x2000
	s_add_u32 s24, s54, s6
	v_lshl_add_u64 v[144:145], s[54:55], 0, v[128:129]
	s_addc_u32 s25, s55, s7
	s_add_i32 s20, s21, s30
	global_load_lds_dwordx4 v[144:145], off
	v_lshl_add_u64 v[148:149], s[24:25], 0, v[176:177]
	s_mov_b32 m0, s20
	v_lshl_add_u64 v[224:225], s[24:25], 0, v[128:129]
	global_load_lds_dwordx4 v[148:149], off
	s_add_i32 m0, s20, 0x2000
	v_lshl_add_u64 v[226:227], s[38:39], 0, v[132:133]
	global_load_lds_dwordx4 v[224:225], off
	s_mov_b32 m0, s31
	v_lshl_add_u64 v[228:229], s[38:39], 0, v[130:131]
	global_load_lds_dwordx4 v[226:227], off
	s_mov_b32 m0, s40
	s_nop 0
	global_load_lds_dwordx4 v[228:229], off
	s_nop 15
	s_nop 15
	s_nop 15
	s_nop 15
	s_waitcnt vmcnt(8)
	s_waitcnt lgkmcnt(0)
	s_barrier
; #define PG8_STAGE(bufoff, gbase, voff) do { _Pragma("unroll") for (int _i = 0; _i < 2; ++_i) \
;         __builtin_amdgcn_global_load_lds((const unsigned*)((const char*)(gbase) + (voff)[_i]), (LAS unsigned*)(lds + (bufoff) + ldsw + _i * 8192), 16, 0, 0); } while (0)
; #define PG8_LDA(dst, b, h) do { _Pragma("unroll") for (int m = 0; m < 4; ++m) _Pragma("unroll") for (int k = 0; k < 2; ++k) dst[m][k] = *(const LAS bf16x8*)(lds + PG8_SA(b, h) + aoff + m * 2048 + k * 1024); } while (0)
; #define PG8_LDB(dst, b, h) do { _Pragma("unroll") for (int n = 0; n < 2; ++n) _Pragma("unroll") for (int k = 0; k < 2; ++k) dst[n][k] = *(const LAS bf16x8*)(lds + PG8_SB(b, h) + boff + n * 2048 + k * 1024); } while (0)
; #define PG8_MMA(ai, bj, At, Bt) do { __builtin_amdgcn_s_setprio(1); _Pragma("unroll") for (int m = 0; m < 4; ++m) _Pragma("unroll") for (int n = 0; n < 2; ++n) _Pragma("unroll") for (int k = 0; k < 2; ++k) \
;         acc[ai][bj][m][n] = __builtin_amdgcn_mfma_f32_16x16x32_bf16(Bt[n][k], At[m][k], acc[ai][bj][m][n], 0, 0, 0); __builtin_amdgcn_s_setprio(0); } while (0)
; #define PG8_WAIT_V(n) asm volatile("s_waitcnt vmcnt(" #n ")" ::: "memory")
; #define PG8_WAIT_L(n) asm volatile("s_waitcnt lgkmcnt(" #n ")" ::: "memory")
; #define PG8_BAR __builtin_amdgcn_s_barrier()
; #define PG8_SCHED __builtin_amdgcn_sched_barrier(0)
; template <class Epi, bool ALIGN_EPI = PG8_ALIGN>
; __device__ __forceinline__ void gemm_phase(LAS unsigned char* lds, const Gemm g, const StaticOrder& S, const Epi& E) {
;     ...
;             PG8_WAIT_V(8); PG8_WAIT_L(0); PG8_BAR; PG8_MMA(1, 0, At, B0); PG8_MMA(1, 1, At, B1); PG8_BAR; PG8_SCHED;
;             PG8_LDB(B0, 1, 0); PG8_LDB(B1, 1, 1); PG8_SCHED; PG8_LDA(At, 1, 0); PG8_STAGE(PG8_SA(0, 1), a2 + hstepA, voffA);
;             PG8_WAIT_V(8); PG8_WAIT_L(0); PG8_BAR; PG8_MMA(0, 0, At, B0); PG8_MMA(0, 1, At, B1); PG8_BAR; PG8_SCHED;
	s_setprio 1
	s_waitcnt lgkmcnt(0)
	v_mfma_f32_16x16x32_bf16 v[60:63], v[152:155], v[192:195], v[60:63]
	v_mfma_f32_16x16x32_bf16 v[56:59], v[160:163], v[192:195], v[56:59]
	v_mfma_f32_16x16x32_bf16 v[44:47], v[152:155], v[200:203], v[44:47]
	v_mfma_f32_16x16x32_bf16 v[40:43], v[160:163], v[200:203], v[40:43]
	v_mfma_f32_16x16x32_bf16 v[28:31], v[152:155], v[208:211], v[28:31]
	v_mfma_f32_16x16x32_bf16 v[24:27], v[160:163], v[208:211], v[24:27]
	v_mfma_f32_16x16x32_bf16 v[12:15], v[152:155], v[216:219], v[12:15]
	v_mfma_f32_16x16x32_bf16 v[8:11], v[160:163], v[216:219], v[8:11]
	v_mfma_f32_16x16x32_bf16 v[60:63], v[156:159], v[196:199], v[60:63]
	v_mfma_f32_16x16x32_bf16 v[56:59], v[164:167], v[196:199], v[56:59]
	v_mfma_f32_16x16x32_bf16 v[44:47], v[156:159], v[204:207], v[44:47]
	v_mfma_f32_16x16x32_bf16 v[40:43], v[164:167], v[204:207], v[40:43]
	v_mfma_f32_16x16x32_bf16 v[28:31], v[156:159], v[212:215], v[28:31]
	v_mfma_f32_16x16x32_bf16 v[24:27], v[164:167], v[212:215], v[24:27]
	v_mfma_f32_16x16x32_bf16 v[12:15], v[156:159], v[220:223], v[12:15]
	v_mfma_f32_16x16x32_bf16 v[8:11], v[164:167], v[220:223], v[8:11]
	s_setprio 0
	s_setprio 1
	v_mfma_f32_16x16x32_bf16 v[52:55], v[168:171], v[192:195], v[52:55]
	v_mfma_f32_16x16x32_bf16 v[48:51], v[184:187], v[192:195], v[48:51]
	v_mfma_f32_16x16x32_bf16 v[36:39], v[168:171], v[200:203], v[36:39]
	v_mfma_f32_16x16x32_bf16 v[32:35], v[184:187], v[200:203], v[32:35]
	v_mfma_f32_16x16x32_bf16 v[20:23], v[168:171], v[208:211], v[20:23]
	v_mfma_f32_16x16x32_bf16 v[16:19], v[184:187], v[208:211], v[16:19]
	v_mfma_f32_16x16x32_bf16 v[4:7], v[168:171], v[216:219], v[4:7]
	v_mfma_f32_16x16x32_bf16 v[0:3], v[184:187], v[216:219], v[0:3]
	v_mfma_f32_16x16x32_bf16 v[52:55], v[172:175], v[196:199], v[52:55]
	v_mfma_f32_16x16x32_bf16 v[48:51], v[188:191], v[196:199], v[48:51]
	v_mfma_f32_16x16x32_bf16 v[36:39], v[172:175], v[204:207], v[36:39]
	v_mfma_f32_16x16x32_bf16 v[32:35], v[188:191], v[204:207], v[32:35]
	v_mfma_f32_16x16x32_bf16 v[20:23], v[172:175], v[212:215], v[20:23]
	v_mfma_f32_16x16x32_bf16 v[16:19], v[188:191], v[212:215], v[16:19]
	v_mfma_f32_16x16x32_bf16 v[4:7], v[172:175], v[220:223], v[4:7]
	v_mfma_f32_16x16x32_bf16 v[0:3], v[188:191], v[220:223], v[0:3]
	s_setprio 0
	s_barrier
	s_add_i32 s20, 16, 0x18000
	v_add_u32_e32 v138, s20, v143
	s_add_i32 s21, 16, 0x1c000
	ds_read_b128 v[152:155], v138
	ds_read_b128 v[156:159], v138 offset:1024
	ds_read_b128 v[160:163], v138 offset:2048
	ds_read_b128 v[164:167], v138 offset:3072
	v_add_u32_e32 v138, s21, v143
	ds_read_b128 v[168:171], v138
	ds_read_b128 v[172:175], v138 offset:1024
	ds_read_b128 v[184:187], v138 offset:2048
	ds_read_b128 v[188:191], v138 offset:3072
	s_add_u32 s24, s38, 0x110000
	s_addc_u32 s25, s39, 0
	s_mov_b32 m0, s41
	v_lshl_add_u64 v[230:231], s[24:25], 0, v[132:133]
	ds_read_b128 v[192:195], v151 offset:32768
	ds_read_b128 v[196:199], v151 offset:33792
	ds_read_b128 v[200:203], v151 offset:34816
	ds_read_b128 v[204:207], v151 offset:35840
	ds_read_b128 v[208:211], v151 offset:36864
	ds_read_b128 v[212:215], v151 offset:37888
	ds_read_b128 v[216:219], v151 offset:38912
	ds_read_b128 v[220:223], v151 offset:39936
	global_load_lds_dwordx4 v[230:231], off
	v_lshl_add_u64 v[230:231], s[24:25], 0, v[130:131]
	s_mov_b32 m0, s44
	s_nop 0
	global_load_lds_dwordx4 v[230:231], off
	s_waitcnt vmcnt(8)
	s_waitcnt lgkmcnt(0)
	s_barrier
	s_setprio 1
	s_waitcnt lgkmcnt(0)
	v_mfma_f32_16x16x32_bf16 v[120:123], v[152:155], v[192:195], v[120:123]
	v_mfma_f32_16x16x32_bf16 v[124:127], v[160:163], v[192:195], v[124:127]
	v_mfma_f32_16x16x32_bf16 v[108:111], v[152:155], v[200:203], v[108:111]
	v_mfma_f32_16x16x32_bf16 v[104:107], v[160:163], v[200:203], v[104:107]
	v_mfma_f32_16x16x32_bf16 v[92:95], v[152:155], v[208:211], v[92:95]
	v_mfma_f32_16x16x32_bf16 v[88:91], v[160:163], v[208:211], v[88:91]
	v_mfma_f32_16x16x32_bf16 v[76:79], v[152:155], v[216:219], v[76:79]
	v_mfma_f32_16x16x32_bf16 v[72:75], v[160:163], v[216:219], v[72:75]
	v_mfma_f32_16x16x32_bf16 v[120:123], v[156:159], v[196:199], v[120:123]
	v_mfma_f32_16x16x32_bf16 v[124:127], v[164:167], v[196:199], v[124:127]
	v_mfma_f32_16x16x32_bf16 v[108:111], v[156:159], v[204:207], v[108:111]
	v_mfma_f32_16x16x32_bf16 v[104:107], v[164:167], v[204:207], v[104:107]
	v_mfma_f32_16x16x32_bf16 v[92:95], v[156:159], v[212:215], v[92:95]
	v_mfma_f32_16x16x32_bf16 v[88:91], v[164:167], v[212:215], v[88:91]
	v_mfma_f32_16x16x32_bf16 v[76:79], v[156:159], v[220:223], v[76:79]
	v_mfma_f32_16x16x32_bf16 v[72:75], v[164:167], v[220:223], v[72:75]
	s_setprio 0
	s_setprio 1
	v_mfma_f32_16x16x32_bf16 v[116:119], v[168:171], v[192:195], v[116:119]
	v_mfma_f32_16x16x32_bf16 v[112:115], v[184:187], v[192:195], v[112:115]
	v_mfma_f32_16x16x32_bf16 v[100:103], v[168:171], v[200:203], v[100:103]
	v_mfma_f32_16x16x32_bf16 v[96:99], v[184:187], v[200:203], v[96:99]
	v_mfma_f32_16x16x32_bf16 v[84:87], v[168:171], v[208:211], v[84:87]
	v_mfma_f32_16x16x32_bf16 v[80:83], v[184:187], v[208:211], v[80:83]
	v_mfma_f32_16x16x32_bf16 v[68:71], v[168:171], v[216:219], v[68:71]
	v_mfma_f32_16x16x32_bf16 v[64:67], v[184:187], v[216:219], v[64:67]
	v_mfma_f32_16x16x32_bf16 v[116:119], v[172:175], v[196:199], v[116:119]
	v_mfma_f32_16x16x32_bf16 v[112:115], v[188:191], v[196:199], v[112:115]
	v_mfma_f32_16x16x32_bf16 v[100:103], v[172:175], v[204:207], v[100:103]
	v_mfma_f32_16x16x32_bf16 v[96:99], v[188:191], v[204:207], v[96:99]
	v_mfma_f32_16x16x32_bf16 v[84:87], v[172:175], v[212:215], v[84:87]
	v_mfma_f32_16x16x32_bf16 v[80:83], v[188:191], v[212:215], v[80:83]
	v_mfma_f32_16x16x32_bf16 v[68:71], v[172:175], v[220:223], v[68:71]
	v_mfma_f32_16x16x32_bf16 v[64:67], v[188:191], v[220:223], v[64:67]
	s_setprio 0
	s_barrier
; #define PG8_STAGE(bufoff, gbase, voff) do { _Pragma("unroll") for (int _i = 0; _i < 2; ++_i) \
;         __builtin_amdgcn_global_load_lds((const unsigned*)((const char*)(gbase) + (voff)[_i]), (LAS unsigned*)(lds + (bufoff) + ldsw + _i * 8192), 16, 0, 0); } while (0)
; #define PG8_LDA(dst, b, h) do { _Pragma("unroll") for (int m = 0; m < 4; ++m) _Pragma("unroll") for (int k = 0; k < 2; ++k) dst[m][k] = *(const LAS bf16x8*)(lds + PG8_SA(b, h) + aoff + m * 2048 + k * 1024); } while (0)
; #define PG8_MMA(ai, bj, At, Bt) do { __builtin_amdgcn_s_setprio(1); _Pragma("unroll") for (int m = 0; m < 4; ++m) _Pragma("unroll") for (int n = 0; n < 2; ++n) _Pragma("unroll") for (int k = 0; k < 2; ++k) \
;         acc[ai][bj][m][n] = __builtin_amdgcn_mfma_f32_16x16x32_bf16(Bt[n][k], At[m][k], acc[ai][bj][m][n], 0, 0, 0); __builtin_amdgcn_s_setprio(0); } while (0)
; #define PG8_WAIT_V(n) asm volatile("s_waitcnt vmcnt(" #n ")" ::: "memory")
; #define PG8_WAIT_L(n) asm volatile("s_waitcnt lgkmcnt(" #n ")" ::: "memory")
; #define PG8_BAR __builtin_amdgcn_s_barrier()
; #define PG8_SCHED __builtin_amdgcn_sched_barrier(0)
; template <class Epi, bool ALIGN_EPI = PG8_ALIGN>
; __device__ __forceinline__ void gemm_phase(LAS unsigned char* lds, const Gemm g, const StaticOrder& S, const Epi& E) {
;     ...
;             PG8_LDA(At, 1, 1); PG8_STAGE(PG8_SB(1, 0), b3, voffB); PG8_STAGE(PG8_SB(1, 1), b3 + hstepB, voffB); PG8_STAGE(PG8_SA(1, 0), a3, voffA);
;             PG8_WAIT_V(8); PG8_WAIT_L(0); PG8_BAR; PG8_MMA(1, 0, At, B0); PG8_MMA(1, 1, At, B1); PG8_BAR; PG8_SCHED;
;         }
	s_add_i32 s20, s20, s30
	v_lshl_add_u64 v[140:141], v[140:141], 0, s[0:1]
	s_mov_b32 m0, s20
	ds_read_b128 v[192:195], v151 offset:49152
	ds_read_b128 v[196:199], v151 offset:50176
	ds_read_b128 v[200:203], v151 offset:51200
	ds_read_b128 v[204:207], v151 offset:52224
	ds_read_b128 v[208:211], v151 offset:53248
	ds_read_b128 v[212:215], v151 offset:54272
	ds_read_b128 v[216:219], v151 offset:55296
	ds_read_b128 v[220:223], v151 offset:56320
	global_load_lds_dwordx4 v[140:141], off
	v_lshl_add_u64 v[140:141], v[144:145], 0, s[0:1]
	s_add_i32 m0, s20, 0x2000
	s_add_i32 s20, s21, s30
	global_load_lds_dwordx4 v[140:141], off
	v_lshl_add_u64 v[140:141], v[148:149], 0, s[0:1]
	s_mov_b32 m0, s20
	s_nop 0
	global_load_lds_dwordx4 v[140:141], off
	v_lshl_add_u64 v[140:141], v[224:225], 0, s[0:1]
	s_add_i32 m0, s20, 0x2000
	s_nop 0
	global_load_lds_dwordx4 v[140:141], off
	v_lshl_add_u64 v[140:141], v[226:227], 0, s[0:1]
	s_mov_b32 m0, s45
	s_nop 0
	global_load_lds_dwordx4 v[140:141], off
	v_lshl_add_u64 v[140:141], v[228:229], 0, s[0:1]
	s_mov_b32 m0, s46
	s_nop 0
	global_load_lds_dwordx4 v[140:141], off
	s_nop 15
	s_nop 15
	s_nop 15
	s_nop 15
	s_waitcnt vmcnt(8)
	s_waitcnt lgkmcnt(0)
	s_barrier
	s_setprio 1
	s_waitcnt lgkmcnt(0)
	v_mfma_f32_16x16x32_bf16 v[60:63], v[152:155], v[192:195], v[60:63]
	v_mfma_f32_16x16x32_bf16 v[56:59], v[160:163], v[192:195], v[56:59]
	v_mfma_f32_16x16x32_bf16 v[44:47], v[152:155], v[200:203], v[44:47]
	v_mfma_f32_16x16x32_bf16 v[40:43], v[160:163], v[200:203], v[40:43]
	v_mfma_f32_16x16x32_bf16 v[28:31], v[152:155], v[208:211], v[28:31]
	v_mfma_f32_16x16x32_bf16 v[24:27], v[160:163], v[208:211], v[24:27]
	v_mfma_f32_16x16x32_bf16 v[12:15], v[152:155], v[216:219], v[12:15]
	v_mfma_f32_16x16x32_bf16 v[8:11], v[160:163], v[216:219], v[8:11]
	v_mfma_f32_16x16x32_bf16 v[60:63], v[156:159], v[196:199], v[60:63]
	v_mfma_f32_16x16x32_bf16 v[56:59], v[164:167], v[196:199], v[56:59]
	v_mfma_f32_16x16x32_bf16 v[44:47], v[156:159], v[204:207], v[44:47]
	v_mfma_f32_16x16x32_bf16 v[40:43], v[164:167], v[204:207], v[40:43]
	v_mfma_f32_16x16x32_bf16 v[28:31], v[156:159], v[212:215], v[28:31]
	v_mfma_f32_16x16x32_bf16 v[24:27], v[164:167], v[212:215], v[24:27]
	v_mfma_f32_16x16x32_bf16 v[12:15], v[156:159], v[220:223], v[12:15]
	v_mfma_f32_16x16x32_bf16 v[8:11], v[164:167], v[220:223], v[8:11]
	s_setprio 0
	s_setprio 1
	v_mfma_f32_16x16x32_bf16 v[52:55], v[168:171], v[192:195], v[52:55]
	v_mfma_f32_16x16x32_bf16 v[48:51], v[184:187], v[192:195], v[48:51]
	v_mfma_f32_16x16x32_bf16 v[36:39], v[168:171], v[200:203], v[36:39]
	v_mfma_f32_16x16x32_bf16 v[32:35], v[184:187], v[200:203], v[32:35]
	v_mfma_f32_16x16x32_bf16 v[20:23], v[168:171], v[208:211], v[20:23]
	v_mfma_f32_16x16x32_bf16 v[16:19], v[184:187], v[208:211], v[16:19]
	v_mfma_f32_16x16x32_bf16 v[4:7], v[168:171], v[216:219], v[4:7]
	v_mfma_f32_16x16x32_bf16 v[0:3], v[184:187], v[216:219], v[0:3]
	v_mfma_f32_16x16x32_bf16 v[52:55], v[172:175], v[196:199], v[52:55]
	v_mfma_f32_16x16x32_bf16 v[48:51], v[188:191], v[196:199], v[48:51]
	v_mfma_f32_16x16x32_bf16 v[36:39], v[172:175], v[204:207], v[36:39]
	v_mfma_f32_16x16x32_bf16 v[32:35], v[188:191], v[204:207], v[32:35]
	v_mfma_f32_16x16x32_bf16 v[20:23], v[172:175], v[212:215], v[20:23]
	v_mfma_f32_16x16x32_bf16 v[16:19], v[188:191], v[212:215], v[16:19]
	v_mfma_f32_16x16x32_bf16 v[4:7], v[172:175], v[220:223], v[4:7]
	v_mfma_f32_16x16x32_bf16 v[0:3], v[188:191], v[220:223], v[0:3]
	s_setprio 0
	s_barrier
	s_add_u32 s34, s34, 0x100
	s_addc_u32 s52, s52, 0
	s_cmp_ge_i32 s53, s47
	s_mov_b64 s[24:25], s[36:37]
	s_mov_b32 s38, s53
	s_cbranch_scc0 .LBB0_663

; #define PG8_STAGE(bufoff, gbase, voff) do { _Pragma("unroll") for (int _i = 0; _i < 2; ++_i) \
;         __builtin_amdgcn_global_load_lds((const unsigned*)((const char*)(gbase) + (voff)[_i]), (LAS unsigned*)(lds + (bufoff) + ldsw + _i * 8192), 16, 0, 0); } while (0)
; #define PG8_LDA(dst, b, h) do { _Pragma("unroll") for (int m = 0; m < 4; ++m) _Pragma("unroll") for (int k = 0; k < 2; ++k) dst[m][k] = *(const LAS bf16x8*)(lds + PG8_SA(b, h) + aoff + m * 2048 + k * 1024); } while (0)
; #define PG8_LDB(dst, b, h) do { _Pragma("unroll") for (int n = 0; n < 2; ++n) _Pragma("unroll") for (int k = 0; k < 2; ++k) dst[n][k] = *(const LAS bf16x8*)(lds + PG8_SB(b, h) + boff + n * 2048 + k * 1024); } while (0)
; #define PG8_MMA(ai, bj, At, Bt) do { __builtin_amdgcn_s_setprio(1); _Pragma("unroll") for (int m = 0; m < 4; ++m) _Pragma("unroll") for (int n = 0; n < 2; ++n) _Pragma("unroll") for (int k = 0; k < 2; ++k) \
;         acc[ai][bj][m][n] = __builtin_amdgcn_mfma_f32_16x16x32_bf16(Bt[n][k], At[m][k], acc[ai][bj][m][n], 0, 0, 0); __builtin_amdgcn_s_setprio(0); } while (0)
; #define PG8_BAR __builtin_amdgcn_s_barrier()
; template <class Epi, bool ALIGN_EPI = PG8_ALIGN>
; __device__ __forceinline__ void gemm_phase(LAS unsigned char* lds, const Gemm g, const StaticOrder& S, const Epi& E) {
;     ...
;         const bool has_next = S.next(ui + 1, nxt);
;         const char* nA = has_next ? (const char*)g.A + (size_t)nxt.pm * tstepA : cA; const char* nB = has_next ? (const char*)g.Bt + (size_t)nxt.pn * tstepB : cB;
;         for (int t = 0; t < nt; t += 2) {
;             const bool last = (t == nt - 2);
;             const char* a1 = cA + (size_t)(t + 1) * kstep;
;             const char* a2 = last ? nA : cA + (size_t)(t + 2) * kstep; const char* b2 = last ? nB : cB + (size_t)(t + 2) * kstep;
;             const char* a3 = a2 + kstep; const char* b3 = b2 + kstep;
;             PG8_LDB(B0, 0, 0); PG8_LDB(B1, 0, 1); PG8_SCHED; PG8_LDA(At, 0, 0); PG8_STAGE(PG8_SA(1, 1), a1 + hstepA, voffA);
;             PG8_WAIT_V(8); PG8_WAIT_L(0); PG8_BAR; PG8_MMA(0, 0, At, B0); PG8_MMA(0, 1, At, B1); PG8_BAR; PG8_SCHED;
;             PG8_LDA(At, 0, 1); PG8_STAGE(PG8_SB(0, 0), b2, voffB); PG8_STAGE(PG8_SB(0, 1), b2 + hstepB, voffB); PG8_STAGE(PG8_SA(0, 0), a2, voffA);
;             PG8_WAIT_V(8); PG8_WAIT_L(0); PG8_BAR; PG8_MMA(1, 0, At, B0); PG8_MMA(1, 1, At, B1); PG8_BAR; PG8_SCHED;
.LBB0_901:
	s_add_i32 s53, s40, 2
	s_add_u32 s20, s4, 0xfff80080
	s_addc_u32 s21, s5, -1
	s_add_i32 s22, 16, 0x10000
	s_cmp_eq_u32 s47, s40
	s_cselect_b32 s41, s25, s21
	s_cselect_b32 s40, s52, s20
	s_cselect_b32 s21, s37, s43
	s_cselect_b32 s20, s36, s42
	s_add_i32 s23, 16, 0x14000
	v_add_u32_e32 v154, s22, v139
	v_add_u32_e32 v170, s23, v139
	ds_read_b128 v[142:145], v154
	ds_read_b128 v[146:149], v154 offset:1024
	ds_read_b128 v[150:153], v154 offset:2048
	ds_read_b128 v[154:157], v154 offset:3072
	ds_read_b128 v[158:161], v170
	ds_read_b128 v[162:165], v170 offset:1024
	ds_read_b128 v[166:169], v170 offset:2048
	ds_read_b128 v[170:173], v170 offset:3072
	v_lshl_add_u64 v[174:175], s[4:5], 0, v[134:135]
	s_add_i32 m0, s29, 0xc000
	ds_read_b128 v[184:187], v141
	ds_read_b128 v[188:191], v141 offset:1024
	ds_read_b128 v[192:195], v141 offset:2048
	ds_read_b128 v[196:199], v141 offset:3072
	ds_read_b128 v[200:203], v141 offset:4096
	ds_read_b128 v[204:207], v141 offset:5120
	ds_read_b128 v[208:211], v141 offset:6144
	ds_read_b128 v[212:215], v141 offset:7168
	global_load_lds_dwordx4 v[174:175], off
	v_lshl_add_u64 v[174:175], s[4:5], 0, v[136:137]
	s_add_i32 m0, s29, 0xe000
	s_nop 0
	global_load_lds_dwordx4 v[174:175], off
	s_waitcnt vmcnt(8)
	s_waitcnt lgkmcnt(0)
	s_barrier
	s_setprio 1
	s_waitcnt lgkmcnt(0)
	v_mfma_f32_16x16x32_bf16 v[120:123], v[142:145], v[184:187], v[120:123]
	v_mfma_f32_16x16x32_bf16 v[124:127], v[150:153], v[184:187], v[124:127]
	v_mfma_f32_16x16x32_bf16 v[108:111], v[142:145], v[192:195], v[108:111]
	v_mfma_f32_16x16x32_bf16 v[104:107], v[150:153], v[192:195], v[104:107]
	v_mfma_f32_16x16x32_bf16 v[92:95], v[142:145], v[200:203], v[92:95]
	v_mfma_f32_16x16x32_bf16 v[88:91], v[150:153], v[200:203], v[88:91]
	v_mfma_f32_16x16x32_bf16 v[76:79], v[142:145], v[208:211], v[76:79]
	v_mfma_f32_16x16x32_bf16 v[72:75], v[150:153], v[208:211], v[72:75]
	v_mfma_f32_16x16x32_bf16 v[120:123], v[146:149], v[188:191], v[120:123]
	v_mfma_f32_16x16x32_bf16 v[124:127], v[154:157], v[188:191], v[124:127]
	v_mfma_f32_16x16x32_bf16 v[108:111], v[146:149], v[196:199], v[108:111]
	v_mfma_f32_16x16x32_bf16 v[104:107], v[154:157], v[196:199], v[104:107]
	v_mfma_f32_16x16x32_bf16 v[92:95], v[146:149], v[204:207], v[92:95]
	v_mfma_f32_16x16x32_bf16 v[88:91], v[154:157], v[204:207], v[88:91]
	v_mfma_f32_16x16x32_bf16 v[76:79], v[146:149], v[212:215], v[76:79]
	v_mfma_f32_16x16x32_bf16 v[72:75], v[154:157], v[212:215], v[72:75]
	s_setprio 0
	s_setprio 1
	v_mfma_f32_16x16x32_bf16 v[116:119], v[158:161], v[184:187], v[116:119]
	v_mfma_f32_16x16x32_bf16 v[112:115], v[166:169], v[184:187], v[112:115]
	v_mfma_f32_16x16x32_bf16 v[100:103], v[158:161], v[192:195], v[100:103]
	v_mfma_f32_16x16x32_bf16 v[96:99], v[166:169], v[192:195], v[96:99]
	v_mfma_f32_16x16x32_bf16 v[84:87], v[158:161], v[200:203], v[84:87]
	v_mfma_f32_16x16x32_bf16 v[80:83], v[166:169], v[200:203], v[80:83]
	v_mfma_f32_16x16x32_bf16 v[68:71], v[158:161], v[208:211], v[68:71]
	v_mfma_f32_16x16x32_bf16 v[64:67], v[166:169], v[208:211], v[64:67]
	v_mfma_f32_16x16x32_bf16 v[116:119], v[162:165], v[188:191], v[116:119]
	v_mfma_f32_16x16x32_bf16 v[112:115], v[170:173], v[188:191], v[112:115]
	v_mfma_f32_16x16x32_bf16 v[100:103], v[162:165], v[196:199], v[100:103]
	v_mfma_f32_16x16x32_bf16 v[96:99], v[170:173], v[196:199], v[96:99]
	v_mfma_f32_16x16x32_bf16 v[84:87], v[162:165], v[204:207], v[84:87]
	v_mfma_f32_16x16x32_bf16 v[80:83], v[170:173], v[204:207], v[80:83]
	v_mfma_f32_16x16x32_bf16 v[68:71], v[162:165], v[212:215], v[68:71]
	v_mfma_f32_16x16x32_bf16 v[64:67], v[170:173], v[212:215], v[64:67]
	s_setprio 0
	s_barrier
	s_add_i32 s22, s22, s18
	v_lshl_add_u64 v[174:175], s[20:21], 0, v[176:177]
	s_mov_b32 m0, s22
	ds_read_b128 v[184:187], v141 offset:16384
	ds_read_b128 v[188:191], v141 offset:17408
	ds_read_b128 v[192:195], v141 offset:18432
	ds_read_b128 v[196:199], v141 offset:19456
	ds_read_b128 v[200:203], v141 offset:20480
	ds_read_b128 v[204:207], v141 offset:21504
	ds_read_b128 v[208:211], v141 offset:22528
	ds_read_b128 v[212:215], v141 offset:23552
	global_load_lds_dwordx4 v[174:175], off
	s_add_i32 m0, s22, 0x2000
	v_lshl_add_u64 v[180:181], s[20:21], 0, v[128:129]
	s_add_u32 s20, s20, s8
	s_addc_u32 s21, s21, s9
	s_add_i32 s22, s23, s18
	global_load_lds_dwordx4 v[180:181], off
	v_lshl_add_u64 v[182:183], s[20:21], 0, v[176:177]
	s_mov_b32 m0, s22
	v_lshl_add_u64 v[216:217], s[20:21], 0, v[128:129]
	global_load_lds_dwordx4 v[182:183], off
	s_add_i32 m0, s22, 0x2000
	v_lshl_add_u64 v[218:219], s[40:41], 0, v[132:133]
	global_load_lds_dwordx4 v[216:217], off
	s_mov_b32 m0, s29
	v_lshl_add_u64 v[220:221], s[40:41], 0, v[130:131]
	global_load_lds_dwordx4 v[218:219], off
	s_mov_b32 m0, s30
	s_nop 0
	global_load_lds_dwordx4 v[220:221], off
	s_nop 15
	s_nop 15
	s_nop 15
	s_nop 15
	s_waitcnt vmcnt(8)
	s_waitcnt lgkmcnt(0)
	s_barrier
; #define PG8_STAGE(bufoff, gbase, voff) do { _Pragma("unroll") for (int _i = 0; _i < 2; ++_i) \
;         __builtin_amdgcn_global_load_lds((const unsigned*)((const char*)(gbase) + (voff)[_i]), (LAS unsigned*)(lds + (bufoff) + ldsw + _i * 8192), 16, 0, 0); } while (0)
; #define PG8_LDA(dst, b, h) do { _Pragma("unroll") for (int m = 0; m < 4; ++m) _Pragma("unroll") for (int k = 0; k < 2; ++k) dst[m][k] = *(const LAS bf16x8*)(lds + PG8_SA(b, h) + aoff + m * 2048 + k * 1024); } while (0)
; #define PG8_LDB(dst, b, h) do { _Pragma("unroll") for (int n = 0; n < 2; ++n) _Pragma("unroll") for (int k = 0; k < 2; ++k) dst[n][k] = *(const LAS bf16x8*)(lds + PG8_SB(b, h) + boff + n * 2048 + k * 1024); } while (0)
; #define PG8_MMA(ai, bj, At, Bt) do { __builtin_amdgcn_s_setprio(1); _Pragma("unroll") for (int m = 0; m < 4; ++m) _Pragma("unroll") for (int n = 0; n < 2; ++n) _Pragma("unroll") for (int k = 0; k < 2; ++k) \
;         acc[ai][bj][m][n] = __builtin_amdgcn_mfma_f32_16x16x32_bf16(Bt[n][k], At[m][k], acc[ai][bj][m][n], 0, 0, 0); __builtin_amdgcn_s_setprio(0); } while (0)
; #define PG8_WAIT_V(n) asm volatile("s_waitcnt vmcnt(" #n ")" ::: "memory")
; #define PG8_WAIT_L(n) asm volatile("s_waitcnt lgkmcnt(" #n ")" ::: "memory")
; #define PG8_BAR __builtin_amdgcn_s_barrier()
; #define PG8_SCHED __builtin_amdgcn_sched_barrier(0)
; template <class Epi, bool ALIGN_EPI = PG8_ALIGN>
; __device__ __forceinline__ void gemm_phase(LAS unsigned char* lds, const Gemm g, const StaticOrder& S, const Epi& E) {
;     ...
;             PG8_WAIT_V(8); PG8_WAIT_L(0); PG8_BAR; PG8_MMA(1, 0, At, B0); PG8_MMA(1, 1, At, B1); PG8_BAR; PG8_SCHED;
;             PG8_LDB(B0, 1, 0); PG8_LDB(B1, 1, 1); PG8_SCHED; PG8_LDA(At, 1, 0); PG8_STAGE(PG8_SA(0, 1), a2 + hstepA, voffA);
;             PG8_WAIT_V(8); PG8_WAIT_L(0); PG8_BAR; PG8_MMA(0, 0, At, B0); PG8_MMA(0, 1, At, B1); PG8_BAR; PG8_SCHED;
	s_setprio 1
	s_waitcnt lgkmcnt(0)
	v_mfma_f32_16x16x32_bf16 v[60:63], v[142:145], v[184:187], v[60:63]
	v_mfma_f32_16x16x32_bf16 v[56:59], v[150:153], v[184:187], v[56:59]
	v_mfma_f32_16x16x32_bf16 v[44:47], v[142:145], v[192:195], v[44:47]
	v_mfma_f32_16x16x32_bf16 v[40:43], v[150:153], v[192:195], v[40:43]
	v_mfma_f32_16x16x32_bf16 v[28:31], v[142:145], v[200:203], v[28:31]
	v_mfma_f32_16x16x32_bf16 v[24:27], v[150:153], v[200:203], v[24:27]
	v_mfma_f32_16x16x32_bf16 v[12:15], v[142:145], v[208:211], v[12:15]
	v_mfma_f32_16x16x32_bf16 v[8:11], v[150:153], v[208:211], v[8:11]
	v_mfma_f32_16x16x32_bf16 v[60:63], v[146:149], v[188:191], v[60:63]
	v_mfma_f32_16x16x32_bf16 v[56:59], v[154:157], v[188:191], v[56:59]
	v_mfma_f32_16x16x32_bf16 v[44:47], v[146:149], v[196:199], v[44:47]
	v_mfma_f32_16x16x32_bf16 v[40:43], v[154:157], v[196:199], v[40:43]
	v_mfma_f32_16x16x32_bf16 v[28:31], v[146:149], v[204:207], v[28:31]
	v_mfma_f32_16x16x32_bf16 v[24:27], v[154:157], v[204:207], v[24:27]
	v_mfma_f32_16x16x32_bf16 v[12:15], v[146:149], v[212:215], v[12:15]
	v_mfma_f32_16x16x32_bf16 v[8:11], v[154:157], v[212:215], v[8:11]
	s_setprio 0
	s_setprio 1
	v_mfma_f32_16x16x32_bf16 v[52:55], v[158:161], v[184:187], v[52:55]
	v_mfma_f32_16x16x32_bf16 v[48:51], v[166:169], v[184:187], v[48:51]
	v_mfma_f32_16x16x32_bf16 v[36:39], v[158:161], v[192:195], v[36:39]
	v_mfma_f32_16x16x32_bf16 v[32:35], v[166:169], v[192:195], v[32:35]
	v_mfma_f32_16x16x32_bf16 v[20:23], v[158:161], v[200:203], v[20:23]
	v_mfma_f32_16x16x32_bf16 v[16:19], v[166:169], v[200:203], v[16:19]
	v_mfma_f32_16x16x32_bf16 v[4:7], v[158:161], v[208:211], v[4:7]
	v_mfma_f32_16x16x32_bf16 v[0:3], v[166:169], v[208:211], v[0:3]
	v_mfma_f32_16x16x32_bf16 v[52:55], v[162:165], v[188:191], v[52:55]
	v_mfma_f32_16x16x32_bf16 v[48:51], v[170:173], v[188:191], v[48:51]
	v_mfma_f32_16x16x32_bf16 v[36:39], v[162:165], v[196:199], v[36:39]
	v_mfma_f32_16x16x32_bf16 v[32:35], v[170:173], v[196:199], v[32:35]
	v_mfma_f32_16x16x32_bf16 v[20:23], v[162:165], v[204:207], v[20:23]
	v_mfma_f32_16x16x32_bf16 v[16:19], v[170:173], v[204:207], v[16:19]
	v_mfma_f32_16x16x32_bf16 v[4:7], v[162:165], v[212:215], v[4:7]
	v_mfma_f32_16x16x32_bf16 v[0:3], v[170:173], v[212:215], v[0:3]
	s_setprio 0
	s_barrier
	s_add_i32 s22, 16, 0x18000
	s_add_i32 s23, 16, 0x1c000
	v_add_u32_e32 v154, s22, v139
	v_add_u32_e32 v170, s23, v139
	ds_read_b128 v[142:145], v154
	ds_read_b128 v[146:149], v154 offset:1024
	ds_read_b128 v[150:153], v154 offset:2048
	ds_read_b128 v[154:157], v154 offset:3072
	ds_read_b128 v[158:161], v170
	ds_read_b128 v[162:165], v170 offset:1024
	ds_read_b128 v[166:169], v170 offset:2048
	ds_read_b128 v[170:173], v170 offset:3072
	s_add_u32 s20, s40, 0x80000
	s_addc_u32 s21, s41, 0
	s_mov_b32 m0, s31
	v_lshl_add_u64 v[222:223], s[20:21], 0, v[132:133]
	ds_read_b128 v[184:187], v141 offset:32768
	ds_read_b128 v[188:191], v141 offset:33792
	ds_read_b128 v[192:195], v141 offset:34816
	ds_read_b128 v[196:199], v141 offset:35840
	ds_read_b128 v[200:203], v141 offset:36864
	ds_read_b128 v[204:207], v141 offset:37888
	ds_read_b128 v[208:211], v141 offset:38912
	ds_read_b128 v[212:215], v141 offset:39936
	global_load_lds_dwordx4 v[222:223], off
	v_lshl_add_u64 v[222:223], s[20:21], 0, v[130:131]
	s_mov_b32 m0, s44
	s_nop 0
	global_load_lds_dwordx4 v[222:223], off
	s_waitcnt vmcnt(8)
	s_waitcnt lgkmcnt(0)
	s_barrier
	s_setprio 1
	s_waitcnt lgkmcnt(0)
	v_mfma_f32_16x16x32_bf16 v[120:123], v[142:145], v[184:187], v[120:123]
	v_mfma_f32_16x16x32_bf16 v[124:127], v[150:153], v[184:187], v[124:127]
	v_mfma_f32_16x16x32_bf16 v[108:111], v[142:145], v[192:195], v[108:111]
	v_mfma_f32_16x16x32_bf16 v[104:107], v[150:153], v[192:195], v[104:107]
	v_mfma_f32_16x16x32_bf16 v[92:95], v[142:145], v[200:203], v[92:95]
	v_mfma_f32_16x16x32_bf16 v[88:91], v[150:153], v[200:203], v[88:91]
	v_mfma_f32_16x16x32_bf16 v[76:79], v[142:145], v[208:211], v[76:79]
	v_mfma_f32_16x16x32_bf16 v[72:75], v[150:153], v[208:211], v[72:75]
	v_mfma_f32_16x16x32_bf16 v[120:123], v[146:149], v[188:191], v[120:123]
	v_mfma_f32_16x16x32_bf16 v[124:127], v[154:157], v[188:191], v[124:127]
	v_mfma_f32_16x16x32_bf16 v[108:111], v[146:149], v[196:199], v[108:111]
	v_mfma_f32_16x16x32_bf16 v[104:107], v[154:157], v[196:199], v[104:107]
	v_mfma_f32_16x16x32_bf16 v[92:95], v[146:149], v[204:207], v[92:95]
	v_mfma_f32_16x16x32_bf16 v[88:91], v[154:157], v[204:207], v[88:91]
	v_mfma_f32_16x16x32_bf16 v[76:79], v[146:149], v[212:215], v[76:79]
	v_mfma_f32_16x16x32_bf16 v[72:75], v[154:157], v[212:215], v[72:75]
	s_setprio 0
	s_setprio 1
	v_mfma_f32_16x16x32_bf16 v[116:119], v[158:161], v[184:187], v[116:119]
	v_mfma_f32_16x16x32_bf16 v[112:115], v[166:169], v[184:187], v[112:115]
	v_mfma_f32_16x16x32_bf16 v[100:103], v[158:161], v[192:195], v[100:103]
	v_mfma_f32_16x16x32_bf16 v[96:99], v[166:169], v[192:195], v[96:99]
	v_mfma_f32_16x16x32_bf16 v[84:87], v[158:161], v[200:203], v[84:87]
	v_mfma_f32_16x16x32_bf16 v[80:83], v[166:169], v[200:203], v[80:83]
	v_mfma_f32_16x16x32_bf16 v[68:71], v[158:161], v[208:211], v[68:71]
	v_mfma_f32_16x16x32_bf16 v[64:67], v[166:169], v[208:211], v[64:67]
	v_mfma_f32_16x16x32_bf16 v[116:119], v[162:165], v[188:191], v[116:119]
	v_mfma_f32_16x16x32_bf16 v[112:115], v[170:173], v[188:191], v[112:115]
	v_mfma_f32_16x16x32_bf16 v[100:103], v[162:165], v[196:199], v[100:103]
	v_mfma_f32_16x16x32_bf16 v[96:99], v[170:173], v[196:199], v[96:99]
	v_mfma_f32_16x16x32_bf16 v[84:87], v[162:165], v[204:207], v[84:87]
	v_mfma_f32_16x16x32_bf16 v[80:83], v[170:173], v[204:207], v[80:83]
	v_mfma_f32_16x16x32_bf16 v[68:71], v[162:165], v[212:215], v[68:71]
	v_mfma_f32_16x16x32_bf16 v[64:67], v[170:173], v[212:215], v[64:67]
	s_setprio 0
	s_barrier
; #define PG8_STAGE(bufoff, gbase, voff) do { _Pragma("unroll") for (int _i = 0; _i < 2; ++_i) \
;         __builtin_amdgcn_global_load_lds((const unsigned*)((const char*)(gbase) + (voff)[_i]), (LAS unsigned*)(lds + (bufoff) + ldsw + _i * 8192), 16, 0, 0); } while (0)
; #define PG8_LDA(dst, b, h) do { _Pragma("unroll") for (int m = 0; m < 4; ++m) _Pragma("unroll") for (int k = 0; k < 2; ++k) dst[m][k] = *(const LAS bf16x8*)(lds + PG8_SA(b, h) + aoff + m * 2048 + k * 1024); } while (0)
; #define PG8_MMA(ai, bj, At, Bt) do { __builtin_amdgcn_s_setprio(1); _Pragma("unroll") for (int m = 0; m < 4; ++m) _Pragma("unroll") for (int n = 0; n < 2; ++n) _Pragma("unroll") for (int k = 0; k < 2; ++k) \
;         acc[ai][bj][m][n] = __builtin_amdgcn_mfma_f32_16x16x32_bf16(Bt[n][k], At[m][k], acc[ai][bj][m][n], 0, 0, 0); __builtin_amdgcn_s_setprio(0); } while (0)
; #define PG8_WAIT_V(n) asm volatile("s_waitcnt vmcnt(" #n ")" ::: "memory")
; #define PG8_WAIT_L(n) asm volatile("s_waitcnt lgkmcnt(" #n ")" ::: "memory")
; #define PG8_BAR __builtin_amdgcn_s_barrier()
; #define PG8_SCHED __builtin_amdgcn_sched_barrier(0)
; template <class Epi, bool ALIGN_EPI = PG8_ALIGN>
; __device__ __forceinline__ void gemm_phase(LAS unsigned char* lds, const Gemm g, const StaticOrder& S, const Epi& E) {
;     ...
;             PG8_LDA(At, 1, 1); PG8_STAGE(PG8_SB(1, 0), b3, voffB); PG8_STAGE(PG8_SB(1, 1), b3 + hstepB, voffB); PG8_STAGE(PG8_SA(1, 0), a3, voffA);
;             PG8_WAIT_V(8); PG8_WAIT_L(0); PG8_BAR; PG8_MMA(1, 0, At, B0); PG8_MMA(1, 1, At, B1); PG8_BAR; PG8_SCHED;
;         }
	s_add_i32 s20, s22, s18
	v_lshl_add_u64 v[174:175], v[174:175], 0, s[0:1]
	s_mov_b32 m0, s20
	ds_read_b128 v[184:187], v141 offset:49152
	ds_read_b128 v[188:191], v141 offset:50176
	ds_read_b128 v[192:195], v141 offset:51200
	ds_read_b128 v[196:199], v141 offset:52224
	ds_read_b128 v[200:203], v141 offset:53248
	ds_read_b128 v[204:207], v141 offset:54272
	ds_read_b128 v[208:211], v141 offset:55296
	ds_read_b128 v[212:215], v141 offset:56320
	global_load_lds_dwordx4 v[174:175], off
	v_lshl_add_u64 v[174:175], v[180:181], 0, s[0:1]
	s_add_i32 m0, s20, 0x2000
	s_add_i32 s20, s23, s18
	global_load_lds_dwordx4 v[174:175], off
	v_lshl_add_u64 v[174:175], v[182:183], 0, s[0:1]
	s_mov_b32 m0, s20
	s_nop 0
	global_load_lds_dwordx4 v[174:175], off
	v_lshl_add_u64 v[174:175], v[216:217], 0, s[0:1]
	s_add_i32 m0, s20, 0x2000
	s_nop 0
	global_load_lds_dwordx4 v[174:175], off
	v_lshl_add_u64 v[174:175], v[218:219], 0, s[0:1]
	s_mov_b32 m0, s45
	s_nop 0
	global_load_lds_dwordx4 v[174:175], off
	v_lshl_add_u64 v[174:175], v[220:221], 0, s[0:1]
	s_mov_b32 m0, s46
	s_nop 0
	global_load_lds_dwordx4 v[174:175], off
	s_nop 15
	s_nop 15
	s_nop 15
	s_nop 15
	s_waitcnt vmcnt(8)
	s_waitcnt lgkmcnt(0)
	s_barrier
	s_setprio 1
	s_waitcnt lgkmcnt(0)
	v_mfma_f32_16x16x32_bf16 v[60:63], v[142:145], v[184:187], v[60:63]
	v_mfma_f32_16x16x32_bf16 v[56:59], v[150:153], v[184:187], v[56:59]
	v_mfma_f32_16x16x32_bf16 v[44:47], v[142:145], v[192:195], v[44:47]
	v_mfma_f32_16x16x32_bf16 v[40:43], v[150:153], v[192:195], v[40:43]
	v_mfma_f32_16x16x32_bf16 v[28:31], v[142:145], v[200:203], v[28:31]
	v_mfma_f32_16x16x32_bf16 v[24:27], v[150:153], v[200:203], v[24:27]
	v_mfma_f32_16x16x32_bf16 v[12:15], v[142:145], v[208:211], v[12:15]
	v_mfma_f32_16x16x32_bf16 v[8:11], v[150:153], v[208:211], v[8:11]
	v_mfma_f32_16x16x32_bf16 v[60:63], v[146:149], v[188:191], v[60:63]
	v_mfma_f32_16x16x32_bf16 v[56:59], v[154:157], v[188:191], v[56:59]
	v_mfma_f32_16x16x32_bf16 v[44:47], v[146:149], v[196:199], v[44:47]
	v_mfma_f32_16x16x32_bf16 v[40:43], v[154:157], v[196:199], v[40:43]
	v_mfma_f32_16x16x32_bf16 v[28:31], v[146:149], v[204:207], v[28:31]
	v_mfma_f32_16x16x32_bf16 v[24:27], v[154:157], v[204:207], v[24:27]
	v_mfma_f32_16x16x32_bf16 v[12:15], v[146:149], v[212:215], v[12:15]
	v_mfma_f32_16x16x32_bf16 v[8:11], v[154:157], v[212:215], v[8:11]
	s_setprio 0
	s_setprio 1
	v_mfma_f32_16x16x32_bf16 v[52:55], v[158:161], v[184:187], v[52:55]
	v_mfma_f32_16x16x32_bf16 v[48:51], v[166:169], v[184:187], v[48:51]
	v_mfma_f32_16x16x32_bf16 v[36:39], v[158:161], v[192:195], v[36:39]
	v_mfma_f32_16x16x32_bf16 v[32:35], v[166:169], v[192:195], v[32:35]
	v_mfma_f32_16x16x32_bf16 v[20:23], v[158:161], v[200:203], v[20:23]
	v_mfma_f32_16x16x32_bf16 v[16:19], v[166:169], v[200:203], v[16:19]
	v_mfma_f32_16x16x32_bf16 v[4:7], v[158:161], v[208:211], v[4:7]
	v_mfma_f32_16x16x32_bf16 v[0:3], v[166:169], v[208:211], v[0:3]
	v_mfma_f32_16x16x32_bf16 v[52:55], v[162:165], v[188:191], v[52:55]
	v_mfma_f32_16x16x32_bf16 v[48:51], v[170:173], v[188:191], v[48:51]
	v_mfma_f32_16x16x32_bf16 v[36:39], v[162:165], v[196:199], v[36:39]
	v_mfma_f32_16x16x32_bf16 v[32:35], v[170:173], v[196:199], v[32:35]
	v_mfma_f32_16x16x32_bf16 v[20:23], v[162:165], v[204:207], v[20:23]
	v_mfma_f32_16x16x32_bf16 v[16:19], v[170:173], v[204:207], v[16:19]
	v_mfma_f32_16x16x32_bf16 v[4:7], v[162:165], v[212:215], v[4:7]
	v_mfma_f32_16x16x32_bf16 v[0:3], v[170:173], v[212:215], v[0:3]
	s_setprio 0
	s_barrier
	s_add_u32 s4, s4, 0x100
	s_addc_u32 s5, s5, 0
	s_add_u32 s42, s42, 0x100
	s_addc_u32 s43, s43, 0
	s_cmp_ge_i32 s53, s34
	s_mov_b32 s40, s53
	s_cbranch_scc0 .LBB0_901

; #define PG8_STAGE(bufoff, gbase, voff) do { _Pragma("unroll") for (int _i = 0; _i < 2; ++_i) \
;         __builtin_amdgcn_global_load_lds((const unsigned*)((const char*)(gbase) + (voff)[_i]), (LAS unsigned*)(lds + (bufoff) + ldsw + _i * 8192), 16, 0, 0); } while (0)
; #define PG8_LDA(dst, b, h) do { _Pragma("unroll") for (int m = 0; m < 4; ++m) _Pragma("unroll") for (int k = 0; k < 2; ++k) dst[m][k] = *(const LAS bf16x8*)(lds + PG8_SA(b, h) + aoff + m * 2048 + k * 1024); } while (0)
; #define PG8_LDB(dst, b, h) do { _Pragma("unroll") for (int n = 0; n < 2; ++n) _Pragma("unroll") for (int k = 0; k < 2; ++k) dst[n][k] = *(const LAS bf16x8*)(lds + PG8_SB(b, h) + boff + n * 2048 + k * 1024); } while (0)
; #define PG8_MMA(ai, bj, At, Bt) do { __builtin_amdgcn_s_setprio(1); _Pragma("unroll") for (int m = 0; m < 4; ++m) _Pragma("unroll") for (int n = 0; n < 2; ++n) _Pragma("unroll") for (int k = 0; k < 2; ++k) \
;         acc[ai][bj][m][n] = __builtin_amdgcn_mfma_f32_16x16x32_bf16(Bt[n][k], At[m][k], acc[ai][bj][m][n], 0, 0, 0); __builtin_amdgcn_s_setprio(0); } while (0)
; #define PG8_BAR __builtin_amdgcn_s_barrier()
; template <class Epi, bool ALIGN_EPI = PG8_ALIGN>
; __device__ __forceinline__ void gemm_phase(LAS unsigned char* lds, const Gemm g, const StaticOrder& S, const Epi& E) {
;     ...
;         const bool has_next = S.next(ui + 1, nxt);
;         const char* nA = has_next ? (const char*)g.A + (size_t)nxt.pm * tstepA : cA; const char* nB = has_next ? (const char*)g.Bt + (size_t)nxt.pn * tstepB : cB;
;         for (int t = 0; t < nt; t += 2) {
;             const bool last = (t == nt - 2);
;             const char* a1 = cA + (size_t)(t + 1) * kstep;
;             const char* a2 = last ? nA : cA + (size_t)(t + 2) * kstep; const char* b2 = last ? nB : cB + (size_t)(t + 2) * kstep;
;             const char* a3 = a2 + kstep; const char* b3 = b2 + kstep;
;             PG8_LDB(B0, 0, 0); PG8_LDB(B1, 0, 1); PG8_SCHED; PG8_LDA(At, 0, 0); PG8_STAGE(PG8_SA(1, 1), a1 + hstepA, voffA);
;             PG8_WAIT_V(8); PG8_WAIT_L(0); PG8_BAR; PG8_MMA(0, 0, At, B0); PG8_MMA(0, 1, At, B1); PG8_BAR; PG8_SCHED;
;             PG8_LDA(At, 0, 1); PG8_STAGE(PG8_SB(0, 0), b2, voffB); PG8_STAGE(PG8_SB(0, 1), b2 + hstepB, voffB); PG8_STAGE(PG8_SA(0, 0), a2, voffA);
;             PG8_WAIT_V(8); PG8_WAIT_L(0); PG8_BAR; PG8_MMA(1, 0, At, B0); PG8_MMA(1, 1, At, B1); PG8_BAR; PG8_SCHED;
.LBB0_1028:
	s_add_i32 s31, s24, 2
	s_add_u32 s20, s2, 0xfff80080
	s_addc_u32 s21, s3, -1
	s_add_i32 s22, 16, 0x10000
	s_cmp_eq_u32 s53, s24
	s_cselect_b32 s25, s17, s21
	s_cselect_b32 s24, s27, s20
	s_cselect_b32 s21, s39, s30
	s_cselect_b32 s20, s38, s29
	s_add_i32 s23, 16, 0x14000
	v_add_u32_e32 v140, s22, v220
	v_add_u32_e32 v156, s23, v220
	ds_read_b128 v[128:131], v140
	ds_read_b128 v[132:135], v140 offset:1024
	ds_read_b128 v[136:139], v140 offset:2048
	ds_read_b128 v[140:143], v140 offset:3072
	ds_read_b128 v[144:147], v156
	ds_read_b128 v[148:151], v156 offset:1024
	ds_read_b128 v[152:155], v156 offset:2048
	ds_read_b128 v[156:159], v156 offset:3072
	v_lshl_add_u64 v[180:181], s[2:3], 0, v[192:193]
	s_add_i32 m0, s47, 0xc000
	ds_read_b128 v[160:163], v223
	ds_read_b128 v[164:167], v223 offset:1024
	ds_read_b128 v[168:171], v223 offset:2048
	ds_read_b128 v[172:175], v223 offset:3072
	ds_read_b128 v[196:199], v223 offset:4096
	ds_read_b128 v[200:203], v223 offset:5120
	ds_read_b128 v[204:207], v223 offset:6144
	ds_read_b128 v[208:211], v223 offset:7168
	global_load_lds_dwordx4 v[180:181], off
	v_lshl_add_u64 v[180:181], s[2:3], 0, v[194:195]
	s_add_i32 m0, s47, 0xe000
	s_nop 0
	global_load_lds_dwordx4 v[180:181], off
	s_waitcnt vmcnt(8)
	s_waitcnt lgkmcnt(0)
	s_barrier
	s_setprio 1
	s_waitcnt lgkmcnt(0)
	v_mfma_f32_16x16x32_bf16 v[124:127], v[128:131], v[160:163], v[124:127]
	v_mfma_f32_16x16x32_bf16 v[116:119], v[136:139], v[160:163], v[116:119]
	v_mfma_f32_16x16x32_bf16 v[108:111], v[128:131], v[168:171], v[108:111]
	v_mfma_f32_16x16x32_bf16 v[100:103], v[136:139], v[168:171], v[100:103]
	v_mfma_f32_16x16x32_bf16 v[92:95], v[128:131], v[196:199], v[92:95]
	v_mfma_f32_16x16x32_bf16 v[84:87], v[136:139], v[196:199], v[84:87]
	v_mfma_f32_16x16x32_bf16 v[76:79], v[128:131], v[204:207], v[76:79]
	v_mfma_f32_16x16x32_bf16 v[68:71], v[136:139], v[204:207], v[68:71]
	v_mfma_f32_16x16x32_bf16 v[124:127], v[132:135], v[164:167], v[124:127]
	v_mfma_f32_16x16x32_bf16 v[116:119], v[140:143], v[164:167], v[116:119]
	v_mfma_f32_16x16x32_bf16 v[108:111], v[132:135], v[172:175], v[108:111]
	v_mfma_f32_16x16x32_bf16 v[100:103], v[140:143], v[172:175], v[100:103]
	v_mfma_f32_16x16x32_bf16 v[92:95], v[132:135], v[200:203], v[92:95]
	v_mfma_f32_16x16x32_bf16 v[84:87], v[140:143], v[200:203], v[84:87]
	v_mfma_f32_16x16x32_bf16 v[76:79], v[132:135], v[208:211], v[76:79]
	v_mfma_f32_16x16x32_bf16 v[68:71], v[140:143], v[208:211], v[68:71]
	s_setprio 0
	s_setprio 1
	v_mfma_f32_16x16x32_bf16 v[120:123], v[144:147], v[160:163], v[120:123]
	v_mfma_f32_16x16x32_bf16 v[112:115], v[152:155], v[160:163], v[112:115]
	v_mfma_f32_16x16x32_bf16 v[104:107], v[144:147], v[168:171], v[104:107]
	v_mfma_f32_16x16x32_bf16 v[96:99], v[152:155], v[168:171], v[96:99]
	v_mfma_f32_16x16x32_bf16 v[88:91], v[144:147], v[196:199], v[88:91]
	v_mfma_f32_16x16x32_bf16 v[80:83], v[152:155], v[196:199], v[80:83]
	v_mfma_f32_16x16x32_bf16 v[72:75], v[144:147], v[204:207], v[72:75]
	v_mfma_f32_16x16x32_bf16 v[64:67], v[152:155], v[204:207], v[64:67]
	v_mfma_f32_16x16x32_bf16 v[120:123], v[148:151], v[164:167], v[120:123]
	v_mfma_f32_16x16x32_bf16 v[112:115], v[156:159], v[164:167], v[112:115]
	v_mfma_f32_16x16x32_bf16 v[104:107], v[148:151], v[172:175], v[104:107]
	v_mfma_f32_16x16x32_bf16 v[96:99], v[156:159], v[172:175], v[96:99]
	v_mfma_f32_16x16x32_bf16 v[88:91], v[148:151], v[200:203], v[88:91]
	v_mfma_f32_16x16x32_bf16 v[80:83], v[156:159], v[200:203], v[80:83]
	v_mfma_f32_16x16x32_bf16 v[72:75], v[148:151], v[208:211], v[72:75]
	v_mfma_f32_16x16x32_bf16 v[64:67], v[156:159], v[208:211], v[64:67]
	s_setprio 0
	s_barrier
	s_add_i32 s22, s22, s46
	v_lshl_add_u64 v[180:181], s[20:21], 0, v[188:189]
	s_mov_b32 m0, s22
	ds_read_b128 v[160:163], v223 offset:16384
	ds_read_b128 v[164:167], v223 offset:17408
	ds_read_b128 v[168:171], v223 offset:18432
	ds_read_b128 v[172:175], v223 offset:19456
	ds_read_b128 v[196:199], v223 offset:20480
	ds_read_b128 v[200:203], v223 offset:21504
	ds_read_b128 v[204:207], v223 offset:22528
	ds_read_b128 v[208:211], v223 offset:23552
	global_load_lds_dwordx4 v[180:181], off
	s_add_i32 m0, s22, 0x2000
	v_lshl_add_u64 v[182:183], s[20:21], 0, v[184:185]
	s_add_u32 s20, s20, s4
	s_addc_u32 s21, s21, s5
	s_add_i32 s22, s23, s46
	global_load_lds_dwordx4 v[182:183], off
	v_lshl_add_u64 v[212:213], s[20:21], 0, v[188:189]
	s_mov_b32 m0, s22
	v_lshl_add_u64 v[214:215], s[20:21], 0, v[184:185]
	global_load_lds_dwordx4 v[212:213], off
	s_add_i32 m0, s22, 0x2000
	v_lshl_add_u64 v[216:217], s[24:25], 0, v[190:191]
	global_load_lds_dwordx4 v[214:215], off
	s_mov_b32 m0, s47
	v_lshl_add_u64 v[218:219], s[24:25], 0, v[186:187]
	global_load_lds_dwordx4 v[216:217], off
	s_mov_b32 m0, s48
	s_nop 0
	global_load_lds_dwordx4 v[218:219], off
	s_nop 15
	s_nop 15
	s_nop 15
	s_nop 15
	s_waitcnt vmcnt(8)
	s_waitcnt lgkmcnt(0)
	s_barrier
; #define PG8_STAGE(bufoff, gbase, voff) do { _Pragma("unroll") for (int _i = 0; _i < 2; ++_i) \
;         __builtin_amdgcn_global_load_lds((const unsigned*)((const char*)(gbase) + (voff)[_i]), (LAS unsigned*)(lds + (bufoff) + ldsw + _i * 8192), 16, 0, 0); } while (0)
; #define PG8_LDA(dst, b, h) do { _Pragma("unroll") for (int m = 0; m < 4; ++m) _Pragma("unroll") for (int k = 0; k < 2; ++k) dst[m][k] = *(const LAS bf16x8*)(lds + PG8_SA(b, h) + aoff + m * 2048 + k * 1024); } while (0)
; #define PG8_LDB(dst, b, h) do { _Pragma("unroll") for (int n = 0; n < 2; ++n) _Pragma("unroll") for (int k = 0; k < 2; ++k) dst[n][k] = *(const LAS bf16x8*)(lds + PG8_SB(b, h) + boff + n * 2048 + k * 1024); } while (0)
; #define PG8_MMA(ai, bj, At, Bt) do { __builtin_amdgcn_s_setprio(1); _Pragma("unroll") for (int m = 0; m < 4; ++m) _Pragma("unroll") for (int n = 0; n < 2; ++n) _Pragma("unroll") for (int k = 0; k < 2; ++k) \
;         acc[ai][bj][m][n] = __builtin_amdgcn_mfma_f32_16x16x32_bf16(Bt[n][k], At[m][k], acc[ai][bj][m][n], 0, 0, 0); __builtin_amdgcn_s_setprio(0); } while (0)
; #define PG8_WAIT_V(n) asm volatile("s_waitcnt vmcnt(" #n ")" ::: "memory")
; #define PG8_WAIT_L(n) asm volatile("s_waitcnt lgkmcnt(" #n ")" ::: "memory")
; #define PG8_BAR __builtin_amdgcn_s_barrier()
; #define PG8_SCHED __builtin_amdgcn_sched_barrier(0)
; template <class Epi, bool ALIGN_EPI = PG8_ALIGN>
; __device__ __forceinline__ void gemm_phase(LAS unsigned char* lds, const Gemm g, const StaticOrder& S, const Epi& E) {
;     ...
;             PG8_WAIT_V(8); PG8_WAIT_L(0); PG8_BAR; PG8_MMA(1, 0, At, B0); PG8_MMA(1, 1, At, B1); PG8_BAR; PG8_SCHED;
;             PG8_LDB(B0, 1, 0); PG8_LDB(B1, 1, 1); PG8_SCHED; PG8_LDA(At, 1, 0); PG8_STAGE(PG8_SA(0, 1), a2 + hstepA, voffA);
;             PG8_WAIT_V(8); PG8_WAIT_L(0); PG8_BAR; PG8_MMA(0, 0, At, B0); PG8_MMA(0, 1, At, B1); PG8_BAR; PG8_SCHED;
	s_setprio 1
	s_waitcnt lgkmcnt(0)
	v_mfma_f32_16x16x32_bf16 v[60:63], v[128:131], v[160:163], v[60:63]
	v_mfma_f32_16x16x32_bf16 v[52:55], v[136:139], v[160:163], v[52:55]
	v_mfma_f32_16x16x32_bf16 v[44:47], v[128:131], v[168:171], v[44:47]
	v_mfma_f32_16x16x32_bf16 v[36:39], v[136:139], v[168:171], v[36:39]
	v_mfma_f32_16x16x32_bf16 v[28:31], v[128:131], v[196:199], v[28:31]
	v_mfma_f32_16x16x32_bf16 v[20:23], v[136:139], v[196:199], v[20:23]
	v_mfma_f32_16x16x32_bf16 v[12:15], v[128:131], v[204:207], v[12:15]
	v_mfma_f32_16x16x32_bf16 v[4:7], v[136:139], v[204:207], v[4:7]
	v_mfma_f32_16x16x32_bf16 v[60:63], v[132:135], v[164:167], v[60:63]
	v_mfma_f32_16x16x32_bf16 v[52:55], v[140:143], v[164:167], v[52:55]
	v_mfma_f32_16x16x32_bf16 v[44:47], v[132:135], v[172:175], v[44:47]
	v_mfma_f32_16x16x32_bf16 v[36:39], v[140:143], v[172:175], v[36:39]
	v_mfma_f32_16x16x32_bf16 v[28:31], v[132:135], v[200:203], v[28:31]
	v_mfma_f32_16x16x32_bf16 v[20:23], v[140:143], v[200:203], v[20:23]
	v_mfma_f32_16x16x32_bf16 v[12:15], v[132:135], v[208:211], v[12:15]
	v_mfma_f32_16x16x32_bf16 v[4:7], v[140:143], v[208:211], v[4:7]
	s_setprio 0
	s_setprio 1
	v_mfma_f32_16x16x32_bf16 v[56:59], v[144:147], v[160:163], v[56:59]
	v_mfma_f32_16x16x32_bf16 v[48:51], v[152:155], v[160:163], v[48:51]
	v_mfma_f32_16x16x32_bf16 v[40:43], v[144:147], v[168:171], v[40:43]
	v_mfma_f32_16x16x32_bf16 v[32:35], v[152:155], v[168:171], v[32:35]
	v_mfma_f32_16x16x32_bf16 v[24:27], v[144:147], v[196:199], v[24:27]
	v_mfma_f32_16x16x32_bf16 v[16:19], v[152:155], v[196:199], v[16:19]
	v_mfma_f32_16x16x32_bf16 v[8:11], v[144:147], v[204:207], v[8:11]
	v_mfma_f32_16x16x32_bf16 v[0:3], v[152:155], v[204:207], v[0:3]
	v_mfma_f32_16x16x32_bf16 v[56:59], v[148:151], v[164:167], v[56:59]
	v_mfma_f32_16x16x32_bf16 v[48:51], v[156:159], v[164:167], v[48:51]
	v_mfma_f32_16x16x32_bf16 v[40:43], v[148:151], v[172:175], v[40:43]
	v_mfma_f32_16x16x32_bf16 v[32:35], v[156:159], v[172:175], v[32:35]
	v_mfma_f32_16x16x32_bf16 v[24:27], v[148:151], v[200:203], v[24:27]
	v_mfma_f32_16x16x32_bf16 v[16:19], v[156:159], v[200:203], v[16:19]
	v_mfma_f32_16x16x32_bf16 v[8:11], v[148:151], v[208:211], v[8:11]
	v_mfma_f32_16x16x32_bf16 v[0:3], v[156:159], v[208:211], v[0:3]
	s_setprio 0
	s_barrier
	s_add_i32 s22, 16, 0x18000
	s_add_i32 s23, 16, 0x1c000
	v_add_u32_e32 v140, s22, v220
	v_add_u32_e32 v156, s23, v220
	ds_read_b128 v[128:131], v140
	ds_read_b128 v[132:135], v140 offset:1024
	ds_read_b128 v[136:139], v140 offset:2048
	ds_read_b128 v[140:143], v140 offset:3072
	ds_read_b128 v[144:147], v156
	ds_read_b128 v[148:151], v156 offset:1024
	ds_read_b128 v[152:155], v156 offset:2048
	ds_read_b128 v[156:159], v156 offset:3072
	s_add_u32 s20, s24, 0x80000
	s_addc_u32 s21, s25, 0
	s_mov_b32 m0, s49
	v_lshl_add_u64 v[224:225], s[20:21], 0, v[190:191]
	ds_read_b128 v[160:163], v223 offset:32768
	ds_read_b128 v[164:167], v223 offset:33792
	ds_read_b128 v[168:171], v223 offset:34816
	ds_read_b128 v[172:175], v223 offset:35840
	ds_read_b128 v[196:199], v223 offset:36864
	ds_read_b128 v[200:203], v223 offset:37888
	ds_read_b128 v[204:207], v223 offset:38912
	ds_read_b128 v[208:211], v223 offset:39936
	global_load_lds_dwordx4 v[224:225], off
	v_lshl_add_u64 v[224:225], s[20:21], 0, v[186:187]
	s_mov_b32 m0, s50
	s_nop 0
	global_load_lds_dwordx4 v[224:225], off
	s_waitcnt vmcnt(8)
	s_waitcnt lgkmcnt(0)
	s_barrier
	s_setprio 1
	s_waitcnt lgkmcnt(0)
	v_mfma_f32_16x16x32_bf16 v[124:127], v[128:131], v[160:163], v[124:127]
	v_mfma_f32_16x16x32_bf16 v[116:119], v[136:139], v[160:163], v[116:119]
	v_mfma_f32_16x16x32_bf16 v[108:111], v[128:131], v[168:171], v[108:111]
	v_mfma_f32_16x16x32_bf16 v[100:103], v[136:139], v[168:171], v[100:103]
	v_mfma_f32_16x16x32_bf16 v[92:95], v[128:131], v[196:199], v[92:95]
	v_mfma_f32_16x16x32_bf16 v[84:87], v[136:139], v[196:199], v[84:87]
	v_mfma_f32_16x16x32_bf16 v[76:79], v[128:131], v[204:207], v[76:79]
	v_mfma_f32_16x16x32_bf16 v[68:71], v[136:139], v[204:207], v[68:71]
	v_mfma_f32_16x16x32_bf16 v[124:127], v[132:135], v[164:167], v[124:127]
	v_mfma_f32_16x16x32_bf16 v[116:119], v[140:143], v[164:167], v[116:119]
	v_mfma_f32_16x16x32_bf16 v[108:111], v[132:135], v[172:175], v[108:111]
	v_mfma_f32_16x16x32_bf16 v[100:103], v[140:143], v[172:175], v[100:103]
	v_mfma_f32_16x16x32_bf16 v[92:95], v[132:135], v[200:203], v[92:95]
	v_mfma_f32_16x16x32_bf16 v[84:87], v[140:143], v[200:203], v[84:87]
	v_mfma_f32_16x16x32_bf16 v[76:79], v[132:135], v[208:211], v[76:79]
	v_mfma_f32_16x16x32_bf16 v[68:71], v[140:143], v[208:211], v[68:71]
	s_setprio 0
	s_setprio 1
	v_mfma_f32_16x16x32_bf16 v[120:123], v[144:147], v[160:163], v[120:123]
	v_mfma_f32_16x16x32_bf16 v[112:115], v[152:155], v[160:163], v[112:115]
	v_mfma_f32_16x16x32_bf16 v[104:107], v[144:147], v[168:171], v[104:107]
	v_mfma_f32_16x16x32_bf16 v[96:99], v[152:155], v[168:171], v[96:99]
	v_mfma_f32_16x16x32_bf16 v[88:91], v[144:147], v[196:199], v[88:91]
	v_mfma_f32_16x16x32_bf16 v[80:83], v[152:155], v[196:199], v[80:83]
	v_mfma_f32_16x16x32_bf16 v[72:75], v[144:147], v[204:207], v[72:75]
	v_mfma_f32_16x16x32_bf16 v[64:67], v[152:155], v[204:207], v[64:67]
	v_mfma_f32_16x16x32_bf16 v[120:123], v[148:151], v[164:167], v[120:123]
	v_mfma_f32_16x16x32_bf16 v[112:115], v[156:159], v[164:167], v[112:115]
	v_mfma_f32_16x16x32_bf16 v[104:107], v[148:151], v[172:175], v[104:107]
	v_mfma_f32_16x16x32_bf16 v[96:99], v[156:159], v[172:175], v[96:99]
	v_mfma_f32_16x16x32_bf16 v[88:91], v[148:151], v[200:203], v[88:91]
	v_mfma_f32_16x16x32_bf16 v[80:83], v[156:159], v[200:203], v[80:83]
	v_mfma_f32_16x16x32_bf16 v[72:75], v[148:151], v[208:211], v[72:75]
	v_mfma_f32_16x16x32_bf16 v[64:67], v[156:159], v[208:211], v[64:67]
	s_setprio 0
	s_barrier
; #define PG8_STAGE(bufoff, gbase, voff) do { _Pragma("unroll") for (int _i = 0; _i < 2; ++_i) \
;         __builtin_amdgcn_global_load_lds((const unsigned*)((const char*)(gbase) + (voff)[_i]), (LAS unsigned*)(lds + (bufoff) + ldsw + _i * 8192), 16, 0, 0); } while (0)
; #define PG8_LDA(dst, b, h) do { _Pragma("unroll") for (int m = 0; m < 4; ++m) _Pragma("unroll") for (int k = 0; k < 2; ++k) dst[m][k] = *(const LAS bf16x8*)(lds + PG8_SA(b, h) + aoff + m * 2048 + k * 1024); } while (0)
; #define PG8_MMA(ai, bj, At, Bt) do { __builtin_amdgcn_s_setprio(1); _Pragma("unroll") for (int m = 0; m < 4; ++m) _Pragma("unroll") for (int n = 0; n < 2; ++n) _Pragma("unroll") for (int k = 0; k < 2; ++k) \
;         acc[ai][bj][m][n] = __builtin_amdgcn_mfma_f32_16x16x32_bf16(Bt[n][k], At[m][k], acc[ai][bj][m][n], 0, 0, 0); __builtin_amdgcn_s_setprio(0); } while (0)
; #define PG8_WAIT_V(n) asm volatile("s_waitcnt vmcnt(" #n ")" ::: "memory")
; #define PG8_WAIT_L(n) asm volatile("s_waitcnt lgkmcnt(" #n ")" ::: "memory")
; #define PG8_BAR __builtin_amdgcn_s_barrier()
; #define PG8_SCHED __builtin_amdgcn_sched_barrier(0)
; template <class Epi, bool ALIGN_EPI = PG8_ALIGN>
; __device__ __forceinline__ void gemm_phase(LAS unsigned char* lds, const Gemm g, const StaticOrder& S, const Epi& E) {
;     ...
;             PG8_LDA(At, 1, 1); PG8_STAGE(PG8_SB(1, 0), b3, voffB); PG8_STAGE(PG8_SB(1, 1), b3 + hstepB, voffB); PG8_STAGE(PG8_SA(1, 0), a3, voffA);
;             PG8_WAIT_V(8); PG8_WAIT_L(0); PG8_BAR; PG8_MMA(1, 0, At, B0); PG8_MMA(1, 1, At, B1); PG8_BAR; PG8_SCHED;
;         }
	s_add_i32 s20, s22, s46
	v_lshl_add_u64 v[180:181], v[180:181], 0, s[0:1]
	s_mov_b32 m0, s20
	ds_read_b128 v[160:163], v223 offset:49152
	ds_read_b128 v[164:167], v223 offset:50176
	ds_read_b128 v[168:171], v223 offset:51200
	ds_read_b128 v[172:175], v223 offset:52224
	ds_read_b128 v[196:199], v223 offset:53248
	ds_read_b128 v[200:203], v223 offset:54272
	ds_read_b128 v[204:207], v223 offset:55296
	ds_read_b128 v[208:211], v223 offset:56320
	global_load_lds_dwordx4 v[180:181], off
	v_lshl_add_u64 v[180:181], v[182:183], 0, s[0:1]
	s_add_i32 m0, s20, 0x2000
	s_add_i32 s20, s23, s46
	global_load_lds_dwordx4 v[180:181], off
	v_lshl_add_u64 v[180:181], v[212:213], 0, s[0:1]
	s_mov_b32 m0, s20
	s_nop 0
	global_load_lds_dwordx4 v[180:181], off
	v_lshl_add_u64 v[180:181], v[214:215], 0, s[0:1]
	s_add_i32 m0, s20, 0x2000
	s_nop 0
	global_load_lds_dwordx4 v[180:181], off
	v_lshl_add_u64 v[180:181], v[216:217], 0, s[0:1]
	s_mov_b32 m0, s18
	s_nop 0
	global_load_lds_dwordx4 v[180:181], off
	v_lshl_add_u64 v[180:181], v[218:219], 0, s[0:1]
	s_mov_b32 m0, s51
	s_nop 0
	global_load_lds_dwordx4 v[180:181], off
	s_nop 15
	s_nop 15
	s_nop 15
	s_nop 15
	s_waitcnt vmcnt(8)
	s_waitcnt lgkmcnt(0)
	s_barrier
	s_setprio 1
	s_waitcnt lgkmcnt(0)
	v_mfma_f32_16x16x32_bf16 v[60:63], v[128:131], v[160:163], v[60:63]
	v_mfma_f32_16x16x32_bf16 v[52:55], v[136:139], v[160:163], v[52:55]
	v_mfma_f32_16x16x32_bf16 v[44:47], v[128:131], v[168:171], v[44:47]
	v_mfma_f32_16x16x32_bf16 v[36:39], v[136:139], v[168:171], v[36:39]
	v_mfma_f32_16x16x32_bf16 v[28:31], v[128:131], v[196:199], v[28:31]
	v_mfma_f32_16x16x32_bf16 v[20:23], v[136:139], v[196:199], v[20:23]
	v_mfma_f32_16x16x32_bf16 v[12:15], v[128:131], v[204:207], v[12:15]
	v_mfma_f32_16x16x32_bf16 v[4:7], v[136:139], v[204:207], v[4:7]
	v_mfma_f32_16x16x32_bf16 v[60:63], v[132:135], v[164:167], v[60:63]
	v_mfma_f32_16x16x32_bf16 v[52:55], v[140:143], v[164:167], v[52:55]
	v_mfma_f32_16x16x32_bf16 v[44:47], v[132:135], v[172:175], v[44:47]
	v_mfma_f32_16x16x32_bf16 v[36:39], v[140:143], v[172:175], v[36:39]
	v_mfma_f32_16x16x32_bf16 v[28:31], v[132:135], v[200:203], v[28:31]
	v_mfma_f32_16x16x32_bf16 v[20:23], v[140:143], v[200:203], v[20:23]
	v_mfma_f32_16x16x32_bf16 v[12:15], v[132:135], v[208:211], v[12:15]
	v_mfma_f32_16x16x32_bf16 v[4:7], v[140:143], v[208:211], v[4:7]
	s_setprio 0
	s_setprio 1
	v_mfma_f32_16x16x32_bf16 v[56:59], v[144:147], v[160:163], v[56:59]
	v_mfma_f32_16x16x32_bf16 v[48:51], v[152:155], v[160:163], v[48:51]
	v_mfma_f32_16x16x32_bf16 v[40:43], v[144:147], v[168:171], v[40:43]
	v_mfma_f32_16x16x32_bf16 v[32:35], v[152:155], v[168:171], v[32:35]
	v_mfma_f32_16x16x32_bf16 v[24:27], v[144:147], v[196:199], v[24:27]
	v_mfma_f32_16x16x32_bf16 v[16:19], v[152:155], v[196:199], v[16:19]
	v_mfma_f32_16x16x32_bf16 v[8:11], v[144:147], v[204:207], v[8:11]
	v_mfma_f32_16x16x32_bf16 v[0:3], v[152:155], v[204:207], v[0:3]
	v_mfma_f32_16x16x32_bf16 v[56:59], v[148:151], v[164:167], v[56:59]
	v_mfma_f32_16x16x32_bf16 v[48:51], v[156:159], v[164:167], v[48:51]
	v_mfma_f32_16x16x32_bf16 v[40:43], v[148:151], v[172:175], v[40:43]
	v_mfma_f32_16x16x32_bf16 v[32:35], v[156:159], v[172:175], v[32:35]
	v_mfma_f32_16x16x32_bf16 v[24:27], v[148:151], v[200:203], v[24:27]
	v_mfma_f32_16x16x32_bf16 v[16:19], v[156:159], v[200:203], v[16:19]
	v_mfma_f32_16x16x32_bf16 v[8:11], v[148:151], v[208:211], v[8:11]
	v_mfma_f32_16x16x32_bf16 v[0:3], v[156:159], v[208:211], v[0:3]
	s_setprio 0
	s_barrier
	s_add_u32 s2, s2, 0x100
	s_addc_u32 s3, s3, 0
	s_add_u32 s29, s29, 0x100
	s_addc_u32 s30, s30, 0
	s_cmp_ge_i32 s31, s52
	s_mov_b32 s24, s31
	s_cbranch_scc0 .LBB0_1028

; #define PG8_STAGE(bufoff, gbase, voff) do { _Pragma("unroll") for (int _i = 0; _i < 2; ++_i) \
;         __builtin_amdgcn_global_load_lds((const unsigned*)((const char*)(gbase) + (voff)[_i]), (LAS unsigned*)(lds + (bufoff) + ldsw + _i * 8192), 16, 0, 0); } while (0)
; #define PG8_LDA(dst, b, h) do { _Pragma("unroll") for (int m = 0; m < 4; ++m) _Pragma("unroll") for (int k = 0; k < 2; ++k) dst[m][k] = *(const LAS bf16x8*)(lds + PG8_SA(b, h) + aoff + m * 2048 + k * 1024); } while (0)
; #define PG8_LDB(dst, b, h) do { _Pragma("unroll") for (int n = 0; n < 2; ++n) _Pragma("unroll") for (int k = 0; k < 2; ++k) dst[n][k] = *(const LAS bf16x8*)(lds + PG8_SB(b, h) + boff + n * 2048 + k * 1024); } while (0)
; #define PG8_MMA(ai, bj, At, Bt) do { __builtin_amdgcn_s_setprio(1); _Pragma("unroll") for (int m = 0; m < 4; ++m) _Pragma("unroll") for (int n = 0; n < 2; ++n) _Pragma("unroll") for (int k = 0; k < 2; ++k) \
;         acc[ai][bj][m][n] = __builtin_amdgcn_mfma_f32_16x16x32_bf16(Bt[n][k], At[m][k], acc[ai][bj][m][n], 0, 0, 0); __builtin_amdgcn_s_setprio(0); } while (0)
; #define PG8_BAR __builtin_amdgcn_s_barrier()
; template <class Epi, bool ALIGN_EPI = PG8_ALIGN>
; __device__ __forceinline__ void gemm_phase(LAS unsigned char* lds, const Gemm g, const StaticOrder& S, const Epi& E) {
;     ...
;         const bool has_next = S.next(ui + 1, nxt);
;         const char* nA = has_next ? (const char*)g.A + (size_t)nxt.pm * tstepA : cA; const char* nB = has_next ? (const char*)g.Bt + (size_t)nxt.pn * tstepB : cB;
;         for (int t = 0; t < nt; t += 2) {
;             const bool last = (t == nt - 2);
;             const char* a1 = cA + (size_t)(t + 1) * kstep;
;             const char* a2 = last ? nA : cA + (size_t)(t + 2) * kstep; const char* b2 = last ? nB : cB + (size_t)(t + 2) * kstep;
;             const char* a3 = a2 + kstep; const char* b3 = b2 + kstep;
;             PG8_LDB(B0, 0, 0); PG8_LDB(B1, 0, 1); PG8_SCHED; PG8_LDA(At, 0, 0); PG8_STAGE(PG8_SA(1, 1), a1 + hstepA, voffA);
;             PG8_WAIT_V(8); PG8_WAIT_L(0); PG8_BAR; PG8_MMA(0, 0, At, B0); PG8_MMA(0, 1, At, B1); PG8_BAR; PG8_SCHED;
;             PG8_LDA(At, 0, 1); PG8_STAGE(PG8_SB(0, 0), b2, voffB); PG8_STAGE(PG8_SB(0, 1), b2 + hstepB, voffB); PG8_STAGE(PG8_SA(0, 0), a2, voffA);
;             PG8_WAIT_V(8); PG8_WAIT_L(0); PG8_BAR; PG8_MMA(1, 0, At, B0); PG8_MMA(1, 1, At, B1); PG8_BAR; PG8_SCHED;
.LBB0_1108:
	s_add_i32 s53, s40, 2
	s_add_u32 s36, s24, 0x100
	s_addc_u32 s37, s25, 0
	s_add_i32 s22, 16, 0x10000
	s_cmp_eq_u32 s27, s40
	s_cselect_b32 s41, s3, s37
	s_cselect_b32 s40, s2, s36
	s_cselect_b32 s21, s17, s52
	s_cselect_b32 s20, s16, s51
	s_add_i32 s23, 16, 0x14000
	v_add_u32_e32 v154, s22, v147
	v_add_u32_e32 v170, s23, v147
	ds_read_b128 v[138:141], v154
	ds_read_b128 v[142:145], v154 offset:1024
	ds_read_b128 v[150:153], v154 offset:2048
	ds_read_b128 v[154:157], v154 offset:3072
	ds_read_b128 v[158:161], v170
	ds_read_b128 v[162:165], v170 offset:1024
	ds_read_b128 v[166:169], v170 offset:2048
	ds_read_b128 v[170:173], v170 offset:3072
	v_lshl_add_u64 v[174:175], s[24:25], 0, v[134:135]
	s_add_i32 m0, s31, 0xc000
	ds_read_b128 v[184:187], v149
	ds_read_b128 v[188:191], v149 offset:1024
	ds_read_b128 v[192:195], v149 offset:2048
	ds_read_b128 v[196:199], v149 offset:3072
	ds_read_b128 v[200:203], v149 offset:4096
	ds_read_b128 v[204:207], v149 offset:5120
	ds_read_b128 v[208:211], v149 offset:6144
	ds_read_b128 v[212:215], v149 offset:7168
	global_load_lds_dwordx4 v[174:175], off
	v_lshl_add_u64 v[174:175], s[24:25], 0, v[136:137]
	s_add_i32 m0, s31, 0xe000
	s_nop 0
	global_load_lds_dwordx4 v[174:175], off
	s_waitcnt vmcnt(8)
	s_waitcnt lgkmcnt(0)
	s_barrier
	s_setprio 1
	s_waitcnt lgkmcnt(0)
	v_mfma_f32_16x16x32_bf16 v[124:127], v[138:141], v[184:187], v[124:127]
	v_mfma_f32_16x16x32_bf16 v[120:123], v[150:153], v[184:187], v[120:123]
	v_mfma_f32_16x16x32_bf16 v[116:119], v[138:141], v[192:195], v[116:119]
	v_mfma_f32_16x16x32_bf16 v[112:115], v[150:153], v[192:195], v[112:115]
	v_mfma_f32_16x16x32_bf16 v[104:107], v[138:141], v[200:203], v[104:107]
	v_mfma_f32_16x16x32_bf16 v[96:99], v[150:153], v[200:203], v[96:99]
	v_mfma_f32_16x16x32_bf16 v[88:91], v[138:141], v[208:211], v[88:91]
	v_mfma_f32_16x16x32_bf16 v[80:83], v[150:153], v[208:211], v[80:83]
	v_mfma_f32_16x16x32_bf16 v[124:127], v[142:145], v[188:191], v[124:127]
	v_mfma_f32_16x16x32_bf16 v[120:123], v[154:157], v[188:191], v[120:123]
	v_mfma_f32_16x16x32_bf16 v[116:119], v[142:145], v[196:199], v[116:119]
	v_mfma_f32_16x16x32_bf16 v[112:115], v[154:157], v[196:199], v[112:115]
	v_mfma_f32_16x16x32_bf16 v[104:107], v[142:145], v[204:207], v[104:107]
	v_mfma_f32_16x16x32_bf16 v[96:99], v[154:157], v[204:207], v[96:99]
	v_mfma_f32_16x16x32_bf16 v[88:91], v[142:145], v[212:215], v[88:91]
	v_mfma_f32_16x16x32_bf16 v[80:83], v[154:157], v[212:215], v[80:83]
	s_setprio 0
	s_setprio 1
	v_mfma_f32_16x16x32_bf16 v[108:111], v[158:161], v[184:187], v[108:111]
	v_mfma_f32_16x16x32_bf16 v[100:103], v[166:169], v[184:187], v[100:103]
	v_mfma_f32_16x16x32_bf16 v[92:95], v[158:161], v[192:195], v[92:95]
	v_mfma_f32_16x16x32_bf16 v[84:87], v[166:169], v[192:195], v[84:87]
	v_mfma_f32_16x16x32_bf16 v[76:79], v[158:161], v[200:203], v[76:79]
	v_mfma_f32_16x16x32_bf16 v[72:75], v[166:169], v[200:203], v[72:75]
	v_mfma_f32_16x16x32_bf16 v[68:71], v[158:161], v[208:211], v[68:71]
	v_mfma_f32_16x16x32_bf16 v[64:67], v[166:169], v[208:211], v[64:67]
	v_mfma_f32_16x16x32_bf16 v[108:111], v[162:165], v[188:191], v[108:111]
	v_mfma_f32_16x16x32_bf16 v[100:103], v[170:173], v[188:191], v[100:103]
	v_mfma_f32_16x16x32_bf16 v[92:95], v[162:165], v[196:199], v[92:95]
	v_mfma_f32_16x16x32_bf16 v[84:87], v[170:173], v[196:199], v[84:87]
	v_mfma_f32_16x16x32_bf16 v[76:79], v[162:165], v[204:207], v[76:79]
	v_mfma_f32_16x16x32_bf16 v[72:75], v[170:173], v[204:207], v[72:75]
	v_mfma_f32_16x16x32_bf16 v[68:71], v[162:165], v[212:215], v[68:71]
	v_mfma_f32_16x16x32_bf16 v[64:67], v[170:173], v[212:215], v[64:67]
	s_setprio 0
	s_barrier
	s_add_i32 s22, s22, s18
	v_lshl_add_u64 v[174:175], s[20:21], 0, v[176:177]
	s_mov_b32 m0, s22
	ds_read_b128 v[184:187], v149 offset:16384
	ds_read_b128 v[188:191], v149 offset:17408
	ds_read_b128 v[192:195], v149 offset:18432
	ds_read_b128 v[196:199], v149 offset:19456
	ds_read_b128 v[200:203], v149 offset:20480
	ds_read_b128 v[204:207], v149 offset:21504
	ds_read_b128 v[208:211], v149 offset:22528
	ds_read_b128 v[212:215], v149 offset:23552
	global_load_lds_dwordx4 v[174:175], off
	s_add_i32 m0, s22, 0x2000
	v_lshl_add_u64 v[180:181], s[20:21], 0, v[128:129]
	s_add_u32 s20, s20, s6
	s_addc_u32 s21, s21, s7
	s_add_i32 s22, s23, s18
	global_load_lds_dwordx4 v[180:181], off
	v_lshl_add_u64 v[182:183], s[20:21], 0, v[176:177]
	s_mov_b32 m0, s22
	v_lshl_add_u64 v[216:217], s[20:21], 0, v[128:129]
	global_load_lds_dwordx4 v[182:183], off
	s_add_i32 m0, s22, 0x2000
	v_lshl_add_u64 v[218:219], s[40:41], 0, v[132:133]
	global_load_lds_dwordx4 v[216:217], off
	s_mov_b32 m0, s31
	v_lshl_add_u64 v[220:221], s[40:41], 0, v[130:131]
	global_load_lds_dwordx4 v[218:219], off
	s_mov_b32 m0, s42
	s_nop 0
	global_load_lds_dwordx4 v[220:221], off
	s_nop 15
	s_nop 15
	s_nop 15
	s_nop 15
	s_waitcnt vmcnt(8)
	s_waitcnt lgkmcnt(0)
	s_barrier
; #define PG8_STAGE(bufoff, gbase, voff) do { _Pragma("unroll") for (int _i = 0; _i < 2; ++_i) \
;         __builtin_amdgcn_global_load_lds((const unsigned*)((const char*)(gbase) + (voff)[_i]), (LAS unsigned*)(lds + (bufoff) + ldsw + _i * 8192), 16, 0, 0); } while (0)
; #define PG8_LDA(dst, b, h) do { _Pragma("unroll") for (int m = 0; m < 4; ++m) _Pragma("unroll") for (int k = 0; k < 2; ++k) dst[m][k] = *(const LAS bf16x8*)(lds + PG8_SA(b, h) + aoff + m * 2048 + k * 1024); } while (0)
; #define PG8_LDB(dst, b, h) do { _Pragma("unroll") for (int n = 0; n < 2; ++n) _Pragma("unroll") for (int k = 0; k < 2; ++k) dst[n][k] = *(const LAS bf16x8*)(lds + PG8_SB(b, h) + boff + n * 2048 + k * 1024); } while (0)
; #define PG8_MMA(ai, bj, At, Bt) do { __builtin_amdgcn_s_setprio(1); _Pragma("unroll") for (int m = 0; m < 4; ++m) _Pragma("unroll") for (int n = 0; n < 2; ++n) _Pragma("unroll") for (int k = 0; k < 2; ++k) \
;         acc[ai][bj][m][n] = __builtin_amdgcn_mfma_f32_16x16x32_bf16(Bt[n][k], At[m][k], acc[ai][bj][m][n], 0, 0, 0); __builtin_amdgcn_s_setprio(0); } while (0)
; #define PG8_WAIT_V(n) asm volatile("s_waitcnt vmcnt(" #n ")" ::: "memory")
; #define PG8_WAIT_L(n) asm volatile("s_waitcnt lgkmcnt(" #n ")" ::: "memory")
; #define PG8_BAR __builtin_amdgcn_s_barrier()
; #define PG8_SCHED __builtin_amdgcn_sched_barrier(0)
; template <class Epi, bool ALIGN_EPI = PG8_ALIGN>
; __device__ __forceinline__ void gemm_phase(LAS unsigned char* lds, const Gemm g, const StaticOrder& S, const Epi& E) {
;     ...
;             PG8_WAIT_V(8); PG8_WAIT_L(0); PG8_BAR; PG8_MMA(1, 0, At, B0); PG8_MMA(1, 1, At, B1); PG8_BAR; PG8_SCHED;
;             PG8_LDB(B0, 1, 0); PG8_LDB(B1, 1, 1); PG8_SCHED; PG8_LDA(At, 1, 0); PG8_STAGE(PG8_SA(0, 1), a2 + hstepA, voffA);
;             PG8_WAIT_V(8); PG8_WAIT_L(0); PG8_BAR; PG8_MMA(0, 0, At, B0); PG8_MMA(0, 1, At, B1); PG8_BAR; PG8_SCHED;
	s_setprio 1
	s_waitcnt lgkmcnt(0)
	v_mfma_f32_16x16x32_bf16 v[60:63], v[138:141], v[184:187], v[60:63]
	v_mfma_f32_16x16x32_bf16 v[56:59], v[150:153], v[184:187], v[56:59]
	v_mfma_f32_16x16x32_bf16 v[52:55], v[138:141], v[192:195], v[52:55]
	v_mfma_f32_16x16x32_bf16 v[48:51], v[150:153], v[192:195], v[48:51]
	v_mfma_f32_16x16x32_bf16 v[40:43], v[138:141], v[200:203], v[40:43]
	v_mfma_f32_16x16x32_bf16 v[32:35], v[150:153], v[200:203], v[32:35]
	v_mfma_f32_16x16x32_bf16 v[24:27], v[138:141], v[208:211], v[24:27]
	v_mfma_f32_16x16x32_bf16 v[16:19], v[150:153], v[208:211], v[16:19]
	v_mfma_f32_16x16x32_bf16 v[60:63], v[142:145], v[188:191], v[60:63]
	v_mfma_f32_16x16x32_bf16 v[56:59], v[154:157], v[188:191], v[56:59]
	v_mfma_f32_16x16x32_bf16 v[52:55], v[142:145], v[196:199], v[52:55]
	v_mfma_f32_16x16x32_bf16 v[48:51], v[154:157], v[196:199], v[48:51]
	v_mfma_f32_16x16x32_bf16 v[40:43], v[142:145], v[204:207], v[40:43]
	v_mfma_f32_16x16x32_bf16 v[32:35], v[154:157], v[204:207], v[32:35]
	v_mfma_f32_16x16x32_bf16 v[24:27], v[142:145], v[212:215], v[24:27]
	v_mfma_f32_16x16x32_bf16 v[16:19], v[154:157], v[212:215], v[16:19]
	s_setprio 0
	s_setprio 1
	v_mfma_f32_16x16x32_bf16 v[44:47], v[158:161], v[184:187], v[44:47]
	v_mfma_f32_16x16x32_bf16 v[36:39], v[166:169], v[184:187], v[36:39]
	v_mfma_f32_16x16x32_bf16 v[28:31], v[158:161], v[192:195], v[28:31]
	v_mfma_f32_16x16x32_bf16 v[20:23], v[166:169], v[192:195], v[20:23]
	v_mfma_f32_16x16x32_bf16 v[12:15], v[158:161], v[200:203], v[12:15]
	v_mfma_f32_16x16x32_bf16 v[8:11], v[166:169], v[200:203], v[8:11]
	v_mfma_f32_16x16x32_bf16 v[4:7], v[158:161], v[208:211], v[4:7]
	v_mfma_f32_16x16x32_bf16 v[0:3], v[166:169], v[208:211], v[0:3]
	v_mfma_f32_16x16x32_bf16 v[44:47], v[162:165], v[188:191], v[44:47]
	v_mfma_f32_16x16x32_bf16 v[36:39], v[170:173], v[188:191], v[36:39]
	v_mfma_f32_16x16x32_bf16 v[28:31], v[162:165], v[196:199], v[28:31]
	v_mfma_f32_16x16x32_bf16 v[20:23], v[170:173], v[196:199], v[20:23]
	v_mfma_f32_16x16x32_bf16 v[12:15], v[162:165], v[204:207], v[12:15]
	v_mfma_f32_16x16x32_bf16 v[8:11], v[170:173], v[204:207], v[8:11]
	v_mfma_f32_16x16x32_bf16 v[4:7], v[162:165], v[212:215], v[4:7]
	v_mfma_f32_16x16x32_bf16 v[0:3], v[170:173], v[212:215], v[0:3]
	s_setprio 0
	s_barrier
	s_add_i32 s22, 16, 0x18000
	s_add_i32 s23, 16, 0x1c000
	v_add_u32_e32 v154, s22, v147
	v_add_u32_e32 v170, s23, v147
	ds_read_b128 v[138:141], v154
	ds_read_b128 v[142:145], v154 offset:1024
	ds_read_b128 v[150:153], v154 offset:2048
	ds_read_b128 v[154:157], v154 offset:3072
	ds_read_b128 v[158:161], v170
	ds_read_b128 v[162:165], v170 offset:1024
	ds_read_b128 v[166:169], v170 offset:2048
	ds_read_b128 v[170:173], v170 offset:3072
	s_add_u32 s20, s40, 0x160000
	s_addc_u32 s21, s41, 0
	s_mov_b32 m0, s43
	v_lshl_add_u64 v[222:223], s[20:21], 0, v[132:133]
	ds_read_b128 v[184:187], v149 offset:32768
	ds_read_b128 v[188:191], v149 offset:33792
	ds_read_b128 v[192:195], v149 offset:34816
	ds_read_b128 v[196:199], v149 offset:35840
	ds_read_b128 v[200:203], v149 offset:36864
	ds_read_b128 v[204:207], v149 offset:37888
	ds_read_b128 v[208:211], v149 offset:38912
	ds_read_b128 v[212:215], v149 offset:39936
	global_load_lds_dwordx4 v[222:223], off
	v_lshl_add_u64 v[222:223], s[20:21], 0, v[130:131]
	s_mov_b32 m0, s44
	s_nop 0
	global_load_lds_dwordx4 v[222:223], off
	s_waitcnt vmcnt(8)
	s_waitcnt lgkmcnt(0)
	s_barrier
	s_setprio 1
	s_waitcnt lgkmcnt(0)
	v_mfma_f32_16x16x32_bf16 v[124:127], v[138:141], v[184:187], v[124:127]
	v_mfma_f32_16x16x32_bf16 v[120:123], v[150:153], v[184:187], v[120:123]
	v_mfma_f32_16x16x32_bf16 v[116:119], v[138:141], v[192:195], v[116:119]
	v_mfma_f32_16x16x32_bf16 v[112:115], v[150:153], v[192:195], v[112:115]
	v_mfma_f32_16x16x32_bf16 v[104:107], v[138:141], v[200:203], v[104:107]
	v_mfma_f32_16x16x32_bf16 v[96:99], v[150:153], v[200:203], v[96:99]
	v_mfma_f32_16x16x32_bf16 v[88:91], v[138:141], v[208:211], v[88:91]
	v_mfma_f32_16x16x32_bf16 v[80:83], v[150:153], v[208:211], v[80:83]
	v_mfma_f32_16x16x32_bf16 v[124:127], v[142:145], v[188:191], v[124:127]
	v_mfma_f32_16x16x32_bf16 v[120:123], v[154:157], v[188:191], v[120:123]
	v_mfma_f32_16x16x32_bf16 v[116:119], v[142:145], v[196:199], v[116:119]
	v_mfma_f32_16x16x32_bf16 v[112:115], v[154:157], v[196:199], v[112:115]
	v_mfma_f32_16x16x32_bf16 v[104:107], v[142:145], v[204:207], v[104:107]
	v_mfma_f32_16x16x32_bf16 v[96:99], v[154:157], v[204:207], v[96:99]
	v_mfma_f32_16x16x32_bf16 v[88:91], v[142:145], v[212:215], v[88:91]
	v_mfma_f32_16x16x32_bf16 v[80:83], v[154:157], v[212:215], v[80:83]
	s_setprio 0
	s_setprio 1
	v_mfma_f32_16x16x32_bf16 v[108:111], v[158:161], v[184:187], v[108:111]
	v_mfma_f32_16x16x32_bf16 v[100:103], v[166:169], v[184:187], v[100:103]
	v_mfma_f32_16x16x32_bf16 v[92:95], v[158:161], v[192:195], v[92:95]
	v_mfma_f32_16x16x32_bf16 v[84:87], v[166:169], v[192:195], v[84:87]
	v_mfma_f32_16x16x32_bf16 v[76:79], v[158:161], v[200:203], v[76:79]
	v_mfma_f32_16x16x32_bf16 v[72:75], v[166:169], v[200:203], v[72:75]
	v_mfma_f32_16x16x32_bf16 v[68:71], v[158:161], v[208:211], v[68:71]
	v_mfma_f32_16x16x32_bf16 v[64:67], v[166:169], v[208:211], v[64:67]
	v_mfma_f32_16x16x32_bf16 v[108:111], v[162:165], v[188:191], v[108:111]
	v_mfma_f32_16x16x32_bf16 v[100:103], v[170:173], v[188:191], v[100:103]
	v_mfma_f32_16x16x32_bf16 v[92:95], v[162:165], v[196:199], v[92:95]
	v_mfma_f32_16x16x32_bf16 v[84:87], v[170:173], v[196:199], v[84:87]
	v_mfma_f32_16x16x32_bf16 v[76:79], v[162:165], v[204:207], v[76:79]
	v_mfma_f32_16x16x32_bf16 v[72:75], v[170:173], v[204:207], v[72:75]
	v_mfma_f32_16x16x32_bf16 v[68:71], v[162:165], v[212:215], v[68:71]
	v_mfma_f32_16x16x32_bf16 v[64:67], v[170:173], v[212:215], v[64:67]
	s_setprio 0
	s_barrier
; #define PG8_STAGE(bufoff, gbase, voff) do { _Pragma("unroll") for (int _i = 0; _i < 2; ++_i) \
;         __builtin_amdgcn_global_load_lds((const unsigned*)((const char*)(gbase) + (voff)[_i]), (LAS unsigned*)(lds + (bufoff) + ldsw + _i * 8192), 16, 0, 0); } while (0)
; #define PG8_LDA(dst, b, h) do { _Pragma("unroll") for (int m = 0; m < 4; ++m) _Pragma("unroll") for (int k = 0; k < 2; ++k) dst[m][k] = *(const LAS bf16x8*)(lds + PG8_SA(b, h) + aoff + m * 2048 + k * 1024); } while (0)
; #define PG8_MMA(ai, bj, At, Bt) do { __builtin_amdgcn_s_setprio(1); _Pragma("unroll") for (int m = 0; m < 4; ++m) _Pragma("unroll") for (int n = 0; n < 2; ++n) _Pragma("unroll") for (int k = 0; k < 2; ++k) \
;         acc[ai][bj][m][n] = __builtin_amdgcn_mfma_f32_16x16x32_bf16(Bt[n][k], At[m][k], acc[ai][bj][m][n], 0, 0, 0); __builtin_amdgcn_s_setprio(0); } while (0)
; #define PG8_WAIT_V(n) asm volatile("s_waitcnt vmcnt(" #n ")" ::: "memory")
; #define PG8_WAIT_L(n) asm volatile("s_waitcnt lgkmcnt(" #n ")" ::: "memory")
; #define PG8_BAR __builtin_amdgcn_s_barrier()
; #define PG8_SCHED __builtin_amdgcn_sched_barrier(0)
; template <class Epi, bool ALIGN_EPI = PG8_ALIGN>
; __device__ __forceinline__ void gemm_phase(LAS unsigned char* lds, const Gemm g, const StaticOrder& S, const Epi& E) {
;     ...
;             PG8_LDA(At, 1, 1); PG8_STAGE(PG8_SB(1, 0), b3, voffB); PG8_STAGE(PG8_SB(1, 1), b3 + hstepB, voffB); PG8_STAGE(PG8_SA(1, 0), a3, voffA);
;             PG8_WAIT_V(8); PG8_WAIT_L(0); PG8_BAR; PG8_MMA(1, 0, At, B0); PG8_MMA(1, 1, At, B1); PG8_BAR; PG8_SCHED;
;         }
	s_add_i32 s20, s22, s18
	v_lshl_add_u64 v[174:175], v[174:175], 0, s[0:1]
	s_mov_b32 m0, s20
	ds_read_b128 v[184:187], v149 offset:49152
	ds_read_b128 v[188:191], v149 offset:50176
	ds_read_b128 v[192:195], v149 offset:51200
	ds_read_b128 v[196:199], v149 offset:52224
	ds_read_b128 v[200:203], v149 offset:53248
	ds_read_b128 v[204:207], v149 offset:54272
	ds_read_b128 v[208:211], v149 offset:55296
	ds_read_b128 v[212:215], v149 offset:56320
	global_load_lds_dwordx4 v[174:175], off
	v_lshl_add_u64 v[174:175], v[180:181], 0, s[0:1]
	s_add_i32 m0, s20, 0x2000
	s_add_i32 s20, s23, s18
	global_load_lds_dwordx4 v[174:175], off
	v_lshl_add_u64 v[174:175], v[182:183], 0, s[0:1]
	s_mov_b32 m0, s20
	s_nop 0
	global_load_lds_dwordx4 v[174:175], off
	v_lshl_add_u64 v[174:175], v[216:217], 0, s[0:1]
	s_add_i32 m0, s20, 0x2000
	s_nop 0
	global_load_lds_dwordx4 v[174:175], off
	v_lshl_add_u64 v[174:175], v[218:219], 0, s[0:1]
	s_mov_b32 m0, s45
	s_nop 0
	global_load_lds_dwordx4 v[174:175], off
	v_lshl_add_u64 v[174:175], v[220:221], 0, s[0:1]
	s_mov_b32 m0, s46
	s_nop 0
	global_load_lds_dwordx4 v[174:175], off
	s_nop 15
	s_nop 15
	s_nop 15
	s_nop 15
	s_waitcnt vmcnt(8)
	s_waitcnt lgkmcnt(0)
	s_barrier
	s_setprio 1
	s_waitcnt lgkmcnt(0)
	v_mfma_f32_16x16x32_bf16 v[60:63], v[138:141], v[184:187], v[60:63]
	v_mfma_f32_16x16x32_bf16 v[56:59], v[150:153], v[184:187], v[56:59]
	v_mfma_f32_16x16x32_bf16 v[52:55], v[138:141], v[192:195], v[52:55]
	v_mfma_f32_16x16x32_bf16 v[48:51], v[150:153], v[192:195], v[48:51]
	v_mfma_f32_16x16x32_bf16 v[40:43], v[138:141], v[200:203], v[40:43]
	v_mfma_f32_16x16x32_bf16 v[32:35], v[150:153], v[200:203], v[32:35]
	v_mfma_f32_16x16x32_bf16 v[24:27], v[138:141], v[208:211], v[24:27]
	v_mfma_f32_16x16x32_bf16 v[16:19], v[150:153], v[208:211], v[16:19]
	v_mfma_f32_16x16x32_bf16 v[60:63], v[142:145], v[188:191], v[60:63]
	v_mfma_f32_16x16x32_bf16 v[56:59], v[154:157], v[188:191], v[56:59]
	v_mfma_f32_16x16x32_bf16 v[52:55], v[142:145], v[196:199], v[52:55]
	v_mfma_f32_16x16x32_bf16 v[48:51], v[154:157], v[196:199], v[48:51]
	v_mfma_f32_16x16x32_bf16 v[40:43], v[142:145], v[204:207], v[40:43]
	v_mfma_f32_16x16x32_bf16 v[32:35], v[154:157], v[204:207], v[32:35]
	v_mfma_f32_16x16x32_bf16 v[24:27], v[142:145], v[212:215], v[24:27]
	v_mfma_f32_16x16x32_bf16 v[16:19], v[154:157], v[212:215], v[16:19]
	s_setprio 0
	s_setprio 1
	v_mfma_f32_16x16x32_bf16 v[44:47], v[158:161], v[184:187], v[44:47]
	v_mfma_f32_16x16x32_bf16 v[36:39], v[166:169], v[184:187], v[36:39]
	v_mfma_f32_16x16x32_bf16 v[28:31], v[158:161], v[192:195], v[28:31]
	v_mfma_f32_16x16x32_bf16 v[20:23], v[166:169], v[192:195], v[20:23]
	v_mfma_f32_16x16x32_bf16 v[12:15], v[158:161], v[200:203], v[12:15]
	v_mfma_f32_16x16x32_bf16 v[8:11], v[166:169], v[200:203], v[8:11]
	v_mfma_f32_16x16x32_bf16 v[4:7], v[158:161], v[208:211], v[4:7]
	v_mfma_f32_16x16x32_bf16 v[0:3], v[166:169], v[208:211], v[0:3]
	v_mfma_f32_16x16x32_bf16 v[44:47], v[162:165], v[188:191], v[44:47]
	v_mfma_f32_16x16x32_bf16 v[36:39], v[170:173], v[188:191], v[36:39]
	v_mfma_f32_16x16x32_bf16 v[28:31], v[162:165], v[196:199], v[28:31]
	v_mfma_f32_16x16x32_bf16 v[20:23], v[170:173], v[196:199], v[20:23]
	v_mfma_f32_16x16x32_bf16 v[12:15], v[162:165], v[204:207], v[12:15]
	v_mfma_f32_16x16x32_bf16 v[8:11], v[170:173], v[204:207], v[8:11]
	v_mfma_f32_16x16x32_bf16 v[4:7], v[162:165], v[212:215], v[4:7]
	v_mfma_f32_16x16x32_bf16 v[0:3], v[170:173], v[212:215], v[0:3]
	s_setprio 0
	s_barrier
	s_add_u32 s51, s51, 0x100
	s_addc_u32 s52, s52, 0
	s_cmp_ge_i32 s53, s26
	s_mov_b64 s[24:25], s[36:37]
	s_mov_b32 s40, s53
	s_cbranch_scc0 .LBB0_1108
; __device__ __forceinline__ unsigned cvt_pk(float lo, float hi) { f32x2_t v = {lo, hi}; bf16x2_t b = __builtin_convertvector(v, bf16x2_t); return __builtin_bit_cast(unsigned, b); }
;     __device__ __forceinline__ void operator()(const f32x4 (&acc)[2][2][4][2], const Unit& u, int wr, int wc, int fr, int fq) const {
;     ...
;             for (int m = 0; m < 4; ++m) scv[ai][m] = rs ? rs[(size_t)(row0 + ai * HALF + m * 16) * rs_stride] * cs : cs;
; #pragma unroll
;         for (int ai = 0; ai < 2; ++ai)
; #pragma unroll
;             for (int m = 0; m < 4; ++m) {
;                 const int row = row0 + ai * HALF + m * 16; const float sc = scv[ai][m];
;                 bf16_t* rowp = O + (size_t)row * ldc + col0;
; #pragma unroll
;                 for (int bj = 0; bj < 2; ++bj) { const f32x4 v0 = acc[ai][bj][m][0] * sc, v1 = acc[ai][bj][m][1] * sc;
;                     u32x4 w; w.x = cvt_pk(v0[0], v0[1]); w.y = cvt_pk(v0[2], v0[3]); w.z = cvt_pk(v1[0], v1[1]); w.w = cvt_pk(v1[2], v1[3]);
	v_pk_mul_f32 v[126:127], v[126:127], 0.5 op_sel_hi:[1,0]
	v_pk_mul_f32 v[124:125], v[124:125], 0.5 op_sel_hi:[1,0]
	v_pk_mul_f32 v[122:123], v[122:123], 0.5 op_sel_hi:[1,0]
	v_pk_mul_f32 v[120:121], v[120:121], 0.5 op_sel_hi:[1,0]
	v_pk_mul_f32 v[138:139], v[110:111], 0.5 op_sel_hi:[1,0]
	v_pk_mul_f32 v[140:141], v[108:109], 0.5 op_sel_hi:[1,0]
	v_pk_mul_f32 v[142:143], v[102:103], 0.5 op_sel_hi:[1,0]
	v_pk_mul_f32 v[144:145], v[100:101], 0.5 op_sel_hi:[1,0]
	v_pk_mul_f32 v[100:101], v[118:119], 0.5 op_sel_hi:[1,0]
	v_pk_mul_f32 v[102:103], v[116:117], 0.5 op_sel_hi:[1,0]
	v_pk_mul_f32 v[108:109], v[114:115], 0.5 op_sel_hi:[1,0]
	v_pk_mul_f32 v[110:111], v[112:113], 0.5 op_sel_hi:[1,0]
	v_pk_mul_f32 v[112:113], v[94:95], 0.5 op_sel_hi:[1,0]
	v_pk_mul_f32 v[114:115], v[92:93], 0.5 op_sel_hi:[1,0]
	v_pk_mul_f32 v[116:117], v[86:87], 0.5 op_sel_hi:[1,0]
	v_pk_mul_f32 v[118:119], v[84:85], 0.5 op_sel_hi:[1,0]
	v_pk_mul_f32 v[84:85], v[106:107], 0.5 op_sel_hi:[1,0]
	v_pk_mul_f32 v[86:87], v[104:105], 0.5 op_sel_hi:[1,0]
	v_pk_mul_f32 v[92:93], v[98:99], 0.5 op_sel_hi:[1,0]
	v_pk_mul_f32 v[94:95], v[96:97], 0.5 op_sel_hi:[1,0]
	v_pk_mul_f32 v[96:97], v[78:79], 0.5 op_sel_hi:[1,0]
	v_pk_mul_f32 v[98:99], v[76:77], 0.5 op_sel_hi:[1,0]
	v_pk_mul_f32 v[104:105], v[74:75], 0.5 op_sel_hi:[1,0]
	v_pk_mul_f32 v[106:107], v[72:73], 0.5 op_sel_hi:[1,0]
	v_pk_mul_f32 v[72:73], v[90:91], 0.5 op_sel_hi:[1,0]
	v_pk_mul_f32 v[74:75], v[88:89], 0.5 op_sel_hi:[1,0]
	v_pk_mul_f32 v[76:77], v[82:83], 0.5 op_sel_hi:[1,0]
	v_pk_mul_f32 v[78:79], v[80:81], 0.5 op_sel_hi:[1,0]
	v_pk_mul_f32 v[70:71], v[70:71], 0.5 op_sel_hi:[1,0]
	v_pk_mul_f32 v[68:69], v[68:69], 0.5 op_sel_hi:[1,0]
	v_pk_mul_f32 v[66:67], v[66:67], 0.5 op_sel_hi:[1,0]
	v_pk_mul_f32 v[64:65], v[64:65], 0.5 op_sel_hi:[1,0]
	v_pk_mul_f32 v[62:63], v[62:63], 0.5 op_sel_hi:[1,0]
	v_pk_mul_f32 v[60:61], v[60:61], 0.5 op_sel_hi:[1,0]
	v_pk_mul_f32 v[58:59], v[58:59], 0.5 op_sel_hi:[1,0]
	v_pk_mul_f32 v[56:57], v[56:57], 0.5 op_sel_hi:[1,0]
	v_pk_mul_f32 v[80:81], v[46:47], 0.5 op_sel_hi:[1,0]
	v_pk_mul_f32 v[82:83], v[44:45], 0.5 op_sel_hi:[1,0]
	v_pk_mul_f32 v[88:89], v[38:39], 0.5 op_sel_hi:[1,0]
	v_pk_mul_f32 v[90:91], v[36:37], 0.5 op_sel_hi:[1,0]
	v_pk_mul_f32 v[36:37], v[54:55], 0.5 op_sel_hi:[1,0]
	v_pk_mul_f32 v[38:39], v[52:53], 0.5 op_sel_hi:[1,0]
	v_pk_mul_f32 v[44:45], v[50:51], 0.5 op_sel_hi:[1,0]
	v_pk_mul_f32 v[46:47], v[48:49], 0.5 op_sel_hi:[1,0]
	v_pk_mul_f32 v[48:49], v[30:31], 0.5 op_sel_hi:[1,0]
	v_pk_mul_f32 v[50:51], v[28:29], 0.5 op_sel_hi:[1,0]
	v_pk_mul_f32 v[52:53], v[22:23], 0.5 op_sel_hi:[1,0]
	v_pk_mul_f32 v[54:55], v[20:21], 0.5 op_sel_hi:[1,0]
	v_pk_mul_f32 v[20:21], v[42:43], 0.5 op_sel_hi:[1,0]
	v_pk_mul_f32 v[22:23], v[40:41], 0.5 op_sel_hi:[1,0]
	v_pk_mul_f32 v[28:29], v[34:35], 0.5 op_sel_hi:[1,0]
	v_pk_mul_f32 v[30:31], v[32:33], 0.5 op_sel_hi:[1,0]
	v_pk_mul_f32 v[32:33], v[14:15], 0.5 op_sel_hi:[1,0]
	v_pk_mul_f32 v[34:35], v[12:13], 0.5 op_sel_hi:[1,0]
	v_pk_mul_f32 v[40:41], v[10:11], 0.5 op_sel_hi:[1,0]
	v_pk_mul_f32 v[42:43], v[8:9], 0.5 op_sel_hi:[1,0]
	v_pk_mul_f32 v[8:9], v[26:27], 0.5 op_sel_hi:[1,0]
	v_pk_mul_f32 v[10:11], v[24:25], 0.5 op_sel_hi:[1,0]
	v_pk_mul_f32 v[12:13], v[18:19], 0.5 op_sel_hi:[1,0]
	v_pk_mul_f32 v[14:15], v[16:17], 0.5 op_sel_hi:[1,0]
	v_pk_mul_f32 v[6:7], v[6:7], 0.5 op_sel_hi:[1,0]
	v_pk_mul_f32 v[4:5], v[4:5], 0.5 op_sel_hi:[1,0]
	v_pk_mul_f32 v[2:3], v[2:3], 0.5 op_sel_hi:[1,0]
	v_pk_mul_f32 v[0:1], v[0:1], 0.5 op_sel_hi:[1,0]
